# K-loops: A-fragment ds_read addresses folded into immediate offsets off a lane-base VGPR biased once per phase (32 v_add_u32 removed from load segments)
# baseline (speedup 1.0000x reference)
.LBB0_120:
	s_mov_b32 s100, -1
	v_readlane_b32 s30, v254, 52
	v_readlane_b32 s40, v252, 4
	s_mul_i32 s25, s30, 0x8400
	v_readlane_b32 s44, v252, 8
	s_mul_hi_i32 s1, s30, 0x8400
	v_readlane_b32 s45, v252, 9
	s_add_u32 s68, s44, s25
	v_readlane_b32 s46, v252, 10
	s_addc_u32 s69, s45, s1
	s_mul_i32 s25, s30, 0x2c00
	v_readlane_b32 s47, v252, 11
	s_mul_hi_i32 s1, s30, 0x2c00
	s_add_u32 s70, s46, s25
	s_addc_u32 s71, s47, s1
	s_mul_i32 s25, s38, 0x1c00000
	v_readlane_b32 s20, v252, 32
	s_mul_hi_i32 s1, s38, 0x1c00000
	s_add_u32 s27, s20, s25
	v_readlane_b32 s20, v252, 33
	v_readlane_b32 s31, v254, 53
	s_addc_u32 s30, s20, s1
	s_mul_i32 s33, s38, 0xfea00000
	s_mul_hi_i32 s31, s38, 0xfea00000
	s_add_u32 s94, s27, s33
	s_addc_u32 s95, s30, s31
	s_add_u32 s25, s54, s25
	s_addc_u32 s1, s55, s1
	s_mul_i32 s30, s38, 0xffea0000
	s_mul_hi_i32 s27, s38, 0xffea0000
	s_add_u32 s25, s25, s30
	s_addc_u32 s1, s1, s27
	s_add_u32 s52, s25, 0x5600000
	s_addc_u32 s53, s1, 0
	s_add_u32 s50, s25, 0x5780000
	s_addc_u32 s51, s1, 0
	v_lshrrev_b32_e32 v15, 1, v14
	s_add_u32 s92, s25, 0x5900000
	v_and_b32_e32 v15, 24, v15
	s_addc_u32 s93, s1, 0
	v_and_b32_e32 v216, 15, v14
	s_lshl_b32 s1, s10, 6
	v_lshlrev_b32_e32 v16, 1, v15
	v_lshlrev_b32_e32 v14, 2, v14
	v_writelane_b32 v254, s1, 61
	v_lshl_or_b32 v16, v216, 6, v16
	s_lshl_b32 s1, s10, 13
	v_and_b32_e32 v14, 32, v14
	v_bitop3_b32 v17, v16, s1, v14 bitop3:0xde
	s_lshl_b32 s1, s11, 5
	s_and_b32 s1, s1, 0x60
	s_add_i32 m0, s75, 0x18000
	v_lshl_add_u64 v[6:7], v[6:7], 0, s[18:19]
	s_lshl_b32 s10, s1, 7
	s_waitcnt vmcnt(4)
	s_barrier
	global_load_lds_dwordx4 v[6:7], off
	v_lshl_add_u64 v[4:5], v[4:5], 0, s[18:19]
	s_add_i32 m0, s75, 0x1a000
	s_add_i32 s31, s75, 0x8000
	s_add_i32 s34, s75, 0xa000
	v_bitop3_b32 v217, v16, s10, v14 bitop3:0xde
	v_add_u32_e32 v217, 0x10000, v217
	global_load_lds_dwordx4 v[4:5], off
	v_lshl_add_u64 v[2:3], v[2:3], 0, s[18:19]
	s_mov_b32 m0, s31
	s_add_u32 s10, s82, 0x40080
	global_load_lds_dwordx4 v[2:3], off
	v_lshl_add_u64 v[0:1], v[0:1], 0, s[18:19]
	s_mov_b32 m0, s34
	s_addc_u32 s11, s83, 0
	global_load_lds_dwordx4 v[0:1], off
	s_add_i32 m0, s75, 0x1c000
	v_lshl_add_u64 v[0:1], s[10:11], 0, v[144:145]
	global_load_lds_dwordx4 v[0:1], off
	v_lshl_add_u64 v[0:1], s[10:11], 0, v[162:163]
	s_add_i32 m0, s75, 0x1e000
	s_ashr_i32 s30, s8, 31
	global_load_lds_dwordx4 v[0:1], off
	v_lshlrev_b32_e32 v0, 14, v8
	v_and_b32_e32 v0, 0xffff8000, v0
	v_lshl_add_u32 v0, v9, 11, v0
	v_and_b32_e32 v1, 1, v8
	v_lshl_or_b32 v0, v1, 6, v0
	v_lshl_add_u32 v164, v10, 1, v0
	v_lshlrev_b32_e32 v0, 14, v11
	s_add_u32 s60, s68, 0x2c00
	v_and_b32_e32 v0, 0xffff8000, v0
	s_waitcnt vmcnt(6)
	s_addc_u32 s61, s69, 0
	v_lshl_add_u32 v0, v12, 11, v0
	v_and_b32_e32 v1, 1, v11
	v_readlane_b32 s41, v252, 5
	v_readlane_b32 s42, v252, 6
	v_readlane_b32 s43, v252, 7
	s_add_u32 s64, s68, 0x5800
	v_lshl_or_b32 v0, v1, 6, v0
	v_readlane_b32 s48, v252, 38
	s_mov_b32 s35, 0
	v_cmp_eq_u32_e64 s[38:39], 0, v216
	v_cmp_lt_u32_e64 s[40:41], 1, v216
	v_cmp_gt_u32_e64 s[42:43], 2, v216
	v_cmp_lt_u32_e64 s[44:45], 13, v216
	v_add_u32_e32 v218, -14, v216
	s_addc_u32 s65, s69, 0
	v_or_b32_e32 v219, s1, v15
	v_mov_b32_e32 v165, v145
	v_lshl_add_u32 v166, v13, 1, v0
	v_mov_b32_e32 v167, v145
	v_add_u32_e32 v220, 0, v17
	v_readlane_b32 s49, v252, 39
	s_barrier
	v_readfirstlane_b32 s101, v208
	s_nop 3
	s_lshr_b32 s101, s101, 8
	s_cmp_eq_u32 s101, 0
	s_cbranch_scc1 .Lprio_d_done
	s_setprio 1

.LBB0_124:
	s_ashr_i32 s79, s78, 31
	s_lshl_b64 s[10:11], s[78:79], 19
	s_add_u32 s80, s54, s10
	v_cmp_lt_i64_e32 vcc, s[72:73], v[178:179]
	s_addc_u32 s81, s55, s11
	s_and_b64 s[10:11], vcc, exec
	s_cselect_b32 s1, s81, s87
	s_cselect_b32 s10, s80, s86
	s_ashr_i32 s77, s76, 31
	s_lshl_b64 s[36:37], s[76:77], 19
	s_add_u32 s72, s66, s36
	s_addc_u32 s73, s59, s37
	s_and_b64 s[36:37], vcc, exec
	s_cselect_b32 s11, s73, s83
	s_cselect_b32 s25, s72, s82
	s_add_u32 s86, s86, 0x40080
	s_addc_u32 s87, s87, 0
	s_add_u32 s33, s82, 0x100
	s_addc_u32 s36, s83, 0
	s_mov_b32 s37, -2
	s_add_u32 s27, s86, 0xfffc0080
	s_addc_u32 s56, s87, -1
	s_add_i32 s57, 0, 0x10000
	ds_read_b128 v[64:67], v217
	ds_read_b128 v[68:71], v217 offset:1024
	ds_read_b128 v[72:75], v217 offset:2048
	ds_read_b128 v[76:79], v217 offset:3072
	s_cmp_eq_u32 s37, 12
	s_cselect_b32 vcc_hi, s1, s56
	s_cselect_b32 vcc_lo, s10, s27
	s_cselect_b32 s83, s11, s36
	s_cselect_b32 s82, s25, s33
	s_add_i32 m0, s75, 0xc000
	ds_read_b128 v[80:83], v220
	ds_read_b128 v[84:87], v220 offset:1024
	ds_read_b128 v[88:91], v220 offset:2048
	ds_read_b128 v[92:95], v220 offset:3072
	ds_read_b128 v[188:191], v220 offset:4096
	ds_read_b128 v[192:195], v220 offset:5120
	ds_read_b128 v[196:199], v220 offset:6144
	ds_read_b128 v[200:203], v220 offset:7168
	global_load_lds_dwordx4 v164, s[86:87]
	s_add_i32 m0, s75, 0xe000
	s_nop 0
	global_load_lds_dwordx4 v166, s[86:87]
	s_waitcnt lgkmcnt(8)
	s_barrier
	s_waitcnt lgkmcnt(0)
	v_mfma_f32_16x16x32_bf16 v[146:149], v[64:67], v[80:83], 0
	v_mfma_f32_16x16x32_bf16 v[116:119], v[72:75], v[80:83], 0
	v_mfma_f32_16x16x32_bf16 v[158:161], v[64:67], v[88:91], 0
	v_mfma_f32_16x16x32_bf16 v[124:127], v[72:75], v[88:91], 0
	v_mfma_f32_16x16x32_bf16 v[154:157], v[64:67], v[188:191], 0
	v_mfma_f32_16x16x32_bf16 v[112:115], v[72:75], v[188:191], 0
	v_mfma_f32_16x16x32_bf16 v[150:153], v[64:67], v[196:199], 0
	v_mfma_f32_16x16x32_bf16 v[120:123], v[72:75], v[196:199], 0
	v_mfma_f32_16x16x32_bf16 v[146:149], v[68:71], v[84:87], v[146:149]
	v_mfma_f32_16x16x32_bf16 v[116:119], v[76:79], v[84:87], v[116:119]
	v_mfma_f32_16x16x32_bf16 v[158:161], v[68:71], v[92:95], v[158:161]
	v_mfma_f32_16x16x32_bf16 v[124:127], v[76:79], v[92:95], v[124:127]
	v_mfma_f32_16x16x32_bf16 v[154:157], v[68:71], v[192:195], v[154:157]
	v_mfma_f32_16x16x32_bf16 v[112:115], v[76:79], v[192:195], v[112:115]
	v_mfma_f32_16x16x32_bf16 v[150:153], v[68:71], v[200:203], v[150:153]
	v_mfma_f32_16x16x32_bf16 v[120:123], v[76:79], v[200:203], v[120:123]
	s_barrier
	s_add_i32 s27, 0, 0x14000
	s_add_i32 s56, s57, s74
	ds_read_b128 v[204:207], v217 offset:16384
	ds_read_b128 v[222:225], v217 offset:17408
	ds_read_b128 v[228:231], v217 offset:18432
	ds_read_b128 v[232:235], v217 offset:19456
	s_mov_b32 m0, s56
	global_load_lds_dwordx4 v144, s[82:83]
	s_add_i32 m0, s56, 0x2000
	s_nop 0
	global_load_lds_dwordx4 v162, s[82:83]
	s_barrier
	s_waitcnt lgkmcnt(0)
	v_mfma_f32_16x16x32_bf16 v[140:143], v[204:207], v[80:83], 0
	v_mfma_f32_16x16x32_bf16 v[80:83], v[228:231], v[80:83], 0
	v_mfma_f32_16x16x32_bf16 v[140:143], v[222:225], v[84:87], v[140:143]
	v_mfma_f32_16x16x32_bf16 v[80:83], v[232:235], v[84:87], v[80:83]
	v_mfma_f32_16x16x32_bf16 v[84:87], v[204:207], v[88:91], 0
	v_mfma_f32_16x16x32_bf16 v[88:91], v[228:231], v[88:91], 0
	v_mfma_f32_16x16x32_bf16 v[100:103], v[228:231], v[188:191], 0
	v_mfma_f32_16x16x32_bf16 v[104:107], v[204:207], v[196:199], 0
	v_mfma_f32_16x16x32_bf16 v[96:99], v[228:231], v[196:199], 0
	v_mfma_f32_16x16x32_bf16 v[84:87], v[222:225], v[92:95], v[84:87]
	v_mfma_f32_16x16x32_bf16 v[88:91], v[232:235], v[92:95], v[88:91]
	v_mfma_f32_16x16x32_bf16 v[92:95], v[204:207], v[188:191], 0
	v_mfma_f32_16x16x32_bf16 v[100:103], v[232:235], v[192:195], v[100:103]
	v_mfma_f32_16x16x32_bf16 v[128:131], v[222:225], v[200:203], v[104:107]
	v_mfma_f32_16x16x32_bf16 v[96:99], v[232:235], v[200:203], v[96:99]
	v_mfma_f32_16x16x32_bf16 v[92:95], v[222:225], v[192:195], v[92:95]
	s_barrier
	s_mov_b32 m0, s75
	ds_read_b128 v[104:107], v220 offset:16384
	ds_read_b128 v[108:111], v220 offset:17408
	ds_read_b128 v[132:135], v220 offset:18432
	ds_read_b128 v[136:139], v220 offset:19456
	ds_read_b128 v[188:191], v220 offset:20480
	ds_read_b128 v[192:195], v220 offset:21504
	ds_read_b128 v[196:199], v220 offset:22528
	ds_read_b128 v[200:203], v220 offset:23552
	global_load_lds_dwordx4 v144, vcc
	s_mov_b32 m0, s85
	s_nop 0
	global_load_lds_dwordx4 v162, vcc
	s_barrier
	s_waitcnt lgkmcnt(0)
	v_mfma_f32_16x16x32_bf16 v[48:51], v[64:67], v[104:107], 0
	v_mfma_f32_16x16x32_bf16 v[20:23], v[72:75], v[104:107], 0
	v_mfma_f32_16x16x32_bf16 v[60:63], v[64:67], v[132:135], 0
	v_mfma_f32_16x16x32_bf16 v[28:31], v[72:75], v[132:135], 0
	v_mfma_f32_16x16x32_bf16 v[56:59], v[64:67], v[188:191], 0
	v_mfma_f32_16x16x32_bf16 v[16:19], v[72:75], v[188:191], 0
	v_mfma_f32_16x16x32_bf16 v[52:55], v[64:67], v[196:199], 0
	v_mfma_f32_16x16x32_bf16 v[24:27], v[72:75], v[196:199], 0
	v_mfma_f32_16x16x32_bf16 v[48:51], v[68:71], v[108:111], v[48:51]
	v_mfma_f32_16x16x32_bf16 v[20:23], v[76:79], v[108:111], v[20:23]
	v_mfma_f32_16x16x32_bf16 v[60:63], v[68:71], v[136:139], v[60:63]
	v_mfma_f32_16x16x32_bf16 v[28:31], v[76:79], v[136:139], v[28:31]
	v_mfma_f32_16x16x32_bf16 v[56:59], v[68:71], v[192:195], v[56:59]
	v_mfma_f32_16x16x32_bf16 v[16:19], v[76:79], v[192:195], v[16:19]
	v_mfma_f32_16x16x32_bf16 v[52:55], v[68:71], v[200:203], v[52:55]
	v_mfma_f32_16x16x32_bf16 v[24:27], v[76:79], v[200:203], v[24:27]
	s_barrier
	s_add_u32 s56, s82, 0x40000
	s_addc_u32 s57, s83, 0
	s_add_i32 s27, s27, s74
	s_mov_b32 m0, s27
	s_nop 0
	global_load_lds_dwordx4 v144, s[56:57]
	s_add_i32 m0, s27, 0x2000
	s_nop 0
	global_load_lds_dwordx4 v162, s[56:57]
	s_waitcnt vmcnt(6)
	s_barrier
	v_mfma_f32_16x16x32_bf16 v[44:47], v[204:207], v[104:107], 0
	v_mfma_f32_16x16x32_bf16 v[12:15], v[228:231], v[104:107], 0
	v_mfma_f32_16x16x32_bf16 v[40:43], v[204:207], v[132:135], 0
	v_mfma_f32_16x16x32_bf16 v[8:11], v[228:231], v[132:135], 0
	v_mfma_f32_16x16x32_bf16 v[36:39], v[204:207], v[188:191], 0
	v_mfma_f32_16x16x32_bf16 v[4:7], v[228:231], v[188:191], 0
	v_mfma_f32_16x16x32_bf16 v[32:35], v[204:207], v[196:199], 0
	v_mfma_f32_16x16x32_bf16 v[0:3], v[228:231], v[196:199], 0
	v_mfma_f32_16x16x32_bf16 v[44:47], v[222:225], v[108:111], v[44:47]
	v_mfma_f32_16x16x32_bf16 v[12:15], v[232:235], v[108:111], v[12:15]
	v_mfma_f32_16x16x32_bf16 v[40:43], v[222:225], v[136:139], v[40:43]
	v_mfma_f32_16x16x32_bf16 v[8:11], v[232:235], v[136:139], v[8:11]
	v_mfma_f32_16x16x32_bf16 v[36:39], v[222:225], v[192:195], v[36:39]
	v_mfma_f32_16x16x32_bf16 v[4:7], v[232:235], v[192:195], v[4:7]
	v_mfma_f32_16x16x32_bf16 v[32:35], v[222:225], v[200:203], v[32:35]
	v_mfma_f32_16x16x32_bf16 v[0:3], v[232:235], v[200:203], v[0:3]
	s_barrier
	s_add_i32 s27, 0, 0x18000
	ds_read_b128 v[64:67], v217 offset:32768
	ds_read_b128 v[68:71], v217 offset:33792
	ds_read_b128 v[72:75], v217 offset:34816
	ds_read_b128 v[76:79], v217 offset:35840
	s_add_u32 s56, vcc_lo, 0x40000
	s_addc_u32 s57, vcc_hi, 0
	s_mov_b32 m0, s98
	ds_read_b128 v[104:107], v220 offset:32768
	ds_read_b128 v[108:111], v220 offset:33792
	ds_read_b128 v[132:135], v220 offset:34816
	ds_read_b128 v[188:191], v220 offset:35840
	ds_read_b128 v[192:195], v220 offset:36864
	ds_read_b128 v[196:199], v220 offset:37888
	ds_read_b128 v[200:203], v220 offset:38912
	ds_read_b128 v[204:207], v220 offset:39936
	global_load_lds_dwordx4 v144, s[56:57]
	s_mov_b32 m0, s29
	s_nop 0
	global_load_lds_dwordx4 v162, s[56:57]
	s_waitcnt lgkmcnt(8)
	s_barrier
	s_waitcnt lgkmcnt(0)
	v_mfma_f32_16x16x32_bf16 v[136:139], v[64:67], v[104:107], v[146:149]
	v_mfma_f32_16x16x32_bf16 v[146:149], v[68:71], v[108:111], v[136:139]
	v_mfma_f32_16x16x32_bf16 v[136:139], v[64:67], v[132:135], v[158:161]
	v_mfma_f32_16x16x32_bf16 v[158:161], v[68:71], v[188:191], v[136:139]
	v_mfma_f32_16x16x32_bf16 v[136:139], v[64:67], v[192:195], v[154:157]
	v_mfma_f32_16x16x32_bf16 v[116:119], v[72:75], v[104:107], v[116:119]
	v_mfma_f32_16x16x32_bf16 v[124:127], v[72:75], v[132:135], v[124:127]
	v_mfma_f32_16x16x32_bf16 v[154:157], v[68:71], v[196:199], v[136:139]
	v_mfma_f32_16x16x32_bf16 v[112:115], v[72:75], v[192:195], v[112:115]
	v_mfma_f32_16x16x32_bf16 v[136:139], v[64:67], v[200:203], v[150:153]
	v_mfma_f32_16x16x32_bf16 v[120:123], v[72:75], v[200:203], v[120:123]
	v_mfma_f32_16x16x32_bf16 v[116:119], v[76:79], v[108:111], v[116:119]
	v_mfma_f32_16x16x32_bf16 v[124:127], v[76:79], v[188:191], v[124:127]
	v_mfma_f32_16x16x32_bf16 v[112:115], v[76:79], v[196:199], v[112:115]
	v_mfma_f32_16x16x32_bf16 v[150:153], v[68:71], v[204:207], v[136:139]
	v_mfma_f32_16x16x32_bf16 v[120:123], v[76:79], v[204:207], v[120:123]
	s_barrier
	s_add_i32 s58, 0, 0x1c000
	s_add_i32 s27, s27, s74
	ds_read_b128 v[222:225], v217 offset:49152
	ds_read_b128 v[228:231], v217 offset:50176
	ds_read_b128 v[232:235], v217 offset:51200
	ds_read_b128 v[236:239], v217 offset:52224
	s_add_u32 s56, s82, s18
	s_addc_u32 s57, s83, s19
	s_mov_b32 m0, s27
	s_nop 0
	global_load_lds_dwordx4 v144, s[56:57]
	s_add_u32 s56, s82, s18
	s_addc_u32 s57, s83, s19
	s_add_i32 m0, s27, 0x2000
	s_nop 0
	global_load_lds_dwordx4 v162, s[56:57]
	s_barrier
	s_waitcnt lgkmcnt(0)
	v_mfma_f32_16x16x32_bf16 v[136:139], v[222:225], v[104:107], v[140:143]
	v_mfma_f32_16x16x32_bf16 v[80:83], v[232:235], v[104:107], v[80:83]
	v_mfma_f32_16x16x32_bf16 v[140:143], v[228:231], v[108:111], v[136:139]
	v_mfma_f32_16x16x32_bf16 v[108:111], v[236:239], v[108:111], v[80:83]
	v_mfma_f32_16x16x32_bf16 v[80:83], v[222:225], v[132:135], v[84:87]
	v_mfma_f32_16x16x32_bf16 v[136:139], v[228:231], v[188:191], v[80:83]
	v_mfma_f32_16x16x32_bf16 v[80:83], v[232:235], v[132:135], v[88:91]
	v_mfma_f32_16x16x32_bf16 v[104:107], v[236:239], v[188:191], v[80:83]
	v_mfma_f32_16x16x32_bf16 v[80:83], v[222:225], v[192:195], v[92:95]
	v_mfma_f32_16x16x32_bf16 v[132:135], v[228:231], v[196:199], v[80:83]
	v_mfma_f32_16x16x32_bf16 v[80:83], v[232:235], v[192:195], v[100:103]
	v_mfma_f32_16x16x32_bf16 v[100:103], v[236:239], v[196:199], v[80:83]
	v_mfma_f32_16x16x32_bf16 v[80:83], v[222:225], v[200:203], v[128:131]
	v_mfma_f32_16x16x32_bf16 v[128:131], v[228:231], v[204:207], v[80:83]
	v_mfma_f32_16x16x32_bf16 v[80:83], v[232:235], v[200:203], v[96:99]
	v_mfma_f32_16x16x32_bf16 v[96:99], v[236:239], v[204:207], v[80:83]
	s_barrier
	s_mov_b32 m0, s31
	s_add_u32 s56, vcc_lo, s18
	s_addc_u32 s57, vcc_hi, s19
	s_nop 2
	ds_read_b128 v[80:83], v220 offset:49152
	ds_read_b128 v[84:87], v220 offset:50176
	ds_read_b128 v[88:91], v220 offset:51200
	ds_read_b128 v[92:95], v220 offset:52224
	ds_read_b128 v[188:191], v220 offset:53248
	ds_read_b128 v[192:195], v220 offset:54272
	ds_read_b128 v[196:199], v220 offset:55296
	ds_read_b128 v[200:203], v220 offset:56320
	global_load_lds_dwordx4 v144, s[56:57]
	s_add_u32 s56, vcc_lo, s18
	s_addc_u32 s57, vcc_hi, s19
	s_mov_b32 m0, s34
	s_nop 0
	global_load_lds_dwordx4 v162, s[56:57]
	s_barrier
	s_waitcnt lgkmcnt(0)
	v_mfma_f32_16x16x32_bf16 v[48:51], v[64:67], v[80:83], v[48:51]
	v_mfma_f32_16x16x32_bf16 v[20:23], v[72:75], v[80:83], v[20:23]
	v_mfma_f32_16x16x32_bf16 v[60:63], v[64:67], v[88:91], v[60:63]
	v_mfma_f32_16x16x32_bf16 v[28:31], v[72:75], v[88:91], v[28:31]
	v_mfma_f32_16x16x32_bf16 v[56:59], v[64:67], v[188:191], v[56:59]
	v_mfma_f32_16x16x32_bf16 v[16:19], v[72:75], v[188:191], v[16:19]
	v_mfma_f32_16x16x32_bf16 v[52:55], v[64:67], v[196:199], v[52:55]
	v_mfma_f32_16x16x32_bf16 v[24:27], v[72:75], v[196:199], v[24:27]
	v_mfma_f32_16x16x32_bf16 v[48:51], v[68:71], v[84:87], v[48:51]
	v_mfma_f32_16x16x32_bf16 v[20:23], v[76:79], v[84:87], v[20:23]
	v_mfma_f32_16x16x32_bf16 v[60:63], v[68:71], v[92:95], v[60:63]
	v_mfma_f32_16x16x32_bf16 v[28:31], v[76:79], v[92:95], v[28:31]
	v_mfma_f32_16x16x32_bf16 v[56:59], v[68:71], v[192:195], v[56:59]
	v_mfma_f32_16x16x32_bf16 v[16:19], v[76:79], v[192:195], v[16:19]
	v_mfma_f32_16x16x32_bf16 v[52:55], v[68:71], v[200:203], v[52:55]
	v_mfma_f32_16x16x32_bf16 v[24:27], v[76:79], v[200:203], v[24:27]
	s_barrier
	s_add_u32 s56, s82, 0x40080
	s_addc_u32 s57, s83, 0
	s_add_i32 s27, s58, s74
	s_mov_b32 m0, s27
	s_nop 0
	global_load_lds_dwordx4 v144, s[56:57]
	s_add_i32 m0, s27, 0x2000
	s_nop 0
	global_load_lds_dwordx4 v162, s[56:57]
	s_waitcnt vmcnt(6)
	s_barrier
	v_mfma_f32_16x16x32_bf16 v[44:47], v[222:225], v[80:83], v[44:47]
	v_mfma_f32_16x16x32_bf16 v[12:15], v[232:235], v[80:83], v[12:15]
	v_mfma_f32_16x16x32_bf16 v[40:43], v[222:225], v[88:91], v[40:43]
	v_mfma_f32_16x16x32_bf16 v[8:11], v[232:235], v[88:91], v[8:11]
	v_mfma_f32_16x16x32_bf16 v[36:39], v[222:225], v[188:191], v[36:39]
	v_mfma_f32_16x16x32_bf16 v[4:7], v[232:235], v[188:191], v[4:7]
	v_mfma_f32_16x16x32_bf16 v[32:35], v[222:225], v[196:199], v[32:35]
	v_mfma_f32_16x16x32_bf16 v[0:3], v[232:235], v[196:199], v[0:3]
	v_mfma_f32_16x16x32_bf16 v[44:47], v[228:231], v[84:87], v[44:47]
	v_mfma_f32_16x16x32_bf16 v[12:15], v[236:239], v[84:87], v[12:15]
	v_mfma_f32_16x16x32_bf16 v[40:43], v[228:231], v[92:95], v[40:43]
	v_mfma_f32_16x16x32_bf16 v[8:11], v[236:239], v[92:95], v[8:11]
	v_mfma_f32_16x16x32_bf16 v[36:39], v[228:231], v[192:195], v[36:39]
	v_mfma_f32_16x16x32_bf16 v[4:7], v[236:239], v[192:195], v[4:7]
	v_mfma_f32_16x16x32_bf16 v[32:35], v[228:231], v[200:203], v[32:35]
	v_mfma_f32_16x16x32_bf16 v[0:3], v[236:239], v[200:203], v[0:3]
	s_barrier
	s_add_i32 s37, s37, 2
	s_add_u32 s86, s86, 0x100
	s_addc_u32 s87, s87, 0
	s_add_u32 s33, s33, 0x100
	s_addc_u32 s36, s36, 0
	s_cmp_gt_u32 s37, 13
.LBB0_125:
	s_add_u32 s27, s86, 0xfffc0080
	s_addc_u32 s56, s87, -1
	s_add_i32 s57, 0, 0x10000
	ds_read_b128 v[64:67], v217
	ds_read_b128 v[68:71], v217 offset:1024
	ds_read_b128 v[72:75], v217 offset:2048
	ds_read_b128 v[76:79], v217 offset:3072
	s_cmp_eq_u32 s37, 12
	s_cselect_b32 vcc_hi, s1, s56
	s_cselect_b32 vcc_lo, s10, s27
	s_cselect_b32 s83, s11, s36
	s_cselect_b32 s82, s25, s33
	s_add_i32 m0, s75, 0xc000
	ds_read_b128 v[80:83], v220
	ds_read_b128 v[84:87], v220 offset:1024
	ds_read_b128 v[88:91], v220 offset:2048
	ds_read_b128 v[92:95], v220 offset:3072
	ds_read_b128 v[188:191], v220 offset:4096
	ds_read_b128 v[192:195], v220 offset:5120
	ds_read_b128 v[196:199], v220 offset:6144
	ds_read_b128 v[200:203], v220 offset:7168
	global_load_lds_dwordx4 v164, s[86:87]
	s_add_i32 m0, s75, 0xe000
	s_nop 0
	global_load_lds_dwordx4 v166, s[86:87]
	s_waitcnt lgkmcnt(8)
	s_barrier
	s_waitcnt lgkmcnt(0)
	v_mfma_f32_16x16x32_bf16 v[146:149], v[64:67], v[80:83], v[146:149]
	v_mfma_f32_16x16x32_bf16 v[116:119], v[72:75], v[80:83], v[116:119]
	v_mfma_f32_16x16x32_bf16 v[158:161], v[64:67], v[88:91], v[158:161]
	v_mfma_f32_16x16x32_bf16 v[124:127], v[72:75], v[88:91], v[124:127]
	v_mfma_f32_16x16x32_bf16 v[154:157], v[64:67], v[188:191], v[154:157]
	v_mfma_f32_16x16x32_bf16 v[112:115], v[72:75], v[188:191], v[112:115]
	v_mfma_f32_16x16x32_bf16 v[150:153], v[64:67], v[196:199], v[150:153]
	v_mfma_f32_16x16x32_bf16 v[120:123], v[72:75], v[196:199], v[120:123]
	v_mfma_f32_16x16x32_bf16 v[146:149], v[68:71], v[84:87], v[146:149]
	v_mfma_f32_16x16x32_bf16 v[116:119], v[76:79], v[84:87], v[116:119]
	v_mfma_f32_16x16x32_bf16 v[158:161], v[68:71], v[92:95], v[158:161]
	v_mfma_f32_16x16x32_bf16 v[124:127], v[76:79], v[92:95], v[124:127]
	v_mfma_f32_16x16x32_bf16 v[154:157], v[68:71], v[192:195], v[154:157]
	v_mfma_f32_16x16x32_bf16 v[112:115], v[76:79], v[192:195], v[112:115]
	v_mfma_f32_16x16x32_bf16 v[150:153], v[68:71], v[200:203], v[150:153]
	v_mfma_f32_16x16x32_bf16 v[120:123], v[76:79], v[200:203], v[120:123]
	s_barrier
	s_add_i32 s27, 0, 0x14000
	s_add_i32 s56, s57, s74
	ds_read_b128 v[204:207], v217 offset:16384
	ds_read_b128 v[222:225], v217 offset:17408
	ds_read_b128 v[228:231], v217 offset:18432
	ds_read_b128 v[232:235], v217 offset:19456
	s_mov_b32 m0, s56
	global_load_lds_dwordx4 v144, s[82:83]
	s_add_i32 m0, s56, 0x2000
	s_nop 0
	global_load_lds_dwordx4 v162, s[82:83]
	s_barrier
	s_waitcnt lgkmcnt(0)
	v_mfma_f32_16x16x32_bf16 v[140:143], v[204:207], v[80:83], v[140:143]
	v_mfma_f32_16x16x32_bf16 v[80:83], v[228:231], v[80:83], v[108:111]
	v_mfma_f32_16x16x32_bf16 v[140:143], v[222:225], v[84:87], v[140:143]
	v_mfma_f32_16x16x32_bf16 v[80:83], v[232:235], v[84:87], v[80:83]
	v_mfma_f32_16x16x32_bf16 v[84:87], v[204:207], v[88:91], v[136:139]
	v_mfma_f32_16x16x32_bf16 v[88:91], v[228:231], v[88:91], v[104:107]
	v_mfma_f32_16x16x32_bf16 v[100:103], v[228:231], v[188:191], v[100:103]
	v_mfma_f32_16x16x32_bf16 v[104:107], v[204:207], v[196:199], v[128:131]
	v_mfma_f32_16x16x32_bf16 v[96:99], v[228:231], v[196:199], v[96:99]
	v_mfma_f32_16x16x32_bf16 v[84:87], v[222:225], v[92:95], v[84:87]
	v_mfma_f32_16x16x32_bf16 v[88:91], v[232:235], v[92:95], v[88:91]
	v_mfma_f32_16x16x32_bf16 v[92:95], v[204:207], v[188:191], v[132:135]
	v_mfma_f32_16x16x32_bf16 v[100:103], v[232:235], v[192:195], v[100:103]
	v_mfma_f32_16x16x32_bf16 v[128:131], v[222:225], v[200:203], v[104:107]
	v_mfma_f32_16x16x32_bf16 v[96:99], v[232:235], v[200:203], v[96:99]
	v_mfma_f32_16x16x32_bf16 v[92:95], v[222:225], v[192:195], v[92:95]
	s_barrier
	s_mov_b32 m0, s75
	ds_read_b128 v[104:107], v220 offset:16384
	ds_read_b128 v[108:111], v220 offset:17408
	ds_read_b128 v[132:135], v220 offset:18432
	ds_read_b128 v[136:139], v220 offset:19456
	ds_read_b128 v[188:191], v220 offset:20480
	ds_read_b128 v[192:195], v220 offset:21504
	ds_read_b128 v[196:199], v220 offset:22528
	ds_read_b128 v[200:203], v220 offset:23552
	global_load_lds_dwordx4 v144, vcc
	s_mov_b32 m0, s85
	s_nop 0
	global_load_lds_dwordx4 v162, vcc
	s_barrier
	s_waitcnt lgkmcnt(0)
	v_mfma_f32_16x16x32_bf16 v[48:51], v[64:67], v[104:107], v[48:51]
	v_mfma_f32_16x16x32_bf16 v[20:23], v[72:75], v[104:107], v[20:23]
	v_mfma_f32_16x16x32_bf16 v[60:63], v[64:67], v[132:135], v[60:63]
	v_mfma_f32_16x16x32_bf16 v[28:31], v[72:75], v[132:135], v[28:31]
	v_mfma_f32_16x16x32_bf16 v[56:59], v[64:67], v[188:191], v[56:59]
	v_mfma_f32_16x16x32_bf16 v[16:19], v[72:75], v[188:191], v[16:19]
	v_mfma_f32_16x16x32_bf16 v[52:55], v[64:67], v[196:199], v[52:55]
	v_mfma_f32_16x16x32_bf16 v[24:27], v[72:75], v[196:199], v[24:27]
	v_mfma_f32_16x16x32_bf16 v[48:51], v[68:71], v[108:111], v[48:51]
	v_mfma_f32_16x16x32_bf16 v[20:23], v[76:79], v[108:111], v[20:23]
	v_mfma_f32_16x16x32_bf16 v[60:63], v[68:71], v[136:139], v[60:63]
	v_mfma_f32_16x16x32_bf16 v[28:31], v[76:79], v[136:139], v[28:31]
	v_mfma_f32_16x16x32_bf16 v[56:59], v[68:71], v[192:195], v[56:59]
	v_mfma_f32_16x16x32_bf16 v[16:19], v[76:79], v[192:195], v[16:19]
	v_mfma_f32_16x16x32_bf16 v[52:55], v[68:71], v[200:203], v[52:55]
	v_mfma_f32_16x16x32_bf16 v[24:27], v[76:79], v[200:203], v[24:27]
	s_barrier
	s_add_u32 s56, s82, 0x40000
	s_addc_u32 s57, s83, 0
	s_add_i32 s27, s27, s74
	s_mov_b32 m0, s27
	s_nop 0
	global_load_lds_dwordx4 v144, s[56:57]
	s_add_i32 m0, s27, 0x2000
	s_nop 0
	global_load_lds_dwordx4 v162, s[56:57]
	s_waitcnt vmcnt(6)
	s_barrier
	v_mfma_f32_16x16x32_bf16 v[44:47], v[204:207], v[104:107], v[44:47]
	v_mfma_f32_16x16x32_bf16 v[12:15], v[228:231], v[104:107], v[12:15]
	v_mfma_f32_16x16x32_bf16 v[40:43], v[204:207], v[132:135], v[40:43]
	v_mfma_f32_16x16x32_bf16 v[8:11], v[228:231], v[132:135], v[8:11]
	v_mfma_f32_16x16x32_bf16 v[36:39], v[204:207], v[188:191], v[36:39]
	v_mfma_f32_16x16x32_bf16 v[4:7], v[228:231], v[188:191], v[4:7]
	v_mfma_f32_16x16x32_bf16 v[32:35], v[204:207], v[196:199], v[32:35]
	v_mfma_f32_16x16x32_bf16 v[0:3], v[228:231], v[196:199], v[0:3]
	v_mfma_f32_16x16x32_bf16 v[44:47], v[222:225], v[108:111], v[44:47]
	v_mfma_f32_16x16x32_bf16 v[12:15], v[232:235], v[108:111], v[12:15]
	v_mfma_f32_16x16x32_bf16 v[40:43], v[222:225], v[136:139], v[40:43]
	v_mfma_f32_16x16x32_bf16 v[8:11], v[232:235], v[136:139], v[8:11]
	v_mfma_f32_16x16x32_bf16 v[36:39], v[222:225], v[192:195], v[36:39]
	v_mfma_f32_16x16x32_bf16 v[4:7], v[232:235], v[192:195], v[4:7]
	v_mfma_f32_16x16x32_bf16 v[32:35], v[222:225], v[200:203], v[32:35]
	v_mfma_f32_16x16x32_bf16 v[0:3], v[232:235], v[200:203], v[0:3]
	s_barrier
	s_add_i32 s27, 0, 0x18000
	ds_read_b128 v[64:67], v217 offset:32768
	ds_read_b128 v[68:71], v217 offset:33792
	ds_read_b128 v[72:75], v217 offset:34816
	ds_read_b128 v[76:79], v217 offset:35840
	s_add_u32 s56, vcc_lo, 0x40000
	s_addc_u32 s57, vcc_hi, 0
	s_mov_b32 m0, s98
	ds_read_b128 v[104:107], v220 offset:32768
	ds_read_b128 v[108:111], v220 offset:33792
	ds_read_b128 v[132:135], v220 offset:34816
	ds_read_b128 v[188:191], v220 offset:35840
	ds_read_b128 v[192:195], v220 offset:36864
	ds_read_b128 v[196:199], v220 offset:37888
	ds_read_b128 v[200:203], v220 offset:38912
	ds_read_b128 v[204:207], v220 offset:39936
	global_load_lds_dwordx4 v144, s[56:57]
	s_mov_b32 m0, s29
	s_nop 0
	global_load_lds_dwordx4 v162, s[56:57]
	s_waitcnt lgkmcnt(8)
	s_barrier
	s_waitcnt lgkmcnt(0)
	v_mfma_f32_16x16x32_bf16 v[136:139], v[64:67], v[104:107], v[146:149]
	v_mfma_f32_16x16x32_bf16 v[146:149], v[68:71], v[108:111], v[136:139]
	v_mfma_f32_16x16x32_bf16 v[136:139], v[64:67], v[132:135], v[158:161]
	v_mfma_f32_16x16x32_bf16 v[158:161], v[68:71], v[188:191], v[136:139]
	v_mfma_f32_16x16x32_bf16 v[136:139], v[64:67], v[192:195], v[154:157]
	v_mfma_f32_16x16x32_bf16 v[116:119], v[72:75], v[104:107], v[116:119]
	v_mfma_f32_16x16x32_bf16 v[124:127], v[72:75], v[132:135], v[124:127]
	v_mfma_f32_16x16x32_bf16 v[154:157], v[68:71], v[196:199], v[136:139]
	v_mfma_f32_16x16x32_bf16 v[112:115], v[72:75], v[192:195], v[112:115]
	v_mfma_f32_16x16x32_bf16 v[136:139], v[64:67], v[200:203], v[150:153]
	v_mfma_f32_16x16x32_bf16 v[120:123], v[72:75], v[200:203], v[120:123]
	v_mfma_f32_16x16x32_bf16 v[116:119], v[76:79], v[108:111], v[116:119]
	v_mfma_f32_16x16x32_bf16 v[124:127], v[76:79], v[188:191], v[124:127]
	v_mfma_f32_16x16x32_bf16 v[112:115], v[76:79], v[196:199], v[112:115]
	v_mfma_f32_16x16x32_bf16 v[150:153], v[68:71], v[204:207], v[136:139]
	v_mfma_f32_16x16x32_bf16 v[120:123], v[76:79], v[204:207], v[120:123]
	s_barrier
	s_add_i32 s58, 0, 0x1c000
	s_add_i32 s27, s27, s74
	ds_read_b128 v[222:225], v217 offset:49152
	ds_read_b128 v[228:231], v217 offset:50176
	ds_read_b128 v[232:235], v217 offset:51200
	ds_read_b128 v[236:239], v217 offset:52224
	s_add_u32 s56, s82, s18
	s_addc_u32 s57, s83, s19
	s_mov_b32 m0, s27
	s_nop 0
	global_load_lds_dwordx4 v144, s[56:57]
	s_add_u32 s56, s82, s18
	s_addc_u32 s57, s83, s19
	s_add_i32 m0, s27, 0x2000
	s_nop 0
	global_load_lds_dwordx4 v162, s[56:57]
	s_barrier
	s_waitcnt lgkmcnt(0)
	v_mfma_f32_16x16x32_bf16 v[136:139], v[222:225], v[104:107], v[140:143]
	v_mfma_f32_16x16x32_bf16 v[80:83], v[232:235], v[104:107], v[80:83]
	v_mfma_f32_16x16x32_bf16 v[140:143], v[228:231], v[108:111], v[136:139]
	v_mfma_f32_16x16x32_bf16 v[108:111], v[236:239], v[108:111], v[80:83]
	v_mfma_f32_16x16x32_bf16 v[80:83], v[222:225], v[132:135], v[84:87]
	v_mfma_f32_16x16x32_bf16 v[136:139], v[228:231], v[188:191], v[80:83]
	v_mfma_f32_16x16x32_bf16 v[80:83], v[232:235], v[132:135], v[88:91]
	v_mfma_f32_16x16x32_bf16 v[104:107], v[236:239], v[188:191], v[80:83]
	v_mfma_f32_16x16x32_bf16 v[80:83], v[222:225], v[192:195], v[92:95]
	v_mfma_f32_16x16x32_bf16 v[132:135], v[228:231], v[196:199], v[80:83]
	v_mfma_f32_16x16x32_bf16 v[80:83], v[232:235], v[192:195], v[100:103]
	v_mfma_f32_16x16x32_bf16 v[100:103], v[236:239], v[196:199], v[80:83]
	v_mfma_f32_16x16x32_bf16 v[80:83], v[222:225], v[200:203], v[128:131]
	v_mfma_f32_16x16x32_bf16 v[128:131], v[228:231], v[204:207], v[80:83]
	v_mfma_f32_16x16x32_bf16 v[80:83], v[232:235], v[200:203], v[96:99]
	v_mfma_f32_16x16x32_bf16 v[96:99], v[236:239], v[204:207], v[80:83]
	s_barrier
	s_mov_b32 m0, s31
	s_add_u32 s56, vcc_lo, s18
	s_addc_u32 s57, vcc_hi, s19
	s_nop 2
	ds_read_b128 v[80:83], v220 offset:49152
	ds_read_b128 v[84:87], v220 offset:50176
	ds_read_b128 v[88:91], v220 offset:51200
	ds_read_b128 v[92:95], v220 offset:52224
	ds_read_b128 v[188:191], v220 offset:53248
	ds_read_b128 v[192:195], v220 offset:54272
	ds_read_b128 v[196:199], v220 offset:55296
	ds_read_b128 v[200:203], v220 offset:56320
	global_load_lds_dwordx4 v144, s[56:57]
	s_add_u32 s56, vcc_lo, s18
	s_addc_u32 s57, vcc_hi, s19
	s_mov_b32 m0, s34
	s_nop 0
	global_load_lds_dwordx4 v162, s[56:57]
	s_barrier
	s_waitcnt lgkmcnt(0)
	v_mfma_f32_16x16x32_bf16 v[48:51], v[64:67], v[80:83], v[48:51]
	v_mfma_f32_16x16x32_bf16 v[20:23], v[72:75], v[80:83], v[20:23]
	v_mfma_f32_16x16x32_bf16 v[60:63], v[64:67], v[88:91], v[60:63]
	v_mfma_f32_16x16x32_bf16 v[28:31], v[72:75], v[88:91], v[28:31]
	v_mfma_f32_16x16x32_bf16 v[56:59], v[64:67], v[188:191], v[56:59]
	v_mfma_f32_16x16x32_bf16 v[16:19], v[72:75], v[188:191], v[16:19]
	v_mfma_f32_16x16x32_bf16 v[52:55], v[64:67], v[196:199], v[52:55]
	v_mfma_f32_16x16x32_bf16 v[24:27], v[72:75], v[196:199], v[24:27]
	v_mfma_f32_16x16x32_bf16 v[48:51], v[68:71], v[84:87], v[48:51]
	v_mfma_f32_16x16x32_bf16 v[20:23], v[76:79], v[84:87], v[20:23]
	v_mfma_f32_16x16x32_bf16 v[60:63], v[68:71], v[92:95], v[60:63]
	v_mfma_f32_16x16x32_bf16 v[28:31], v[76:79], v[92:95], v[28:31]
	v_mfma_f32_16x16x32_bf16 v[56:59], v[68:71], v[192:195], v[56:59]
	v_mfma_f32_16x16x32_bf16 v[16:19], v[76:79], v[192:195], v[16:19]
	v_mfma_f32_16x16x32_bf16 v[52:55], v[68:71], v[200:203], v[52:55]
	v_mfma_f32_16x16x32_bf16 v[24:27], v[76:79], v[200:203], v[24:27]
	s_barrier
	s_add_u32 s56, s82, 0x40080
	s_addc_u32 s57, s83, 0
	s_add_i32 s27, s58, s74
	s_mov_b32 m0, s27
	s_nop 0
	global_load_lds_dwordx4 v144, s[56:57]
	s_add_i32 m0, s27, 0x2000
	s_nop 0
	global_load_lds_dwordx4 v162, s[56:57]
	s_waitcnt vmcnt(6)
	s_barrier
	v_mfma_f32_16x16x32_bf16 v[44:47], v[222:225], v[80:83], v[44:47]
	v_mfma_f32_16x16x32_bf16 v[12:15], v[232:235], v[80:83], v[12:15]
	v_mfma_f32_16x16x32_bf16 v[40:43], v[222:225], v[88:91], v[40:43]
	v_mfma_f32_16x16x32_bf16 v[8:11], v[232:235], v[88:91], v[8:11]
	v_mfma_f32_16x16x32_bf16 v[36:39], v[222:225], v[188:191], v[36:39]
	v_mfma_f32_16x16x32_bf16 v[4:7], v[232:235], v[188:191], v[4:7]
	v_mfma_f32_16x16x32_bf16 v[32:35], v[222:225], v[196:199], v[32:35]
	v_mfma_f32_16x16x32_bf16 v[0:3], v[232:235], v[196:199], v[0:3]
	v_mfma_f32_16x16x32_bf16 v[44:47], v[228:231], v[84:87], v[44:47]
	v_mfma_f32_16x16x32_bf16 v[12:15], v[236:239], v[84:87], v[12:15]
	v_mfma_f32_16x16x32_bf16 v[40:43], v[228:231], v[92:95], v[40:43]
	v_mfma_f32_16x16x32_bf16 v[8:11], v[236:239], v[92:95], v[8:11]
	v_mfma_f32_16x16x32_bf16 v[36:39], v[228:231], v[192:195], v[36:39]
	v_mfma_f32_16x16x32_bf16 v[4:7], v[236:239], v[192:195], v[4:7]
	v_mfma_f32_16x16x32_bf16 v[32:35], v[228:231], v[200:203], v[32:35]
	v_mfma_f32_16x16x32_bf16 v[0:3], v[236:239], v[200:203], v[0:3]
	s_barrier
	s_add_i32 s37, s37, 2
	s_add_u32 s86, s86, 0x100
	s_addc_u32 s87, s87, 0
	s_add_u32 s33, s33, 0x100
	s_addc_u32 s36, s36, 0
	s_cmp_gt_u32 s37, 13
	s_cbranch_scc0 .LBB0_125
	s_lshl_b32 s1, s84, 8
	v_readlane_b32 s10, v254, 61
	s_add_i32 s1, s1, s10
	v_or_b32_e32 v198, s1, v216
	s_add_i32 s10, s1, 0x80
	v_or_b32_e32 v168, s10, v216
	v_lshl_or_b32 v188, s0, 7, v219
	v_lshlrev_b32_e32 v190, 2, v188
	v_lshlrev_b32_e32 v189, 1, v188
	s_ashr_i32 s11, s1, 5
	s_movk_i32 s10, 0xb00
	s_movk_i32 s20, 0x1600
	s_mov_b32 s101, 0xbfb8aa3b
	s_cmp_eq_u32 s84, s100
	s_cbranch_scc1 .Ldepi_w
	v_ashrrev_i32_e32 v199, 31, v198
	v_ashrrev_i32_e32 v169, 31, v168
	v_lshl_add_u64 v[170:171], v[198:199], 3, s[48:49]
	v_lshl_add_u64 v[172:173], v[168:169], 3, s[48:49]
	global_load_dwordx2 v[176:177], v[170:171], off
	global_load_dwordx2 v[202:203], v[170:171], off offset:128
	global_load_dwordx2 v[206:207], v[170:171], off offset:256
	global_load_dwordx2 v[222:223], v[170:171], off offset:384
	global_load_dwordx2 v[200:201], v[172:173], off
	global_load_dwordx2 v[196:197], v[172:173], off offset:128
	global_load_dwordx2 v[194:195], v[172:173], off offset:256
	global_load_dwordx2 v[192:193], v[172:173], off offset:384

.LBB0_181:
	v_readlane_b32 s20, v254, 47
	s_add_i32 s31, s20, 4
	s_cmp_lt_u32 s31, 11
	s_cselect_b64 s[34:35], -1, 0
	s_and_b64 s[34:35], s[34:35], s[0:1]
	v_readlane_b32 s56, v254, 23
	s_and_b64 s[34:35], s[34:35], exec
	v_readlane_b32 s57, v254, 24
	s_cselect_b32 s51, s57, 0
	s_cselect_b32 s50, s56, 0
	s_sub_i32 s31, s20, 25
	s_cmp_lt_u32 s31, -6
	s_cselect_b64 s[34:35], -1, 0
	s_or_b64 s[0:1], s[34:35], s[0:1]
	v_readlane_b32 s40, v252, 0
	s_and_b64 s[0:1], s[0:1], exec
	v_readlane_b32 s42, v252, 2
	v_readlane_b32 s43, v252, 3
	v_bfe_u32 v19, v18, 4, 2
	s_cselect_b32 s95, 0, s43
	s_cselect_b32 s94, 0, s42
	s_add_u32 s52, s54, s38
	v_and_b32_e32 v20, 15, v18
	v_lshlrev_b32_e32 v21, 4, v19
	v_lshlrev_b32_e32 v18, 2, v18
	s_addc_u32 s53, s55, s39
	v_lshl_or_b32 v206, s27, 6, v20
	v_lshl_or_b32 v20, v20, 6, v21
	s_lshl_b32 s0, s27, 13
	v_and_b32_e32 v18, 32, v18
	s_add_i32 m0, s85, 0x18000
	v_lshl_add_u64 v[0:1], v[0:1], 0, s[18:19]
	v_bitop3_b32 v21, v20, s0, v18 bitop3:0xde
	s_lshl_b32 s0, s30, 5
	s_waitcnt vmcnt(4)
	s_barrier
	global_load_lds_dwordx4 v[0:1], off
	v_lshl_add_u64 v[0:1], v[2:3], 0, s[18:19]
	s_add_i32 m0, s85, 0x1a000
	s_add_i32 s30, s85, 0x8000
	global_load_lds_dwordx4 v[0:1], off
	v_lshl_add_u64 v[0:1], v[4:5], 0, s[18:19]
	s_mov_b32 m0, s30
	s_add_i32 s31, s85, 0xa000
	global_load_lds_dwordx4 v[0:1], off
	v_lshl_add_u64 v[0:1], v[6:7], 0, s[18:19]
	s_mov_b32 m0, s31
	s_lshr_b32 s34, s25, 6
	global_load_lds_dwordx4 v[0:1], off
	s_add_i32 m0, s85, 0x1c000
	v_lshl_add_u64 v[0:1], v[8:9], 0, s[18:19]
	global_load_lds_dwordx4 v[0:1], off
	v_lshl_add_u64 v[0:1], v[10:11], 0, s[18:19]
	s_add_i32 m0, s85, 0x1e000
	s_and_b32 s0, s0, 0x60
	global_load_lds_dwordx4 v[0:1], off
	s_lshl_b32 s1, s0, 7
	s_add_i32 s82, s34, -2
	s_ashr_i32 s35, s29, 31
	v_add_u32_e32 v0, v14, v12
	s_cmp_lg_u64 s[50:51], 0
	v_add_lshl_u32 v0, v0, v13, 1
	v_mov_b32_e32 v1, v145
	s_waitcnt vmcnt(6)
	s_cselect_b64 s[92:93], -1, 0
	s_cmp_eq_u64 s[94:95], 0
	v_lshl_add_u64 v[190:191], s[98:99], 0, v[0:1]
	v_add_u32_e32 v0, v17, v15
	s_cselect_b64 s[72:73], -1, 0
	s_cmp_lg_u64 s[94:95], 0
	v_add_lshl_u32 v0, v0, v16, 1
	s_mov_b32 s81, 0
	v_bitop3_b32 v207, v20, s1, v18 bitop3:0xde
	v_add_u32_e32 v207, 0x10000, v207
	v_cmp_eq_u32_e64 s[38:39], 0, v19
	s_cselect_b64 s[74:75], -1, 0
	v_lshl_or_b32 v216, v19, 3, s0
	v_lshl_add_u64 v[192:193], s[98:99], 0, v[0:1]
	v_add_u32_e32 v217, 0, v21
	v_readlane_b32 s58, v254, 25
	v_readlane_b32 s59, v254, 26
	v_readlane_b32 s60, v254, 27
	v_readlane_b32 s61, v254, 28
	v_readlane_b32 s62, v254, 29
	v_readlane_b32 s63, v254, 30
	v_readlane_b32 s64, v254, 31
	v_readlane_b32 s65, v254, 32
	v_readlane_b32 s66, v254, 33
	v_readlane_b32 s67, v254, 34
	v_readlane_b32 s68, v254, 35
	v_readlane_b32 s69, v254, 36
	v_readlane_b32 s70, v254, 37
	v_readlane_b32 s71, v254, 38
	v_readlane_b32 s41, v252, 1
	s_barrier
	v_readfirstlane_b32 s101, v208
	s_nop 3
	s_lshr_b32 s101, s101, 8
	s_cmp_eq_u32 s101, 0
	s_cbranch_scc1 .Lprio_ce_done
	s_setprio 1

.LBB0_195:
	s_add_u32 s42, s78, 0x80
	s_addc_u32 s43, s79, 0
	s_add_u32 s33, s44, 0x100
	s_addc_u32 s37, s45, 0
	s_mov_b32 s27, 0
	s_waitcnt lgkmcnt(0)
	s_add_i32 s56, s27, 2
	s_add_u32 s44, s42, 0x80
	s_addc_u32 s45, s43, 0
	s_add_i32 s57, 0, 0x10000
	ds_read_b128 v[128:131], v207
	ds_read_b128 v[132:135], v207 offset:1024
	ds_read_b128 v[136:139], v207 offset:2048
	ds_read_b128 v[140:143], v207 offset:3072
	s_cmp_eq_u32 s82, s27
	s_cselect_b32 s45, s77, s45
	s_cselect_b32 s44, s76, s44
	s_cselect_b32 s79, s1, s37
	s_cselect_b32 s78, s0, s33
	v_lshl_add_u64 v[176:177], s[42:43], 0, v[190:191]
	s_add_i32 m0, s85, 0xc000
	ds_read_b128 v[146:149], v217
	ds_read_b128 v[150:153], v217 offset:1024
	ds_read_b128 v[154:157], v217 offset:2048
	ds_read_b128 v[158:161], v217 offset:3072
	ds_read_b128 v[162:165], v217 offset:4096
	ds_read_b128 v[166:169], v217 offset:5120
	ds_read_b128 v[194:197], v217 offset:6144
	ds_read_b128 v[198:201], v217 offset:7168
	global_load_lds_dwordx4 v[176:177], off
	v_lshl_add_u64 v[176:177], s[42:43], 0, v[192:193]
	s_add_i32 m0, s85, 0xe000
	s_nop 0
	global_load_lds_dwordx4 v[176:177], off
	s_waitcnt lgkmcnt(8)
	s_barrier
	s_waitcnt lgkmcnt(0)
	v_mfma_f32_16x16x32_bf16 v[124:127], v[128:131], v[146:149], 0
	v_mfma_f32_16x16x32_bf16 v[120:123], v[136:139], v[146:149], 0
	v_mfma_f32_16x16x32_bf16 v[108:111], v[128:131], v[154:157], 0
	v_mfma_f32_16x16x32_bf16 v[104:107], v[136:139], v[154:157], 0
	v_mfma_f32_16x16x32_bf16 v[92:95], v[128:131], v[162:165], 0
	v_mfma_f32_16x16x32_bf16 v[88:91], v[136:139], v[162:165], 0
	v_mfma_f32_16x16x32_bf16 v[76:79], v[128:131], v[194:197], 0
	v_mfma_f32_16x16x32_bf16 v[72:75], v[136:139], v[194:197], 0
	v_mfma_f32_16x16x32_bf16 v[124:127], v[132:135], v[150:153], v[124:127]
	v_mfma_f32_16x16x32_bf16 v[120:123], v[140:143], v[150:153], v[120:123]
	v_mfma_f32_16x16x32_bf16 v[108:111], v[132:135], v[158:161], v[108:111]
	v_mfma_f32_16x16x32_bf16 v[104:107], v[140:143], v[158:161], v[104:107]
	v_mfma_f32_16x16x32_bf16 v[92:95], v[132:135], v[166:169], v[92:95]
	v_mfma_f32_16x16x32_bf16 v[88:91], v[140:143], v[166:169], v[88:91]
	v_mfma_f32_16x16x32_bf16 v[76:79], v[132:135], v[198:201], v[76:79]
	v_mfma_f32_16x16x32_bf16 v[72:75], v[140:143], v[198:201], v[72:75]
	s_barrier
	s_add_i32 s27, 0, 0x14000
	s_add_i32 s57, s57, s84
	ds_read_b128 v[202:205], v207 offset:16384
	ds_read_b128 v[218:221], v207 offset:17408
	ds_read_b128 v[222:225], v207 offset:18432
	ds_read_b128 v[228:231], v207 offset:19456
	v_lshl_add_u64 v[176:177], s[78:79], 0, v[144:145]
	s_mov_b32 m0, s57
	v_lshl_add_u64 v[232:233], s[78:79], 0, v[188:189]
	global_load_lds_dwordx4 v[176:177], off
	s_add_i32 m0, s57, 0x2000
	s_nop 0
	global_load_lds_dwordx4 v[232:233], off
	s_barrier
	s_waitcnt lgkmcnt(0)
	v_mfma_f32_16x16x32_bf16 v[116:119], v[202:205], v[146:149], 0
	v_mfma_f32_16x16x32_bf16 v[112:115], v[222:225], v[146:149], 0
	v_mfma_f32_16x16x32_bf16 v[100:103], v[202:205], v[154:157], 0
	v_mfma_f32_16x16x32_bf16 v[96:99], v[222:225], v[154:157], 0
	v_mfma_f32_16x16x32_bf16 v[84:87], v[202:205], v[162:165], 0
	v_mfma_f32_16x16x32_bf16 v[80:83], v[222:225], v[162:165], 0
	v_mfma_f32_16x16x32_bf16 v[68:71], v[202:205], v[194:197], 0
	v_mfma_f32_16x16x32_bf16 v[64:67], v[222:225], v[194:197], 0
	v_mfma_f32_16x16x32_bf16 v[116:119], v[218:221], v[150:153], v[116:119]
	v_mfma_f32_16x16x32_bf16 v[112:115], v[228:231], v[150:153], v[112:115]
	v_mfma_f32_16x16x32_bf16 v[100:103], v[218:221], v[158:161], v[100:103]
	v_mfma_f32_16x16x32_bf16 v[96:99], v[228:231], v[158:161], v[96:99]
	v_mfma_f32_16x16x32_bf16 v[84:87], v[218:221], v[166:169], v[84:87]
	v_mfma_f32_16x16x32_bf16 v[80:83], v[228:231], v[166:169], v[80:83]
	v_mfma_f32_16x16x32_bf16 v[68:71], v[218:221], v[198:201], v[68:71]
	v_mfma_f32_16x16x32_bf16 v[64:67], v[228:231], v[198:201], v[64:67]
	s_barrier
	s_mov_b32 m0, s85
	v_lshl_add_u64 v[234:235], s[44:45], 0, v[144:145]
	ds_read_b128 v[146:149], v217 offset:16384
	ds_read_b128 v[150:153], v217 offset:17408
	ds_read_b128 v[154:157], v217 offset:18432
	ds_read_b128 v[158:161], v217 offset:19456
	ds_read_b128 v[162:165], v217 offset:20480
	ds_read_b128 v[166:169], v217 offset:21504
	ds_read_b128 v[194:197], v217 offset:22528
	ds_read_b128 v[198:201], v217 offset:23552
	global_load_lds_dwordx4 v[234:235], off
	v_lshl_add_u64 v[236:237], s[44:45], 0, v[188:189]
	s_mov_b32 m0, s86
	s_nop 0
	global_load_lds_dwordx4 v[236:237], off
	s_barrier
	s_waitcnt lgkmcnt(0)
	v_mfma_f32_16x16x32_bf16 v[60:63], v[128:131], v[146:149], 0
	v_mfma_f32_16x16x32_bf16 v[56:59], v[136:139], v[146:149], 0
	v_mfma_f32_16x16x32_bf16 v[44:47], v[128:131], v[154:157], 0
	v_mfma_f32_16x16x32_bf16 v[40:43], v[136:139], v[154:157], 0
	v_mfma_f32_16x16x32_bf16 v[28:31], v[128:131], v[162:165], 0
	v_mfma_f32_16x16x32_bf16 v[24:27], v[136:139], v[162:165], 0
	v_mfma_f32_16x16x32_bf16 v[12:15], v[128:131], v[194:197], 0
	v_mfma_f32_16x16x32_bf16 v[8:11], v[136:139], v[194:197], 0
	v_mfma_f32_16x16x32_bf16 v[60:63], v[132:135], v[150:153], v[60:63]
	v_mfma_f32_16x16x32_bf16 v[56:59], v[140:143], v[150:153], v[56:59]
	v_mfma_f32_16x16x32_bf16 v[44:47], v[132:135], v[158:161], v[44:47]
	v_mfma_f32_16x16x32_bf16 v[40:43], v[140:143], v[158:161], v[40:43]
	v_mfma_f32_16x16x32_bf16 v[28:31], v[132:135], v[166:169], v[28:31]
	v_mfma_f32_16x16x32_bf16 v[24:27], v[140:143], v[166:169], v[24:27]
	v_mfma_f32_16x16x32_bf16 v[12:15], v[132:135], v[198:201], v[12:15]
	v_mfma_f32_16x16x32_bf16 v[8:11], v[140:143], v[198:201], v[8:11]
	s_barrier
	s_add_u32 s58, s78, s98
	s_addc_u32 s59, s79, 0
	s_add_i32 s27, s27, s84
	v_lshl_add_u64 v[238:239], s[58:59], 0, v[144:145]
	s_mov_b32 m0, s27
	v_lshl_add_u64 v[240:241], s[58:59], 0, v[188:189]
	global_load_lds_dwordx4 v[238:239], off
	s_add_i32 m0, s27, 0x2000
	s_nop 0
	global_load_lds_dwordx4 v[240:241], off
	s_waitcnt vmcnt(6)
	s_barrier
	v_mfma_f32_16x16x32_bf16 v[52:55], v[202:205], v[146:149], 0
	v_mfma_f32_16x16x32_bf16 v[48:51], v[222:225], v[146:149], 0
	v_mfma_f32_16x16x32_bf16 v[36:39], v[202:205], v[154:157], 0
	v_mfma_f32_16x16x32_bf16 v[32:35], v[222:225], v[154:157], 0
	v_mfma_f32_16x16x32_bf16 v[20:23], v[202:205], v[162:165], 0
	v_mfma_f32_16x16x32_bf16 v[16:19], v[222:225], v[162:165], 0
	v_mfma_f32_16x16x32_bf16 v[4:7], v[202:205], v[194:197], 0
	v_mfma_f32_16x16x32_bf16 v[0:3], v[222:225], v[194:197], 0
	v_mfma_f32_16x16x32_bf16 v[52:55], v[218:221], v[150:153], v[52:55]
	v_mfma_f32_16x16x32_bf16 v[48:51], v[228:231], v[150:153], v[48:51]
	v_mfma_f32_16x16x32_bf16 v[36:39], v[218:221], v[158:161], v[36:39]
	v_mfma_f32_16x16x32_bf16 v[32:35], v[228:231], v[158:161], v[32:35]
	v_mfma_f32_16x16x32_bf16 v[20:23], v[218:221], v[166:169], v[20:23]
	v_mfma_f32_16x16x32_bf16 v[16:19], v[228:231], v[166:169], v[16:19]
	v_mfma_f32_16x16x32_bf16 v[4:7], v[218:221], v[198:201], v[4:7]
	v_mfma_f32_16x16x32_bf16 v[0:3], v[228:231], v[198:201], v[0:3]
	s_barrier
	s_add_i32 s27, 0, 0x18000
	ds_read_b128 v[128:131], v207 offset:32768
	ds_read_b128 v[132:135], v207 offset:33792
	ds_read_b128 v[136:139], v207 offset:34816
	ds_read_b128 v[140:143], v207 offset:35840
	s_add_u32 s44, s44, s98
	s_addc_u32 s45, s45, 0
	s_mov_b32 m0, s87
	ds_read_b128 v[146:149], v217 offset:32768
	ds_read_b128 v[150:153], v217 offset:33792
	ds_read_b128 v[154:157], v217 offset:34816
	ds_read_b128 v[158:161], v217 offset:35840
	ds_read_b128 v[162:165], v217 offset:36864
	ds_read_b128 v[166:169], v217 offset:37888
	ds_read_b128 v[194:197], v217 offset:38912
	ds_read_b128 v[198:201], v217 offset:39936
	global_load_lds_dwordx4 v144, s[44:45]
	s_mov_b32 m0, s80
	s_nop 0
	global_load_lds_dwordx4 v188, s[44:45]
	s_waitcnt lgkmcnt(8)
	s_barrier
	s_waitcnt lgkmcnt(0)
	v_mfma_f32_16x16x32_bf16 v[124:127], v[128:131], v[146:149], v[124:127]
	v_mfma_f32_16x16x32_bf16 v[120:123], v[136:139], v[146:149], v[120:123]
	v_mfma_f32_16x16x32_bf16 v[108:111], v[128:131], v[154:157], v[108:111]
	v_mfma_f32_16x16x32_bf16 v[104:107], v[136:139], v[154:157], v[104:107]
	v_mfma_f32_16x16x32_bf16 v[92:95], v[128:131], v[162:165], v[92:95]
	v_mfma_f32_16x16x32_bf16 v[88:91], v[136:139], v[162:165], v[88:91]
	v_mfma_f32_16x16x32_bf16 v[76:79], v[128:131], v[194:197], v[76:79]
	v_mfma_f32_16x16x32_bf16 v[72:75], v[136:139], v[194:197], v[72:75]
	v_mfma_f32_16x16x32_bf16 v[124:127], v[132:135], v[150:153], v[124:127]
	v_mfma_f32_16x16x32_bf16 v[120:123], v[140:143], v[150:153], v[120:123]
	v_mfma_f32_16x16x32_bf16 v[108:111], v[132:135], v[158:161], v[108:111]
	v_mfma_f32_16x16x32_bf16 v[104:107], v[140:143], v[158:161], v[104:107]
	v_mfma_f32_16x16x32_bf16 v[92:95], v[132:135], v[166:169], v[92:95]
	v_mfma_f32_16x16x32_bf16 v[88:91], v[140:143], v[166:169], v[88:91]
	v_mfma_f32_16x16x32_bf16 v[76:79], v[132:135], v[198:201], v[76:79]
	v_mfma_f32_16x16x32_bf16 v[72:75], v[140:143], v[198:201], v[72:75]
	s_barrier
	s_add_i32 s44, 0, 0x1c000
	s_add_i32 s27, s27, s84
	v_lshl_add_u64 v[176:177], v[176:177], 0, s[18:19]
	s_mov_b32 m0, s27
	ds_read_b128 v[202:205], v207 offset:49152
	ds_read_b128 v[218:221], v207 offset:50176
	ds_read_b128 v[222:225], v207 offset:51200
	ds_read_b128 v[228:231], v207 offset:52224
	global_load_lds_dwordx4 v[176:177], off
	v_lshl_add_u64 v[176:177], v[232:233], 0, s[18:19]
	s_add_i32 m0, s27, 0x2000
	s_nop 0
	global_load_lds_dwordx4 v[176:177], off
	s_barrier
	s_waitcnt lgkmcnt(0)
	v_mfma_f32_16x16x32_bf16 v[116:119], v[202:205], v[146:149], v[116:119]
	v_mfma_f32_16x16x32_bf16 v[112:115], v[222:225], v[146:149], v[112:115]
	v_mfma_f32_16x16x32_bf16 v[100:103], v[202:205], v[154:157], v[100:103]
	v_mfma_f32_16x16x32_bf16 v[96:99], v[222:225], v[154:157], v[96:99]
	v_mfma_f32_16x16x32_bf16 v[84:87], v[202:205], v[162:165], v[84:87]
	v_mfma_f32_16x16x32_bf16 v[80:83], v[222:225], v[162:165], v[80:83]
	v_mfma_f32_16x16x32_bf16 v[68:71], v[202:205], v[194:197], v[68:71]
	v_mfma_f32_16x16x32_bf16 v[64:67], v[222:225], v[194:197], v[64:67]
	v_mfma_f32_16x16x32_bf16 v[116:119], v[218:221], v[150:153], v[116:119]
	v_mfma_f32_16x16x32_bf16 v[112:115], v[228:231], v[150:153], v[112:115]
	v_mfma_f32_16x16x32_bf16 v[100:103], v[218:221], v[158:161], v[100:103]
	v_mfma_f32_16x16x32_bf16 v[96:99], v[228:231], v[158:161], v[96:99]
	v_mfma_f32_16x16x32_bf16 v[84:87], v[218:221], v[166:169], v[84:87]
	v_mfma_f32_16x16x32_bf16 v[80:83], v[228:231], v[166:169], v[80:83]
	v_mfma_f32_16x16x32_bf16 v[68:71], v[218:221], v[198:201], v[68:71]
	v_mfma_f32_16x16x32_bf16 v[64:67], v[228:231], v[198:201], v[64:67]
	s_barrier
	s_mov_b32 m0, s30
	v_lshl_add_u64 v[176:177], v[234:235], 0, s[18:19]
	ds_read_b128 v[146:149], v217 offset:49152
	ds_read_b128 v[150:153], v217 offset:50176
	ds_read_b128 v[154:157], v217 offset:51200
	ds_read_b128 v[158:161], v217 offset:52224
	ds_read_b128 v[162:165], v217 offset:53248
	ds_read_b128 v[166:169], v217 offset:54272
	ds_read_b128 v[194:197], v217 offset:55296
	ds_read_b128 v[198:201], v217 offset:56320
	global_load_lds_dwordx4 v[176:177], off
	v_lshl_add_u64 v[176:177], v[236:237], 0, s[18:19]
	s_mov_b32 m0, s31
	s_nop 0
	global_load_lds_dwordx4 v[176:177], off
	s_barrier
	s_waitcnt lgkmcnt(0)
	v_mfma_f32_16x16x32_bf16 v[60:63], v[128:131], v[146:149], v[60:63]
	v_mfma_f32_16x16x32_bf16 v[56:59], v[136:139], v[146:149], v[56:59]
	v_mfma_f32_16x16x32_bf16 v[44:47], v[128:131], v[154:157], v[44:47]
	v_mfma_f32_16x16x32_bf16 v[40:43], v[136:139], v[154:157], v[40:43]
	v_mfma_f32_16x16x32_bf16 v[28:31], v[128:131], v[162:165], v[28:31]
	v_mfma_f32_16x16x32_bf16 v[24:27], v[136:139], v[162:165], v[24:27]
	v_mfma_f32_16x16x32_bf16 v[12:15], v[128:131], v[194:197], v[12:15]
	v_mfma_f32_16x16x32_bf16 v[8:11], v[136:139], v[194:197], v[8:11]
	v_mfma_f32_16x16x32_bf16 v[60:63], v[132:135], v[150:153], v[60:63]
	v_mfma_f32_16x16x32_bf16 v[56:59], v[140:143], v[150:153], v[56:59]
	v_mfma_f32_16x16x32_bf16 v[44:47], v[132:135], v[158:161], v[44:47]
	v_mfma_f32_16x16x32_bf16 v[40:43], v[140:143], v[158:161], v[40:43]
	v_mfma_f32_16x16x32_bf16 v[28:31], v[132:135], v[166:169], v[28:31]
	v_mfma_f32_16x16x32_bf16 v[24:27], v[140:143], v[166:169], v[24:27]
	v_mfma_f32_16x16x32_bf16 v[12:15], v[132:135], v[198:201], v[12:15]
	v_mfma_f32_16x16x32_bf16 v[8:11], v[140:143], v[198:201], v[8:11]
	s_barrier
	s_add_i32 s27, s44, s84
	v_lshl_add_u64 v[128:129], v[238:239], 0, s[18:19]
	s_mov_b32 m0, s27
	s_nop 0
	global_load_lds_dwordx4 v[128:129], off
	v_lshl_add_u64 v[128:129], v[240:241], 0, s[18:19]
	s_add_i32 m0, s27, 0x2000
	s_nop 0
	global_load_lds_dwordx4 v[128:129], off
	s_waitcnt vmcnt(6)
	s_barrier
	v_mfma_f32_16x16x32_bf16 v[52:55], v[202:205], v[146:149], v[52:55]
	v_mfma_f32_16x16x32_bf16 v[48:51], v[222:225], v[146:149], v[48:51]
	v_mfma_f32_16x16x32_bf16 v[36:39], v[202:205], v[154:157], v[36:39]
	v_mfma_f32_16x16x32_bf16 v[32:35], v[222:225], v[154:157], v[32:35]
	v_mfma_f32_16x16x32_bf16 v[20:23], v[202:205], v[162:165], v[20:23]
	v_mfma_f32_16x16x32_bf16 v[16:19], v[222:225], v[162:165], v[16:19]
	v_mfma_f32_16x16x32_bf16 v[4:7], v[202:205], v[194:197], v[4:7]
	v_mfma_f32_16x16x32_bf16 v[0:3], v[222:225], v[194:197], v[0:3]
	v_mfma_f32_16x16x32_bf16 v[52:55], v[218:221], v[150:153], v[52:55]
	v_mfma_f32_16x16x32_bf16 v[48:51], v[228:231], v[150:153], v[48:51]
	v_mfma_f32_16x16x32_bf16 v[36:39], v[218:221], v[158:161], v[36:39]
	v_mfma_f32_16x16x32_bf16 v[32:35], v[228:231], v[158:161], v[32:35]
	v_mfma_f32_16x16x32_bf16 v[20:23], v[218:221], v[166:169], v[20:23]
	v_mfma_f32_16x16x32_bf16 v[16:19], v[228:231], v[166:169], v[16:19]
	v_mfma_f32_16x16x32_bf16 v[4:7], v[218:221], v[198:201], v[4:7]
	v_mfma_f32_16x16x32_bf16 v[0:3], v[228:231], v[198:201], v[0:3]
	s_barrier
	s_add_u32 s42, s42, 0x100
	s_addc_u32 s43, s43, 0
	s_add_u32 s33, s33, 0x100
	s_addc_u32 s37, s37, 0
	s_cmp_ge_u32 s56, s34
	s_mov_b32 s27, s56
.LBB0_196:
	s_add_i32 s56, s27, 2
	s_add_u32 s44, s42, 0x80
	s_addc_u32 s45, s43, 0
	s_add_i32 s57, 0, 0x10000
	ds_read_b128 v[128:131], v207
	ds_read_b128 v[132:135], v207 offset:1024
	ds_read_b128 v[136:139], v207 offset:2048
	ds_read_b128 v[140:143], v207 offset:3072
	s_cmp_eq_u32 s82, s27
	s_cselect_b32 s45, s77, s45
	s_cselect_b32 s44, s76, s44
	s_cselect_b32 s79, s1, s37
	s_cselect_b32 s78, s0, s33
	v_lshl_add_u64 v[176:177], s[42:43], 0, v[190:191]
	s_add_i32 m0, s85, 0xc000
	ds_read_b128 v[146:149], v217
	ds_read_b128 v[150:153], v217 offset:1024
	ds_read_b128 v[154:157], v217 offset:2048
	ds_read_b128 v[158:161], v217 offset:3072
	ds_read_b128 v[162:165], v217 offset:4096
	ds_read_b128 v[166:169], v217 offset:5120
	ds_read_b128 v[194:197], v217 offset:6144
	ds_read_b128 v[198:201], v217 offset:7168
	global_load_lds_dwordx4 v[176:177], off
	v_lshl_add_u64 v[176:177], s[42:43], 0, v[192:193]
	s_add_i32 m0, s85, 0xe000
	s_nop 0
	global_load_lds_dwordx4 v[176:177], off
	s_waitcnt lgkmcnt(8)
	s_barrier
	s_waitcnt lgkmcnt(0)
	v_mfma_f32_16x16x32_bf16 v[124:127], v[128:131], v[146:149], v[124:127]
	v_mfma_f32_16x16x32_bf16 v[120:123], v[136:139], v[146:149], v[120:123]
	v_mfma_f32_16x16x32_bf16 v[108:111], v[128:131], v[154:157], v[108:111]
	v_mfma_f32_16x16x32_bf16 v[104:107], v[136:139], v[154:157], v[104:107]
	v_mfma_f32_16x16x32_bf16 v[92:95], v[128:131], v[162:165], v[92:95]
	v_mfma_f32_16x16x32_bf16 v[88:91], v[136:139], v[162:165], v[88:91]
	v_mfma_f32_16x16x32_bf16 v[76:79], v[128:131], v[194:197], v[76:79]
	v_mfma_f32_16x16x32_bf16 v[72:75], v[136:139], v[194:197], v[72:75]
	v_mfma_f32_16x16x32_bf16 v[124:127], v[132:135], v[150:153], v[124:127]
	v_mfma_f32_16x16x32_bf16 v[120:123], v[140:143], v[150:153], v[120:123]
	v_mfma_f32_16x16x32_bf16 v[108:111], v[132:135], v[158:161], v[108:111]
	v_mfma_f32_16x16x32_bf16 v[104:107], v[140:143], v[158:161], v[104:107]
	v_mfma_f32_16x16x32_bf16 v[92:95], v[132:135], v[166:169], v[92:95]
	v_mfma_f32_16x16x32_bf16 v[88:91], v[140:143], v[166:169], v[88:91]
	v_mfma_f32_16x16x32_bf16 v[76:79], v[132:135], v[198:201], v[76:79]
	v_mfma_f32_16x16x32_bf16 v[72:75], v[140:143], v[198:201], v[72:75]
	s_barrier
	s_add_i32 s27, 0, 0x14000
	s_add_i32 s57, s57, s84
	ds_read_b128 v[202:205], v207 offset:16384
	ds_read_b128 v[218:221], v207 offset:17408
	ds_read_b128 v[222:225], v207 offset:18432
	ds_read_b128 v[228:231], v207 offset:19456
	v_lshl_add_u64 v[176:177], s[78:79], 0, v[144:145]
	s_mov_b32 m0, s57
	v_lshl_add_u64 v[232:233], s[78:79], 0, v[188:189]
	global_load_lds_dwordx4 v[176:177], off
	s_add_i32 m0, s57, 0x2000
	s_nop 0
	global_load_lds_dwordx4 v[232:233], off
	s_barrier
	s_waitcnt lgkmcnt(0)
	v_mfma_f32_16x16x32_bf16 v[116:119], v[202:205], v[146:149], v[116:119]
	v_mfma_f32_16x16x32_bf16 v[112:115], v[222:225], v[146:149], v[112:115]
	v_mfma_f32_16x16x32_bf16 v[100:103], v[202:205], v[154:157], v[100:103]
	v_mfma_f32_16x16x32_bf16 v[96:99], v[222:225], v[154:157], v[96:99]
	v_mfma_f32_16x16x32_bf16 v[84:87], v[202:205], v[162:165], v[84:87]
	v_mfma_f32_16x16x32_bf16 v[80:83], v[222:225], v[162:165], v[80:83]
	v_mfma_f32_16x16x32_bf16 v[68:71], v[202:205], v[194:197], v[68:71]
	v_mfma_f32_16x16x32_bf16 v[64:67], v[222:225], v[194:197], v[64:67]
	v_mfma_f32_16x16x32_bf16 v[116:119], v[218:221], v[150:153], v[116:119]
	v_mfma_f32_16x16x32_bf16 v[112:115], v[228:231], v[150:153], v[112:115]
	v_mfma_f32_16x16x32_bf16 v[100:103], v[218:221], v[158:161], v[100:103]
	v_mfma_f32_16x16x32_bf16 v[96:99], v[228:231], v[158:161], v[96:99]
	v_mfma_f32_16x16x32_bf16 v[84:87], v[218:221], v[166:169], v[84:87]
	v_mfma_f32_16x16x32_bf16 v[80:83], v[228:231], v[166:169], v[80:83]
	v_mfma_f32_16x16x32_bf16 v[68:71], v[218:221], v[198:201], v[68:71]
	v_mfma_f32_16x16x32_bf16 v[64:67], v[228:231], v[198:201], v[64:67]
	s_barrier
	s_mov_b32 m0, s85
	v_lshl_add_u64 v[234:235], s[44:45], 0, v[144:145]
	ds_read_b128 v[146:149], v217 offset:16384
	ds_read_b128 v[150:153], v217 offset:17408
	ds_read_b128 v[154:157], v217 offset:18432
	ds_read_b128 v[158:161], v217 offset:19456
	ds_read_b128 v[162:165], v217 offset:20480
	ds_read_b128 v[166:169], v217 offset:21504
	ds_read_b128 v[194:197], v217 offset:22528
	ds_read_b128 v[198:201], v217 offset:23552
	global_load_lds_dwordx4 v[234:235], off
	v_lshl_add_u64 v[236:237], s[44:45], 0, v[188:189]
	s_mov_b32 m0, s86
	s_nop 0
	global_load_lds_dwordx4 v[236:237], off
	s_barrier
	s_waitcnt lgkmcnt(0)
	v_mfma_f32_16x16x32_bf16 v[60:63], v[128:131], v[146:149], v[60:63]
	v_mfma_f32_16x16x32_bf16 v[56:59], v[136:139], v[146:149], v[56:59]
	v_mfma_f32_16x16x32_bf16 v[44:47], v[128:131], v[154:157], v[44:47]
	v_mfma_f32_16x16x32_bf16 v[40:43], v[136:139], v[154:157], v[40:43]
	v_mfma_f32_16x16x32_bf16 v[28:31], v[128:131], v[162:165], v[28:31]
	v_mfma_f32_16x16x32_bf16 v[24:27], v[136:139], v[162:165], v[24:27]
	v_mfma_f32_16x16x32_bf16 v[12:15], v[128:131], v[194:197], v[12:15]
	v_mfma_f32_16x16x32_bf16 v[8:11], v[136:139], v[194:197], v[8:11]
	v_mfma_f32_16x16x32_bf16 v[60:63], v[132:135], v[150:153], v[60:63]
	v_mfma_f32_16x16x32_bf16 v[56:59], v[140:143], v[150:153], v[56:59]
	v_mfma_f32_16x16x32_bf16 v[44:47], v[132:135], v[158:161], v[44:47]
	v_mfma_f32_16x16x32_bf16 v[40:43], v[140:143], v[158:161], v[40:43]
	v_mfma_f32_16x16x32_bf16 v[28:31], v[132:135], v[166:169], v[28:31]
	v_mfma_f32_16x16x32_bf16 v[24:27], v[140:143], v[166:169], v[24:27]
	v_mfma_f32_16x16x32_bf16 v[12:15], v[132:135], v[198:201], v[12:15]
	v_mfma_f32_16x16x32_bf16 v[8:11], v[140:143], v[198:201], v[8:11]
	s_barrier
	s_add_u32 s58, s78, s98
	s_addc_u32 s59, s79, 0
	s_add_i32 s27, s27, s84
	v_lshl_add_u64 v[238:239], s[58:59], 0, v[144:145]
	s_mov_b32 m0, s27
	v_lshl_add_u64 v[240:241], s[58:59], 0, v[188:189]
	global_load_lds_dwordx4 v[238:239], off
	s_add_i32 m0, s27, 0x2000
	s_nop 0
	global_load_lds_dwordx4 v[240:241], off
	s_waitcnt vmcnt(6)
	s_barrier
	v_mfma_f32_16x16x32_bf16 v[52:55], v[202:205], v[146:149], v[52:55]
	v_mfma_f32_16x16x32_bf16 v[48:51], v[222:225], v[146:149], v[48:51]
	v_mfma_f32_16x16x32_bf16 v[36:39], v[202:205], v[154:157], v[36:39]
	v_mfma_f32_16x16x32_bf16 v[32:35], v[222:225], v[154:157], v[32:35]
	v_mfma_f32_16x16x32_bf16 v[20:23], v[202:205], v[162:165], v[20:23]
	v_mfma_f32_16x16x32_bf16 v[16:19], v[222:225], v[162:165], v[16:19]
	v_mfma_f32_16x16x32_bf16 v[4:7], v[202:205], v[194:197], v[4:7]
	v_mfma_f32_16x16x32_bf16 v[0:3], v[222:225], v[194:197], v[0:3]
	v_mfma_f32_16x16x32_bf16 v[52:55], v[218:221], v[150:153], v[52:55]
	v_mfma_f32_16x16x32_bf16 v[48:51], v[228:231], v[150:153], v[48:51]
	v_mfma_f32_16x16x32_bf16 v[36:39], v[218:221], v[158:161], v[36:39]
	v_mfma_f32_16x16x32_bf16 v[32:35], v[228:231], v[158:161], v[32:35]
	v_mfma_f32_16x16x32_bf16 v[20:23], v[218:221], v[166:169], v[20:23]
	v_mfma_f32_16x16x32_bf16 v[16:19], v[228:231], v[166:169], v[16:19]
	v_mfma_f32_16x16x32_bf16 v[4:7], v[218:221], v[198:201], v[4:7]
	v_mfma_f32_16x16x32_bf16 v[0:3], v[228:231], v[198:201], v[0:3]
	s_barrier
	s_add_i32 s27, 0, 0x18000
	ds_read_b128 v[128:131], v207 offset:32768
	ds_read_b128 v[132:135], v207 offset:33792
	ds_read_b128 v[136:139], v207 offset:34816
	ds_read_b128 v[140:143], v207 offset:35840
	s_add_u32 s44, s44, s98
	s_addc_u32 s45, s45, 0
	s_mov_b32 m0, s87
	ds_read_b128 v[146:149], v217 offset:32768
	ds_read_b128 v[150:153], v217 offset:33792
	ds_read_b128 v[154:157], v217 offset:34816
	ds_read_b128 v[158:161], v217 offset:35840
	ds_read_b128 v[162:165], v217 offset:36864
	ds_read_b128 v[166:169], v217 offset:37888
	ds_read_b128 v[194:197], v217 offset:38912
	ds_read_b128 v[198:201], v217 offset:39936
	global_load_lds_dwordx4 v144, s[44:45]
	s_mov_b32 m0, s80
	s_nop 0
	global_load_lds_dwordx4 v188, s[44:45]
	s_waitcnt lgkmcnt(8)
	s_barrier
	s_waitcnt lgkmcnt(0)
	v_mfma_f32_16x16x32_bf16 v[124:127], v[128:131], v[146:149], v[124:127]
	v_mfma_f32_16x16x32_bf16 v[120:123], v[136:139], v[146:149], v[120:123]
	v_mfma_f32_16x16x32_bf16 v[108:111], v[128:131], v[154:157], v[108:111]
	v_mfma_f32_16x16x32_bf16 v[104:107], v[136:139], v[154:157], v[104:107]
	v_mfma_f32_16x16x32_bf16 v[92:95], v[128:131], v[162:165], v[92:95]
	v_mfma_f32_16x16x32_bf16 v[88:91], v[136:139], v[162:165], v[88:91]
	v_mfma_f32_16x16x32_bf16 v[76:79], v[128:131], v[194:197], v[76:79]
	v_mfma_f32_16x16x32_bf16 v[72:75], v[136:139], v[194:197], v[72:75]
	v_mfma_f32_16x16x32_bf16 v[124:127], v[132:135], v[150:153], v[124:127]
	v_mfma_f32_16x16x32_bf16 v[120:123], v[140:143], v[150:153], v[120:123]
	v_mfma_f32_16x16x32_bf16 v[108:111], v[132:135], v[158:161], v[108:111]
	v_mfma_f32_16x16x32_bf16 v[104:107], v[140:143], v[158:161], v[104:107]
	v_mfma_f32_16x16x32_bf16 v[92:95], v[132:135], v[166:169], v[92:95]
	v_mfma_f32_16x16x32_bf16 v[88:91], v[140:143], v[166:169], v[88:91]
	v_mfma_f32_16x16x32_bf16 v[76:79], v[132:135], v[198:201], v[76:79]
	v_mfma_f32_16x16x32_bf16 v[72:75], v[140:143], v[198:201], v[72:75]
	s_barrier
	s_add_i32 s44, 0, 0x1c000
	s_add_i32 s27, s27, s84
	v_lshl_add_u64 v[176:177], v[176:177], 0, s[18:19]
	s_mov_b32 m0, s27
	ds_read_b128 v[202:205], v207 offset:49152
	ds_read_b128 v[218:221], v207 offset:50176
	ds_read_b128 v[222:225], v207 offset:51200
	ds_read_b128 v[228:231], v207 offset:52224
	global_load_lds_dwordx4 v[176:177], off
	v_lshl_add_u64 v[176:177], v[232:233], 0, s[18:19]
	s_add_i32 m0, s27, 0x2000
	s_nop 0
	global_load_lds_dwordx4 v[176:177], off
	s_barrier
	s_waitcnt lgkmcnt(0)
	v_mfma_f32_16x16x32_bf16 v[116:119], v[202:205], v[146:149], v[116:119]
	v_mfma_f32_16x16x32_bf16 v[112:115], v[222:225], v[146:149], v[112:115]
	v_mfma_f32_16x16x32_bf16 v[100:103], v[202:205], v[154:157], v[100:103]
	v_mfma_f32_16x16x32_bf16 v[96:99], v[222:225], v[154:157], v[96:99]
	v_mfma_f32_16x16x32_bf16 v[84:87], v[202:205], v[162:165], v[84:87]
	v_mfma_f32_16x16x32_bf16 v[80:83], v[222:225], v[162:165], v[80:83]
	v_mfma_f32_16x16x32_bf16 v[68:71], v[202:205], v[194:197], v[68:71]
	v_mfma_f32_16x16x32_bf16 v[64:67], v[222:225], v[194:197], v[64:67]
	v_mfma_f32_16x16x32_bf16 v[116:119], v[218:221], v[150:153], v[116:119]
	v_mfma_f32_16x16x32_bf16 v[112:115], v[228:231], v[150:153], v[112:115]
	v_mfma_f32_16x16x32_bf16 v[100:103], v[218:221], v[158:161], v[100:103]
	v_mfma_f32_16x16x32_bf16 v[96:99], v[228:231], v[158:161], v[96:99]
	v_mfma_f32_16x16x32_bf16 v[84:87], v[218:221], v[166:169], v[84:87]
	v_mfma_f32_16x16x32_bf16 v[80:83], v[228:231], v[166:169], v[80:83]
	v_mfma_f32_16x16x32_bf16 v[68:71], v[218:221], v[198:201], v[68:71]
	v_mfma_f32_16x16x32_bf16 v[64:67], v[228:231], v[198:201], v[64:67]
	s_barrier
	s_mov_b32 m0, s30
	v_lshl_add_u64 v[176:177], v[234:235], 0, s[18:19]
	ds_read_b128 v[146:149], v217 offset:49152
	ds_read_b128 v[150:153], v217 offset:50176
	ds_read_b128 v[154:157], v217 offset:51200
	ds_read_b128 v[158:161], v217 offset:52224
	ds_read_b128 v[162:165], v217 offset:53248
	ds_read_b128 v[166:169], v217 offset:54272
	ds_read_b128 v[194:197], v217 offset:55296
	ds_read_b128 v[198:201], v217 offset:56320
	global_load_lds_dwordx4 v[176:177], off
	v_lshl_add_u64 v[176:177], v[236:237], 0, s[18:19]
	s_mov_b32 m0, s31
	s_nop 0
	global_load_lds_dwordx4 v[176:177], off
	s_barrier
	s_waitcnt lgkmcnt(0)
	v_mfma_f32_16x16x32_bf16 v[60:63], v[128:131], v[146:149], v[60:63]
	v_mfma_f32_16x16x32_bf16 v[56:59], v[136:139], v[146:149], v[56:59]
	v_mfma_f32_16x16x32_bf16 v[44:47], v[128:131], v[154:157], v[44:47]
	v_mfma_f32_16x16x32_bf16 v[40:43], v[136:139], v[154:157], v[40:43]
	v_mfma_f32_16x16x32_bf16 v[28:31], v[128:131], v[162:165], v[28:31]
	v_mfma_f32_16x16x32_bf16 v[24:27], v[136:139], v[162:165], v[24:27]
	v_mfma_f32_16x16x32_bf16 v[12:15], v[128:131], v[194:197], v[12:15]
	v_mfma_f32_16x16x32_bf16 v[8:11], v[136:139], v[194:197], v[8:11]
	v_mfma_f32_16x16x32_bf16 v[60:63], v[132:135], v[150:153], v[60:63]
	v_mfma_f32_16x16x32_bf16 v[56:59], v[140:143], v[150:153], v[56:59]
	v_mfma_f32_16x16x32_bf16 v[44:47], v[132:135], v[158:161], v[44:47]
	v_mfma_f32_16x16x32_bf16 v[40:43], v[140:143], v[158:161], v[40:43]
	v_mfma_f32_16x16x32_bf16 v[28:31], v[132:135], v[166:169], v[28:31]
	v_mfma_f32_16x16x32_bf16 v[24:27], v[140:143], v[166:169], v[24:27]
	v_mfma_f32_16x16x32_bf16 v[12:15], v[132:135], v[198:201], v[12:15]
	v_mfma_f32_16x16x32_bf16 v[8:11], v[140:143], v[198:201], v[8:11]
	s_barrier
	s_add_i32 s27, s44, s84
	v_lshl_add_u64 v[128:129], v[238:239], 0, s[18:19]
	s_mov_b32 m0, s27
	s_nop 0
	global_load_lds_dwordx4 v[128:129], off
	v_lshl_add_u64 v[128:129], v[240:241], 0, s[18:19]
	s_add_i32 m0, s27, 0x2000
	s_nop 0
	global_load_lds_dwordx4 v[128:129], off
	s_waitcnt vmcnt(6)
	s_barrier
	v_mfma_f32_16x16x32_bf16 v[52:55], v[202:205], v[146:149], v[52:55]
	v_mfma_f32_16x16x32_bf16 v[48:51], v[222:225], v[146:149], v[48:51]
	v_mfma_f32_16x16x32_bf16 v[36:39], v[202:205], v[154:157], v[36:39]
	v_mfma_f32_16x16x32_bf16 v[32:35], v[222:225], v[154:157], v[32:35]
	v_mfma_f32_16x16x32_bf16 v[20:23], v[202:205], v[162:165], v[20:23]
	v_mfma_f32_16x16x32_bf16 v[16:19], v[222:225], v[162:165], v[16:19]
	v_mfma_f32_16x16x32_bf16 v[4:7], v[202:205], v[194:197], v[4:7]
	v_mfma_f32_16x16x32_bf16 v[0:3], v[222:225], v[194:197], v[0:3]
	v_mfma_f32_16x16x32_bf16 v[52:55], v[218:221], v[150:153], v[52:55]
	v_mfma_f32_16x16x32_bf16 v[48:51], v[228:231], v[150:153], v[48:51]
	v_mfma_f32_16x16x32_bf16 v[36:39], v[218:221], v[158:161], v[36:39]
	v_mfma_f32_16x16x32_bf16 v[32:35], v[228:231], v[158:161], v[32:35]
	v_mfma_f32_16x16x32_bf16 v[20:23], v[218:221], v[166:169], v[20:23]
	v_mfma_f32_16x16x32_bf16 v[16:19], v[228:231], v[166:169], v[16:19]
	v_mfma_f32_16x16x32_bf16 v[4:7], v[218:221], v[198:201], v[4:7]
	v_mfma_f32_16x16x32_bf16 v[0:3], v[228:231], v[198:201], v[0:3]
	s_barrier
	s_add_u32 s42, s42, 0x100
	s_addc_u32 s43, s43, 0
	s_add_u32 s33, s33, 0x100
	s_addc_u32 s37, s37, 0
	s_cmp_ge_u32 s56, s34
	s_mov_b32 s27, s56
	s_cbranch_scc0 .LBB0_196
	v_lshl_add_u32 v194, s11, 8, v206
	v_ashrrev_i32_e32 v195, 31, v194
	v_lshl_or_b32 v196, s10, 8, v216
	v_lshlrev_b64 v[128:129], 11, v[194:195]
	v_ashrrev_i32_e32 v197, 31, v196
	s_and_b64 vcc, exec, s[92:93]
	v_or_b32_e32 v198, 16, v194
	v_lshl_add_u64 v[200:201], s[54:55], 0, v[128:129]
	s_cbranch_vccz .LBB0_215
	v_lshlrev_b64 v[128:129], 12, v[194:195]
	v_lshl_add_u64 v[128:129], s[50:51], 0, v[128:129]
	v_lshlrev_b64 v[130:131], 2, v[196:197]
	v_lshl_add_u64 v[128:129], v[128:129], 0, v[130:131]
	global_load_dwordx4 v[146:149], v[128:129], off offset:16
	global_load_dwordx4 v[150:153], v[128:129], off
	global_load_dwordx4 v[154:157], v[128:129], off offset:528
	global_load_dwordx4 v[158:161], v[128:129], off offset:512
	v_ashrrev_i32_e32 v199, 31, v198
	v_lshlrev_b64 v[128:129], 12, v[198:199]
	v_lshl_add_u64 v[128:129], s[50:51], 0, v[128:129]
	v_lshl_add_u64 v[132:133], v[128:129], 0, v[130:131]
	global_load_dwordx4 v[136:139], v[132:133], off offset:16
	global_load_dwordx4 v[140:143], v[132:133], off
	global_load_dwordx4 v[128:131], v[132:133], off offset:528
	s_nop 0
	global_load_dwordx4 v[132:135], v[132:133], off offset:512
	v_lshl_add_u64 v[166:167], v[196:197], 1, v[200:201]
	s_waitcnt vmcnt(0)
	v_pk_add_f32 v[164:165], v[120:121], v[146:147]
	v_pk_add_f32 v[152:153], v[126:127], v[152:153]
	v_pk_add_f32 v[150:151], v[124:125], v[150:151]
	v_pk_add_f32 v[162:163], v[122:123], v[148:149]
	v_cvt_pk_bf16_f32 v146, v150, v151
	v_cvt_pk_bf16_f32 v147, v152, v153
	v_cvt_pk_bf16_f32 v148, v164, v165
	v_pk_add_f32 v[156:157], v[114:115], v[156:157]
	v_cvt_pk_bf16_f32 v149, v162, v163
	global_store_dwordx4 v[166:167], v[146:149], off
	v_pk_add_f32 v[154:155], v[112:113], v[154:155]
	s_nop 0
	v_mul_f32_e32 v146, v151, v151
	v_mul_f32_e32 v147, v153, v153
	v_fmac_f32_e32 v146, v150, v150
	v_fmac_f32_e32 v147, v152, v152
	v_add_f32_e32 v146, v146, v147
	v_mul_f32_e32 v147, v165, v165
	v_mul_f32_e32 v148, v163, v163
	v_fmac_f32_e32 v147, v164, v164
	v_fmac_f32_e32 v148, v162, v162
	v_add_f32_e32 v147, v147, v148
	v_add_f32_e32 v162, v146, v147
	v_pk_add_f32 v[150:151], v[118:119], v[160:161]
	v_pk_add_f32 v[152:153], v[116:117], v[158:159]
	s_nop 0
	v_cvt_pk_bf16_f32 v146, v152, v153
	v_cvt_pk_bf16_f32 v147, v150, v151
	v_cvt_pk_bf16_f32 v148, v154, v155
	v_cvt_pk_bf16_f32 v149, v156, v157
	global_store_dwordx4 v[166:167], v[146:149], off offset:256
	s_nop 1
	v_mul_f32_e32 v146, v153, v153
	v_mul_f32_e32 v147, v151, v151
	v_fmac_f32_e32 v146, v152, v152
	v_fmac_f32_e32 v147, v150, v150
	v_add_f32_e32 v146, v146, v147
	v_mul_f32_e32 v147, v155, v155
	v_mul_f32_e32 v148, v157, v157
	v_fmac_f32_e32 v147, v154, v154
	v_fmac_f32_e32 v148, v156, v156
	v_add_f32_e32 v147, v147, v148
	v_and_b32_e32 v148, 64, v214
	v_add_f32_e32 v146, v146, v147
	v_xor_b32_e32 v147, 16, v214
	v_add_u32_e32 v148, 64, v148
	v_cmp_lt_i32_e32 vcc, v147, v148
	v_add_f32_e32 v146, v162, v146
	s_nop 0
	v_cndmask_b32_e32 v147, v214, v147, vcc
	v_lshlrev_b32_e32 v218, 2, v147
	ds_bpermute_b32 v147, v218, v146
	s_waitcnt lgkmcnt(0)
	v_add_f32_e32 v146, v146, v147
	v_xor_b32_e32 v147, 32, v214
	v_cmp_lt_i32_e32 vcc, v147, v148
	s_nop 1
	v_cndmask_b32_e32 v147, v214, v147, vcc
	v_lshlrev_b32_e32 v219, 2, v147
	ds_bpermute_b32 v147, v219, v146
	s_and_saveexec_b64 s[42:43], s[38:39]
	s_cbranch_execz .LBB0_200
	s_waitcnt lgkmcnt(0)
	v_add_f32_e32 v146, v146, v147
	v_fma_f32 v146, v146, s91, 0.5
	v_trunc_f32_e32 v146, v146
	v_mul_f32_e32 v147, 0x2f800000, v146
	v_floor_f32_e32 v147, v147
	v_fmac_f32_e32 v146, 0xcf800000, v147
	v_cvt_u32_f32_e32 v146, v146
	v_cvt_u32_f32_e32 v147, v147
	v_lshl_add_u64 v[148:149], v[194:195], 3, s[52:53]
	global_atomic_add_x2 v[148:149], v[146:147], off

.LBB0_321:
	v_readlane_b32 s1, v252, 32
	s_add_u32 s1, s1, s27
	v_readlane_b32 s8, v252, 33
	s_addc_u32 s10, s8, s10
	v_writelane_b32 v254, s36, 58
	s_lshl_b64 s[30:31], s[36:37], 22
	s_sub_u32 s27, 0, s30
	v_writelane_b32 v254, s37, 59
	s_subb_u32 s33, 0, s31
	s_add_u32 s96, s1, s27
	v_readlane_b32 s8, v254, 52
	s_addc_u32 s97, s10, s33
	s_lshl_b32 s30, s8, 6
	s_and_b32 s1, s25, 3
	s_add_i32 m0, s83, 0x18000
	v_lshl_add_u64 v[6:7], v[6:7], 0, s[18:19]
	s_ashr_i32 s31, s30, 31
	s_lshl_b32 s25, s11, 13
	s_lshl_b32 s36, s1, 12
	s_waitcnt vmcnt(4)
	s_barrier
	global_load_lds_dwordx4 v[6:7], off
	v_lshl_add_u64 v[4:5], v[4:5], 0, s[18:19]
	s_add_i32 m0, s83, 0x1a000
	s_add_i32 s87, s83, 0x8000
	s_add_i32 s79, s83, 0xa000
	global_load_lds_dwordx4 v[4:5], off
	v_lshl_add_u64 v[2:3], v[2:3], 0, s[18:19]
	s_mov_b32 m0, s87
	s_add_u32 s34, s72, 0x40080
	global_load_lds_dwordx4 v[2:3], off
	v_lshl_add_u64 v[0:1], v[0:1], 0, s[18:19]
	s_mov_b32 m0, s79
	s_addc_u32 s35, s73, 0
	global_load_lds_dwordx4 v[0:1], off
	s_add_i32 m0, s83, 0x1c000
	v_lshl_add_u64 v[0:1], s[34:35], 0, v[148:149]
	global_load_lds_dwordx4 v[0:1], off
	v_lshl_add_u64 v[0:1], s[34:35], 0, v[146:147]
	s_add_i32 m0, s83, 0x1e000
	v_readlane_b32 s9, v254, 53
	global_load_lds_dwordx4 v[0:1], off
	v_lshrrev_b32_e32 v0, 1, v9
	v_and_b32_e32 v0, 24, v0
	v_and_b32_e32 v1, 15, v9
	v_lshlrev_b32_e32 v2, 1, v0
	v_lshl_or_b32 v151, s11, 6, v1
	v_lshl_or_b32 v1, v1, 6, v2
	v_lshlrev_b32_e32 v2, 2, v9
	v_and_b32_e32 v2, 32, v2
	v_bitop3_b32 v3, v1, s25, v2 bitop3:0xde
	v_bitop3_b32 v216, v1, s36, v2 bitop3:0xde
	v_add_u32_e32 v216, 0x10000, v216
	v_lshlrev_b32_e32 v1, 14, v12
	v_and_b32_e32 v1, 0xffff8000, v1
	v_lshl_or_b32 v150, s1, 6, v0
	v_writelane_b32 v254, s22, 60
	s_add_u32 s1, s22, s27
	v_lshl_add_u32 v1, v13, 11, v1
	v_and_b32_e32 v2, 1, v12
	v_writelane_b32 v254, s1, 52
	v_lshl_or_b32 v1, v2, 6, v1
	v_readlane_b32 s1, v254, 54
	v_lshl_add_u32 v152, v14, 1, v1
	v_lshlrev_b32_e32 v1, 14, v8
	s_addc_u32 s1, s1, s33
	v_and_b32_e32 v1, 0xffff8000, v1
	s_waitcnt vmcnt(6)
	v_writelane_b32 v254, s1, 61
	v_lshl_add_u32 v1, v10, 11, v1
	v_and_b32_e32 v2, 1, v8
	s_lshl_b64 s[8:9], s[30:31], 2
	v_lshl_or_b32 v1, v2, 6, v1
	v_writelane_b32 v254, s8, 62
	s_sext_i32_i8 s10, s38
	v_mov_b32_e32 v153, v145
	v_lshl_add_u32 v154, v11, 1, v1
	v_mov_b32_e32 v155, v145
	s_mov_b32 s22, 0
	v_add_u32_e32 v217, 0, v3
	v_writelane_b32 v254, s9, 63
	v_lshlrev_b32_e32 v218, 2, v0
	s_barrier
	v_readfirstlane_b32 s101, v208
	s_nop 3
	s_lshr_b32 s101, s101, 8
	s_cmp_eq_u32 s101, 0
	s_cbranch_scc1 .Lprio_a1_done
	s_setprio 1

.LBB0_325:
	s_ashr_i32 s93, s92, 31
	s_lshl_b64 s[30:31], s[92:93], 19
	s_add_u32 s94, s54, s30
	v_cmp_lt_i64_e32 vcc, s[50:51], v[186:187]
	s_addc_u32 s95, s55, s31
	s_and_b64 s[30:31], vcc, exec
	s_cselect_b32 s1, s95, s53
	s_cselect_b32 s11, s94, s52
	s_ashr_i32 s9, s8, 31
	s_lshl_b64 s[30:31], s[8:9], 19
	s_add_u32 s28, s80, s30
	s_addc_u32 s29, s78, s31
	s_and_b64 s[30:31], vcc, exec
	s_cselect_b32 s25, s29, s73
	s_cselect_b32 s30, s28, s72
	s_add_u32 s52, s52, 0x40080
	s_addc_u32 s53, s53, 0
	s_add_u32 s31, s72, 0x100
	s_addc_u32 s33, s73, 0
	s_mov_b32 s34, -2
	s_add_u32 s27, s52, 0xfffc0080
	s_addc_u32 s35, s53, -1
	s_add_i32 s36, 0, 0x10000
	ds_read_b128 v[128:131], v216
	ds_read_b128 v[132:135], v216 offset:1024
	ds_read_b128 v[136:139], v216 offset:2048
	ds_read_b128 v[140:143], v216 offset:3072
	s_cmp_eq_u32 s34, 12
	s_cselect_b32 s75, s1, s35
	s_cselect_b32 s74, s11, s27
	s_cselect_b32 s73, s25, s33
	s_cselect_b32 s72, s30, s31
	s_add_i32 m0, s83, 0xc000
	ds_read_b128 v[156:159], v217
	ds_read_b128 v[160:163], v217 offset:1024
	ds_read_b128 v[164:167], v217 offset:2048
	ds_read_b128 v[188:191], v217 offset:3072
	ds_read_b128 v[192:195], v217 offset:4096
	ds_read_b128 v[196:199], v217 offset:5120
	ds_read_b128 v[200:203], v217 offset:6144
	ds_read_b128 v[204:207], v217 offset:7168
	global_load_lds_dwordx4 v152, s[52:53]
	s_add_i32 m0, s83, 0xe000
	s_nop 0
	global_load_lds_dwordx4 v154, s[52:53]
	s_waitcnt lgkmcnt(8)
	s_barrier
	s_waitcnt lgkmcnt(0)
	v_mfma_f32_16x16x32_bf16 v[124:127], v[128:131], v[156:159], 0
	v_mfma_f32_16x16x32_bf16 v[120:123], v[136:139], v[156:159], 0
	v_mfma_f32_16x16x32_bf16 v[108:111], v[128:131], v[164:167], 0
	v_mfma_f32_16x16x32_bf16 v[104:107], v[136:139], v[164:167], 0
	v_mfma_f32_16x16x32_bf16 v[92:95], v[128:131], v[192:195], 0
	v_mfma_f32_16x16x32_bf16 v[88:91], v[136:139], v[192:195], 0
	v_mfma_f32_16x16x32_bf16 v[76:79], v[128:131], v[200:203], 0
	v_mfma_f32_16x16x32_bf16 v[72:75], v[136:139], v[200:203], 0
	v_mfma_f32_16x16x32_bf16 v[124:127], v[132:135], v[160:163], v[124:127]
	v_mfma_f32_16x16x32_bf16 v[120:123], v[140:143], v[160:163], v[120:123]
	v_mfma_f32_16x16x32_bf16 v[108:111], v[132:135], v[188:191], v[108:111]
	v_mfma_f32_16x16x32_bf16 v[104:107], v[140:143], v[188:191], v[104:107]
	v_mfma_f32_16x16x32_bf16 v[92:95], v[132:135], v[196:199], v[92:95]
	v_mfma_f32_16x16x32_bf16 v[88:91], v[140:143], v[196:199], v[88:91]
	v_mfma_f32_16x16x32_bf16 v[76:79], v[132:135], v[204:207], v[76:79]
	v_mfma_f32_16x16x32_bf16 v[72:75], v[140:143], v[204:207], v[72:75]
	s_barrier
	s_add_i32 s27, 0, 0x14000
	s_add_i32 s35, s36, s81
	s_mov_b32 m0, s35
	ds_read_b128 v[220:223], v216 offset:16384
	ds_read_b128 v[228:231], v216 offset:17408
	ds_read_b128 v[232:235], v216 offset:18432
	ds_read_b128 v[236:239], v216 offset:19456
	global_load_lds_dwordx4 v148, s[72:73]
	s_add_i32 m0, s35, 0x2000
	s_nop 0
	global_load_lds_dwordx4 v146, s[72:73]
	s_barrier
	s_waitcnt lgkmcnt(0)
	v_mfma_f32_16x16x32_bf16 v[116:119], v[220:223], v[156:159], 0
	v_mfma_f32_16x16x32_bf16 v[112:115], v[232:235], v[156:159], 0
	v_mfma_f32_16x16x32_bf16 v[100:103], v[220:223], v[164:167], 0
	v_mfma_f32_16x16x32_bf16 v[96:99], v[232:235], v[164:167], 0
	v_mfma_f32_16x16x32_bf16 v[84:87], v[220:223], v[192:195], 0
	v_mfma_f32_16x16x32_bf16 v[80:83], v[232:235], v[192:195], 0
	v_mfma_f32_16x16x32_bf16 v[68:71], v[220:223], v[200:203], 0
	v_mfma_f32_16x16x32_bf16 v[64:67], v[232:235], v[200:203], 0
	v_mfma_f32_16x16x32_bf16 v[116:119], v[228:231], v[160:163], v[116:119]
	v_mfma_f32_16x16x32_bf16 v[112:115], v[236:239], v[160:163], v[112:115]
	v_mfma_f32_16x16x32_bf16 v[100:103], v[228:231], v[188:191], v[100:103]
	v_mfma_f32_16x16x32_bf16 v[96:99], v[236:239], v[188:191], v[96:99]
	v_mfma_f32_16x16x32_bf16 v[84:87], v[228:231], v[196:199], v[84:87]
	v_mfma_f32_16x16x32_bf16 v[80:83], v[236:239], v[196:199], v[80:83]
	v_mfma_f32_16x16x32_bf16 v[68:71], v[228:231], v[204:207], v[68:71]
	v_mfma_f32_16x16x32_bf16 v[64:67], v[236:239], v[204:207], v[64:67]
	s_barrier
	s_mov_b32 m0, s83
	ds_read_b128 v[156:159], v217 offset:16384
	ds_read_b128 v[160:163], v217 offset:17408
	ds_read_b128 v[164:167], v217 offset:18432
	ds_read_b128 v[188:191], v217 offset:19456
	ds_read_b128 v[192:195], v217 offset:20480
	ds_read_b128 v[196:199], v217 offset:21504
	ds_read_b128 v[200:203], v217 offset:22528
	ds_read_b128 v[204:207], v217 offset:23552
	global_load_lds_dwordx4 v148, s[74:75]
	s_mov_b32 m0, s84
	s_nop 0
	global_load_lds_dwordx4 v146, s[74:75]
	s_barrier
	s_waitcnt lgkmcnt(0)
	v_mfma_f32_16x16x32_bf16 v[60:63], v[128:131], v[156:159], 0
	v_mfma_f32_16x16x32_bf16 v[56:59], v[136:139], v[156:159], 0
	v_mfma_f32_16x16x32_bf16 v[44:47], v[128:131], v[164:167], 0
	v_mfma_f32_16x16x32_bf16 v[40:43], v[136:139], v[164:167], 0
	v_mfma_f32_16x16x32_bf16 v[28:31], v[128:131], v[192:195], 0
	v_mfma_f32_16x16x32_bf16 v[24:27], v[136:139], v[192:195], 0
	v_mfma_f32_16x16x32_bf16 v[12:15], v[128:131], v[200:203], 0
	v_mfma_f32_16x16x32_bf16 v[8:11], v[136:139], v[200:203], 0
	v_mfma_f32_16x16x32_bf16 v[60:63], v[132:135], v[160:163], v[60:63]
	v_mfma_f32_16x16x32_bf16 v[56:59], v[140:143], v[160:163], v[56:59]
	v_mfma_f32_16x16x32_bf16 v[44:47], v[132:135], v[188:191], v[44:47]
	v_mfma_f32_16x16x32_bf16 v[40:43], v[140:143], v[188:191], v[40:43]
	v_mfma_f32_16x16x32_bf16 v[28:31], v[132:135], v[196:199], v[28:31]
	v_mfma_f32_16x16x32_bf16 v[24:27], v[140:143], v[196:199], v[24:27]
	v_mfma_f32_16x16x32_bf16 v[12:15], v[132:135], v[204:207], v[12:15]
	v_mfma_f32_16x16x32_bf16 v[8:11], v[140:143], v[204:207], v[8:11]
	s_barrier
	s_add_u32 s36, s72, 0x40000
	s_addc_u32 s37, s73, 0
	s_add_i32 s27, s27, s81
	s_mov_b32 m0, s27
	s_nop 0
	global_load_lds_dwordx4 v148, s[36:37]
	s_add_i32 m0, s27, 0x2000
	s_nop 0
	global_load_lds_dwordx4 v146, s[36:37]
	s_waitcnt vmcnt(6)
	s_barrier
	v_mfma_f32_16x16x32_bf16 v[52:55], v[220:223], v[156:159], 0
	v_mfma_f32_16x16x32_bf16 v[48:51], v[232:235], v[156:159], 0
	v_mfma_f32_16x16x32_bf16 v[36:39], v[220:223], v[164:167], 0
	v_mfma_f32_16x16x32_bf16 v[32:35], v[232:235], v[164:167], 0
	v_mfma_f32_16x16x32_bf16 v[20:23], v[220:223], v[192:195], 0
	v_mfma_f32_16x16x32_bf16 v[16:19], v[232:235], v[192:195], 0
	v_mfma_f32_16x16x32_bf16 v[4:7], v[220:223], v[200:203], 0
	v_mfma_f32_16x16x32_bf16 v[0:3], v[232:235], v[200:203], 0
	v_mfma_f32_16x16x32_bf16 v[52:55], v[228:231], v[160:163], v[52:55]
	v_mfma_f32_16x16x32_bf16 v[48:51], v[236:239], v[160:163], v[48:51]
	v_mfma_f32_16x16x32_bf16 v[36:39], v[228:231], v[188:191], v[36:39]
	v_mfma_f32_16x16x32_bf16 v[32:35], v[236:239], v[188:191], v[32:35]
	v_mfma_f32_16x16x32_bf16 v[20:23], v[228:231], v[196:199], v[20:23]
	v_mfma_f32_16x16x32_bf16 v[16:19], v[236:239], v[196:199], v[16:19]
	v_mfma_f32_16x16x32_bf16 v[4:7], v[228:231], v[204:207], v[4:7]
	v_mfma_f32_16x16x32_bf16 v[0:3], v[236:239], v[204:207], v[0:3]
	s_barrier
	s_add_i32 s27, 0, 0x18000
	ds_read_b128 v[128:131], v216 offset:32768
	ds_read_b128 v[132:135], v216 offset:33792
	ds_read_b128 v[136:139], v216 offset:34816
	ds_read_b128 v[140:143], v216 offset:35840
	s_add_u32 s36, s74, 0x40000
	s_addc_u32 s37, s75, 0
	s_mov_b32 m0, s85
	ds_read_b128 v[156:159], v217 offset:32768
	ds_read_b128 v[160:163], v217 offset:33792
	ds_read_b128 v[164:167], v217 offset:34816
	ds_read_b128 v[188:191], v217 offset:35840
	ds_read_b128 v[192:195], v217 offset:36864
	ds_read_b128 v[196:199], v217 offset:37888
	ds_read_b128 v[200:203], v217 offset:38912
	ds_read_b128 v[204:207], v217 offset:39936
	global_load_lds_dwordx4 v148, s[36:37]
	s_mov_b32 m0, s86
	s_nop 0
	global_load_lds_dwordx4 v146, s[36:37]
	s_waitcnt lgkmcnt(8)
	s_barrier
	s_waitcnt lgkmcnt(0)
	v_mfma_f32_16x16x32_bf16 v[124:127], v[128:131], v[156:159], v[124:127]
	v_mfma_f32_16x16x32_bf16 v[120:123], v[136:139], v[156:159], v[120:123]
	v_mfma_f32_16x16x32_bf16 v[108:111], v[128:131], v[164:167], v[108:111]
	v_mfma_f32_16x16x32_bf16 v[104:107], v[136:139], v[164:167], v[104:107]
	v_mfma_f32_16x16x32_bf16 v[92:95], v[128:131], v[192:195], v[92:95]
	v_mfma_f32_16x16x32_bf16 v[88:91], v[136:139], v[192:195], v[88:91]
	v_mfma_f32_16x16x32_bf16 v[76:79], v[128:131], v[200:203], v[76:79]
	v_mfma_f32_16x16x32_bf16 v[72:75], v[136:139], v[200:203], v[72:75]
	v_mfma_f32_16x16x32_bf16 v[124:127], v[132:135], v[160:163], v[124:127]
	v_mfma_f32_16x16x32_bf16 v[120:123], v[140:143], v[160:163], v[120:123]
	v_mfma_f32_16x16x32_bf16 v[108:111], v[132:135], v[188:191], v[108:111]
	v_mfma_f32_16x16x32_bf16 v[104:107], v[140:143], v[188:191], v[104:107]
	v_mfma_f32_16x16x32_bf16 v[92:95], v[132:135], v[196:199], v[92:95]
	v_mfma_f32_16x16x32_bf16 v[88:91], v[140:143], v[196:199], v[88:91]
	v_mfma_f32_16x16x32_bf16 v[76:79], v[132:135], v[204:207], v[76:79]
	v_mfma_f32_16x16x32_bf16 v[72:75], v[140:143], v[204:207], v[72:75]
	s_barrier
	s_add_i32 s35, 0, 0x1c000
	s_add_i32 s27, s27, s81
	s_add_u32 s36, s72, s18
	s_addc_u32 s37, s73, s19
	s_mov_b32 m0, s27
	ds_read_b128 v[220:223], v216 offset:49152
	ds_read_b128 v[228:231], v216 offset:50176
	ds_read_b128 v[232:235], v216 offset:51200
	ds_read_b128 v[236:239], v216 offset:52224
	global_load_lds_dwordx4 v148, s[36:37]
	s_add_u32 s36, s72, s18
	s_addc_u32 s37, s73, s19
	s_add_i32 m0, s27, 0x2000
	s_nop 0
	global_load_lds_dwordx4 v146, s[36:37]
	s_barrier
	s_waitcnt lgkmcnt(0)
	v_mfma_f32_16x16x32_bf16 v[116:119], v[220:223], v[156:159], v[116:119]
	v_mfma_f32_16x16x32_bf16 v[112:115], v[232:235], v[156:159], v[112:115]
	v_mfma_f32_16x16x32_bf16 v[100:103], v[220:223], v[164:167], v[100:103]
	v_mfma_f32_16x16x32_bf16 v[96:99], v[232:235], v[164:167], v[96:99]
	v_mfma_f32_16x16x32_bf16 v[84:87], v[220:223], v[192:195], v[84:87]
	v_mfma_f32_16x16x32_bf16 v[80:83], v[232:235], v[192:195], v[80:83]
	v_mfma_f32_16x16x32_bf16 v[68:71], v[220:223], v[200:203], v[68:71]
	v_mfma_f32_16x16x32_bf16 v[64:67], v[232:235], v[200:203], v[64:67]
	v_mfma_f32_16x16x32_bf16 v[116:119], v[228:231], v[160:163], v[116:119]
	v_mfma_f32_16x16x32_bf16 v[112:115], v[236:239], v[160:163], v[112:115]
	v_mfma_f32_16x16x32_bf16 v[100:103], v[228:231], v[188:191], v[100:103]
	v_mfma_f32_16x16x32_bf16 v[96:99], v[236:239], v[188:191], v[96:99]
	v_mfma_f32_16x16x32_bf16 v[84:87], v[228:231], v[196:199], v[84:87]
	v_mfma_f32_16x16x32_bf16 v[80:83], v[236:239], v[196:199], v[80:83]
	v_mfma_f32_16x16x32_bf16 v[68:71], v[228:231], v[204:207], v[68:71]
	v_mfma_f32_16x16x32_bf16 v[64:67], v[236:239], v[204:207], v[64:67]
	s_barrier
	s_mov_b32 m0, s87
	s_add_u32 s36, s74, s18
	s_addc_u32 s37, s75, s19
	ds_read_b128 v[156:159], v217 offset:49152
	ds_read_b128 v[160:163], v217 offset:50176
	ds_read_b128 v[164:167], v217 offset:51200
	ds_read_b128 v[188:191], v217 offset:52224
	ds_read_b128 v[192:195], v217 offset:53248
	ds_read_b128 v[196:199], v217 offset:54272
	ds_read_b128 v[200:203], v217 offset:55296
	ds_read_b128 v[204:207], v217 offset:56320
	global_load_lds_dwordx4 v148, s[36:37]
	s_add_u32 s36, s74, s18
	s_addc_u32 s37, s75, s19
	s_mov_b32 m0, s79
	s_nop 0
	global_load_lds_dwordx4 v146, s[36:37]
	s_barrier
	s_waitcnt lgkmcnt(0)
	v_mfma_f32_16x16x32_bf16 v[60:63], v[128:131], v[156:159], v[60:63]
	v_mfma_f32_16x16x32_bf16 v[56:59], v[136:139], v[156:159], v[56:59]
	v_mfma_f32_16x16x32_bf16 v[44:47], v[128:131], v[164:167], v[44:47]
	v_mfma_f32_16x16x32_bf16 v[40:43], v[136:139], v[164:167], v[40:43]
	v_mfma_f32_16x16x32_bf16 v[28:31], v[128:131], v[192:195], v[28:31]
	v_mfma_f32_16x16x32_bf16 v[24:27], v[136:139], v[192:195], v[24:27]
	v_mfma_f32_16x16x32_bf16 v[12:15], v[128:131], v[200:203], v[12:15]
	v_mfma_f32_16x16x32_bf16 v[8:11], v[136:139], v[200:203], v[8:11]
	v_mfma_f32_16x16x32_bf16 v[60:63], v[132:135], v[160:163], v[60:63]
	v_mfma_f32_16x16x32_bf16 v[56:59], v[140:143], v[160:163], v[56:59]
	v_mfma_f32_16x16x32_bf16 v[44:47], v[132:135], v[188:191], v[44:47]
	v_mfma_f32_16x16x32_bf16 v[40:43], v[140:143], v[188:191], v[40:43]
	v_mfma_f32_16x16x32_bf16 v[28:31], v[132:135], v[196:199], v[28:31]
	v_mfma_f32_16x16x32_bf16 v[24:27], v[140:143], v[196:199], v[24:27]
	v_mfma_f32_16x16x32_bf16 v[12:15], v[132:135], v[204:207], v[12:15]
	v_mfma_f32_16x16x32_bf16 v[8:11], v[140:143], v[204:207], v[8:11]
	s_barrier
	s_add_u32 s36, s72, 0x40080
	s_addc_u32 s37, s73, 0
	s_add_i32 s27, s35, s81
	s_mov_b32 m0, s27
	s_nop 0
	global_load_lds_dwordx4 v148, s[36:37]
	s_add_i32 m0, s27, 0x2000
	s_nop 0
	global_load_lds_dwordx4 v146, s[36:37]
	s_waitcnt vmcnt(6)
	s_barrier
	v_mfma_f32_16x16x32_bf16 v[52:55], v[220:223], v[156:159], v[52:55]
	v_mfma_f32_16x16x32_bf16 v[48:51], v[232:235], v[156:159], v[48:51]
	v_mfma_f32_16x16x32_bf16 v[36:39], v[220:223], v[164:167], v[36:39]
	v_mfma_f32_16x16x32_bf16 v[32:35], v[232:235], v[164:167], v[32:35]
	v_mfma_f32_16x16x32_bf16 v[20:23], v[220:223], v[192:195], v[20:23]
	v_mfma_f32_16x16x32_bf16 v[16:19], v[232:235], v[192:195], v[16:19]
	v_mfma_f32_16x16x32_bf16 v[4:7], v[220:223], v[200:203], v[4:7]
	v_mfma_f32_16x16x32_bf16 v[0:3], v[232:235], v[200:203], v[0:3]
	v_mfma_f32_16x16x32_bf16 v[52:55], v[228:231], v[160:163], v[52:55]
	v_mfma_f32_16x16x32_bf16 v[48:51], v[236:239], v[160:163], v[48:51]
	v_mfma_f32_16x16x32_bf16 v[36:39], v[228:231], v[188:191], v[36:39]
	v_mfma_f32_16x16x32_bf16 v[32:35], v[236:239], v[188:191], v[32:35]
	v_mfma_f32_16x16x32_bf16 v[20:23], v[228:231], v[196:199], v[20:23]
	v_mfma_f32_16x16x32_bf16 v[16:19], v[236:239], v[196:199], v[16:19]
	v_mfma_f32_16x16x32_bf16 v[4:7], v[228:231], v[204:207], v[4:7]
	v_mfma_f32_16x16x32_bf16 v[0:3], v[236:239], v[204:207], v[0:3]
	s_barrier
	s_add_i32 s34, s34, 2
	s_add_u32 s52, s52, 0x100
	s_addc_u32 s53, s53, 0
	s_add_u32 s31, s31, 0x100
	s_addc_u32 s33, s33, 0
	s_cmp_gt_u32 s34, 13
.LBB0_326:
	s_add_u32 s27, s52, 0xfffc0080
	s_addc_u32 s35, s53, -1
	s_add_i32 s36, 0, 0x10000
	ds_read_b128 v[128:131], v216
	ds_read_b128 v[132:135], v216 offset:1024
	ds_read_b128 v[136:139], v216 offset:2048
	ds_read_b128 v[140:143], v216 offset:3072
	s_cmp_eq_u32 s34, 12
	s_cselect_b32 s75, s1, s35
	s_cselect_b32 s74, s11, s27
	s_cselect_b32 s73, s25, s33
	s_cselect_b32 s72, s30, s31
	s_add_i32 m0, s83, 0xc000
	ds_read_b128 v[156:159], v217
	ds_read_b128 v[160:163], v217 offset:1024
	ds_read_b128 v[164:167], v217 offset:2048
	ds_read_b128 v[188:191], v217 offset:3072
	ds_read_b128 v[192:195], v217 offset:4096
	ds_read_b128 v[196:199], v217 offset:5120
	ds_read_b128 v[200:203], v217 offset:6144
	ds_read_b128 v[204:207], v217 offset:7168
	global_load_lds_dwordx4 v152, s[52:53]
	s_add_i32 m0, s83, 0xe000
	s_nop 0
	global_load_lds_dwordx4 v154, s[52:53]
	s_waitcnt lgkmcnt(8)
	s_barrier
	s_waitcnt lgkmcnt(0)
	v_mfma_f32_16x16x32_bf16 v[124:127], v[128:131], v[156:159], v[124:127]
	v_mfma_f32_16x16x32_bf16 v[120:123], v[136:139], v[156:159], v[120:123]
	v_mfma_f32_16x16x32_bf16 v[108:111], v[128:131], v[164:167], v[108:111]
	v_mfma_f32_16x16x32_bf16 v[104:107], v[136:139], v[164:167], v[104:107]
	v_mfma_f32_16x16x32_bf16 v[92:95], v[128:131], v[192:195], v[92:95]
	v_mfma_f32_16x16x32_bf16 v[88:91], v[136:139], v[192:195], v[88:91]
	v_mfma_f32_16x16x32_bf16 v[76:79], v[128:131], v[200:203], v[76:79]
	v_mfma_f32_16x16x32_bf16 v[72:75], v[136:139], v[200:203], v[72:75]
	v_mfma_f32_16x16x32_bf16 v[124:127], v[132:135], v[160:163], v[124:127]
	v_mfma_f32_16x16x32_bf16 v[120:123], v[140:143], v[160:163], v[120:123]
	v_mfma_f32_16x16x32_bf16 v[108:111], v[132:135], v[188:191], v[108:111]
	v_mfma_f32_16x16x32_bf16 v[104:107], v[140:143], v[188:191], v[104:107]
	v_mfma_f32_16x16x32_bf16 v[92:95], v[132:135], v[196:199], v[92:95]
	v_mfma_f32_16x16x32_bf16 v[88:91], v[140:143], v[196:199], v[88:91]
	v_mfma_f32_16x16x32_bf16 v[76:79], v[132:135], v[204:207], v[76:79]
	v_mfma_f32_16x16x32_bf16 v[72:75], v[140:143], v[204:207], v[72:75]
	s_barrier
	s_add_i32 s27, 0, 0x14000
	s_add_i32 s35, s36, s81
	s_mov_b32 m0, s35
	ds_read_b128 v[220:223], v216 offset:16384
	ds_read_b128 v[228:231], v216 offset:17408
	ds_read_b128 v[232:235], v216 offset:18432
	ds_read_b128 v[236:239], v216 offset:19456
	global_load_lds_dwordx4 v148, s[72:73]
	s_add_i32 m0, s35, 0x2000
	s_nop 0
	global_load_lds_dwordx4 v146, s[72:73]
	s_barrier
	s_waitcnt lgkmcnt(0)
	v_mfma_f32_16x16x32_bf16 v[116:119], v[220:223], v[156:159], v[116:119]
	v_mfma_f32_16x16x32_bf16 v[112:115], v[232:235], v[156:159], v[112:115]
	v_mfma_f32_16x16x32_bf16 v[100:103], v[220:223], v[164:167], v[100:103]
	v_mfma_f32_16x16x32_bf16 v[96:99], v[232:235], v[164:167], v[96:99]
	v_mfma_f32_16x16x32_bf16 v[84:87], v[220:223], v[192:195], v[84:87]
	v_mfma_f32_16x16x32_bf16 v[80:83], v[232:235], v[192:195], v[80:83]
	v_mfma_f32_16x16x32_bf16 v[68:71], v[220:223], v[200:203], v[68:71]
	v_mfma_f32_16x16x32_bf16 v[64:67], v[232:235], v[200:203], v[64:67]
	v_mfma_f32_16x16x32_bf16 v[116:119], v[228:231], v[160:163], v[116:119]
	v_mfma_f32_16x16x32_bf16 v[112:115], v[236:239], v[160:163], v[112:115]
	v_mfma_f32_16x16x32_bf16 v[100:103], v[228:231], v[188:191], v[100:103]
	v_mfma_f32_16x16x32_bf16 v[96:99], v[236:239], v[188:191], v[96:99]
	v_mfma_f32_16x16x32_bf16 v[84:87], v[228:231], v[196:199], v[84:87]
	v_mfma_f32_16x16x32_bf16 v[80:83], v[236:239], v[196:199], v[80:83]
	v_mfma_f32_16x16x32_bf16 v[68:71], v[228:231], v[204:207], v[68:71]
	v_mfma_f32_16x16x32_bf16 v[64:67], v[236:239], v[204:207], v[64:67]
	s_barrier
	s_mov_b32 m0, s83
	ds_read_b128 v[156:159], v217 offset:16384
	ds_read_b128 v[160:163], v217 offset:17408
	ds_read_b128 v[164:167], v217 offset:18432
	ds_read_b128 v[188:191], v217 offset:19456
	ds_read_b128 v[192:195], v217 offset:20480
	ds_read_b128 v[196:199], v217 offset:21504
	ds_read_b128 v[200:203], v217 offset:22528
	ds_read_b128 v[204:207], v217 offset:23552
	global_load_lds_dwordx4 v148, s[74:75]
	s_mov_b32 m0, s84
	s_nop 0
	global_load_lds_dwordx4 v146, s[74:75]
	s_barrier
	s_waitcnt lgkmcnt(0)
	v_mfma_f32_16x16x32_bf16 v[60:63], v[128:131], v[156:159], v[60:63]
	v_mfma_f32_16x16x32_bf16 v[56:59], v[136:139], v[156:159], v[56:59]
	v_mfma_f32_16x16x32_bf16 v[44:47], v[128:131], v[164:167], v[44:47]
	v_mfma_f32_16x16x32_bf16 v[40:43], v[136:139], v[164:167], v[40:43]
	v_mfma_f32_16x16x32_bf16 v[28:31], v[128:131], v[192:195], v[28:31]
	v_mfma_f32_16x16x32_bf16 v[24:27], v[136:139], v[192:195], v[24:27]
	v_mfma_f32_16x16x32_bf16 v[12:15], v[128:131], v[200:203], v[12:15]
	v_mfma_f32_16x16x32_bf16 v[8:11], v[136:139], v[200:203], v[8:11]
	v_mfma_f32_16x16x32_bf16 v[60:63], v[132:135], v[160:163], v[60:63]
	v_mfma_f32_16x16x32_bf16 v[56:59], v[140:143], v[160:163], v[56:59]
	v_mfma_f32_16x16x32_bf16 v[44:47], v[132:135], v[188:191], v[44:47]
	v_mfma_f32_16x16x32_bf16 v[40:43], v[140:143], v[188:191], v[40:43]
	v_mfma_f32_16x16x32_bf16 v[28:31], v[132:135], v[196:199], v[28:31]
	v_mfma_f32_16x16x32_bf16 v[24:27], v[140:143], v[196:199], v[24:27]
	v_mfma_f32_16x16x32_bf16 v[12:15], v[132:135], v[204:207], v[12:15]
	v_mfma_f32_16x16x32_bf16 v[8:11], v[140:143], v[204:207], v[8:11]
	s_barrier
	s_add_u32 s36, s72, 0x40000
	s_addc_u32 s37, s73, 0
	s_add_i32 s27, s27, s81
	s_mov_b32 m0, s27
	s_nop 0
	global_load_lds_dwordx4 v148, s[36:37]
	s_add_i32 m0, s27, 0x2000
	s_nop 0
	global_load_lds_dwordx4 v146, s[36:37]
	s_waitcnt vmcnt(6)
	s_barrier
	v_mfma_f32_16x16x32_bf16 v[52:55], v[220:223], v[156:159], v[52:55]
	v_mfma_f32_16x16x32_bf16 v[48:51], v[232:235], v[156:159], v[48:51]
	v_mfma_f32_16x16x32_bf16 v[36:39], v[220:223], v[164:167], v[36:39]
	v_mfma_f32_16x16x32_bf16 v[32:35], v[232:235], v[164:167], v[32:35]
	v_mfma_f32_16x16x32_bf16 v[20:23], v[220:223], v[192:195], v[20:23]
	v_mfma_f32_16x16x32_bf16 v[16:19], v[232:235], v[192:195], v[16:19]
	v_mfma_f32_16x16x32_bf16 v[4:7], v[220:223], v[200:203], v[4:7]
	v_mfma_f32_16x16x32_bf16 v[0:3], v[232:235], v[200:203], v[0:3]
	v_mfma_f32_16x16x32_bf16 v[52:55], v[228:231], v[160:163], v[52:55]
	v_mfma_f32_16x16x32_bf16 v[48:51], v[236:239], v[160:163], v[48:51]
	v_mfma_f32_16x16x32_bf16 v[36:39], v[228:231], v[188:191], v[36:39]
	v_mfma_f32_16x16x32_bf16 v[32:35], v[236:239], v[188:191], v[32:35]
	v_mfma_f32_16x16x32_bf16 v[20:23], v[228:231], v[196:199], v[20:23]
	v_mfma_f32_16x16x32_bf16 v[16:19], v[236:239], v[196:199], v[16:19]
	v_mfma_f32_16x16x32_bf16 v[4:7], v[228:231], v[204:207], v[4:7]
	v_mfma_f32_16x16x32_bf16 v[0:3], v[236:239], v[204:207], v[0:3]
	s_barrier
	s_add_i32 s27, 0, 0x18000
	ds_read_b128 v[128:131], v216 offset:32768
	ds_read_b128 v[132:135], v216 offset:33792
	ds_read_b128 v[136:139], v216 offset:34816
	ds_read_b128 v[140:143], v216 offset:35840
	s_add_u32 s36, s74, 0x40000
	s_addc_u32 s37, s75, 0
	s_mov_b32 m0, s85
	ds_read_b128 v[156:159], v217 offset:32768
	ds_read_b128 v[160:163], v217 offset:33792
	ds_read_b128 v[164:167], v217 offset:34816
	ds_read_b128 v[188:191], v217 offset:35840
	ds_read_b128 v[192:195], v217 offset:36864
	ds_read_b128 v[196:199], v217 offset:37888
	ds_read_b128 v[200:203], v217 offset:38912
	ds_read_b128 v[204:207], v217 offset:39936
	global_load_lds_dwordx4 v148, s[36:37]
	s_mov_b32 m0, s86
	s_nop 0
	global_load_lds_dwordx4 v146, s[36:37]
	s_waitcnt lgkmcnt(8)
	s_barrier
	s_waitcnt lgkmcnt(0)
	v_mfma_f32_16x16x32_bf16 v[124:127], v[128:131], v[156:159], v[124:127]
	v_mfma_f32_16x16x32_bf16 v[120:123], v[136:139], v[156:159], v[120:123]
	v_mfma_f32_16x16x32_bf16 v[108:111], v[128:131], v[164:167], v[108:111]
	v_mfma_f32_16x16x32_bf16 v[104:107], v[136:139], v[164:167], v[104:107]
	v_mfma_f32_16x16x32_bf16 v[92:95], v[128:131], v[192:195], v[92:95]
	v_mfma_f32_16x16x32_bf16 v[88:91], v[136:139], v[192:195], v[88:91]
	v_mfma_f32_16x16x32_bf16 v[76:79], v[128:131], v[200:203], v[76:79]
	v_mfma_f32_16x16x32_bf16 v[72:75], v[136:139], v[200:203], v[72:75]
	v_mfma_f32_16x16x32_bf16 v[124:127], v[132:135], v[160:163], v[124:127]
	v_mfma_f32_16x16x32_bf16 v[120:123], v[140:143], v[160:163], v[120:123]
	v_mfma_f32_16x16x32_bf16 v[108:111], v[132:135], v[188:191], v[108:111]
	v_mfma_f32_16x16x32_bf16 v[104:107], v[140:143], v[188:191], v[104:107]
	v_mfma_f32_16x16x32_bf16 v[92:95], v[132:135], v[196:199], v[92:95]
	v_mfma_f32_16x16x32_bf16 v[88:91], v[140:143], v[196:199], v[88:91]
	v_mfma_f32_16x16x32_bf16 v[76:79], v[132:135], v[204:207], v[76:79]
	v_mfma_f32_16x16x32_bf16 v[72:75], v[140:143], v[204:207], v[72:75]
	s_barrier
	s_add_i32 s35, 0, 0x1c000
	s_add_i32 s27, s27, s81
	s_add_u32 s36, s72, s18
	s_addc_u32 s37, s73, s19
	s_mov_b32 m0, s27
	ds_read_b128 v[220:223], v216 offset:49152
	ds_read_b128 v[228:231], v216 offset:50176
	ds_read_b128 v[232:235], v216 offset:51200
	ds_read_b128 v[236:239], v216 offset:52224
	global_load_lds_dwordx4 v148, s[36:37]
	s_add_u32 s36, s72, s18
	s_addc_u32 s37, s73, s19
	s_add_i32 m0, s27, 0x2000
	s_nop 0
	global_load_lds_dwordx4 v146, s[36:37]
	s_barrier
	s_waitcnt lgkmcnt(0)
	v_mfma_f32_16x16x32_bf16 v[116:119], v[220:223], v[156:159], v[116:119]
	v_mfma_f32_16x16x32_bf16 v[112:115], v[232:235], v[156:159], v[112:115]
	v_mfma_f32_16x16x32_bf16 v[100:103], v[220:223], v[164:167], v[100:103]
	v_mfma_f32_16x16x32_bf16 v[96:99], v[232:235], v[164:167], v[96:99]
	v_mfma_f32_16x16x32_bf16 v[84:87], v[220:223], v[192:195], v[84:87]
	v_mfma_f32_16x16x32_bf16 v[80:83], v[232:235], v[192:195], v[80:83]
	v_mfma_f32_16x16x32_bf16 v[68:71], v[220:223], v[200:203], v[68:71]
	v_mfma_f32_16x16x32_bf16 v[64:67], v[232:235], v[200:203], v[64:67]
	v_mfma_f32_16x16x32_bf16 v[116:119], v[228:231], v[160:163], v[116:119]
	v_mfma_f32_16x16x32_bf16 v[112:115], v[236:239], v[160:163], v[112:115]
	v_mfma_f32_16x16x32_bf16 v[100:103], v[228:231], v[188:191], v[100:103]
	v_mfma_f32_16x16x32_bf16 v[96:99], v[236:239], v[188:191], v[96:99]
	v_mfma_f32_16x16x32_bf16 v[84:87], v[228:231], v[196:199], v[84:87]
	v_mfma_f32_16x16x32_bf16 v[80:83], v[236:239], v[196:199], v[80:83]
	v_mfma_f32_16x16x32_bf16 v[68:71], v[228:231], v[204:207], v[68:71]
	v_mfma_f32_16x16x32_bf16 v[64:67], v[236:239], v[204:207], v[64:67]
	s_barrier
	s_mov_b32 m0, s87
	s_add_u32 s36, s74, s18
	s_addc_u32 s37, s75, s19
	ds_read_b128 v[156:159], v217 offset:49152
	ds_read_b128 v[160:163], v217 offset:50176
	ds_read_b128 v[164:167], v217 offset:51200
	ds_read_b128 v[188:191], v217 offset:52224
	ds_read_b128 v[192:195], v217 offset:53248
	ds_read_b128 v[196:199], v217 offset:54272
	ds_read_b128 v[200:203], v217 offset:55296
	ds_read_b128 v[204:207], v217 offset:56320
	global_load_lds_dwordx4 v148, s[36:37]
	s_add_u32 s36, s74, s18
	s_addc_u32 s37, s75, s19
	s_mov_b32 m0, s79
	s_nop 0
	global_load_lds_dwordx4 v146, s[36:37]
	s_barrier
	s_waitcnt lgkmcnt(0)
	v_mfma_f32_16x16x32_bf16 v[60:63], v[128:131], v[156:159], v[60:63]
	v_mfma_f32_16x16x32_bf16 v[56:59], v[136:139], v[156:159], v[56:59]
	v_mfma_f32_16x16x32_bf16 v[44:47], v[128:131], v[164:167], v[44:47]
	v_mfma_f32_16x16x32_bf16 v[40:43], v[136:139], v[164:167], v[40:43]
	v_mfma_f32_16x16x32_bf16 v[28:31], v[128:131], v[192:195], v[28:31]
	v_mfma_f32_16x16x32_bf16 v[24:27], v[136:139], v[192:195], v[24:27]
	v_mfma_f32_16x16x32_bf16 v[12:15], v[128:131], v[200:203], v[12:15]
	v_mfma_f32_16x16x32_bf16 v[8:11], v[136:139], v[200:203], v[8:11]
	v_mfma_f32_16x16x32_bf16 v[60:63], v[132:135], v[160:163], v[60:63]
	v_mfma_f32_16x16x32_bf16 v[56:59], v[140:143], v[160:163], v[56:59]
	v_mfma_f32_16x16x32_bf16 v[44:47], v[132:135], v[188:191], v[44:47]
	v_mfma_f32_16x16x32_bf16 v[40:43], v[140:143], v[188:191], v[40:43]
	v_mfma_f32_16x16x32_bf16 v[28:31], v[132:135], v[196:199], v[28:31]
	v_mfma_f32_16x16x32_bf16 v[24:27], v[140:143], v[196:199], v[24:27]
	v_mfma_f32_16x16x32_bf16 v[12:15], v[132:135], v[204:207], v[12:15]
	v_mfma_f32_16x16x32_bf16 v[8:11], v[140:143], v[204:207], v[8:11]
	s_barrier
	s_add_u32 s36, s72, 0x40080
	s_addc_u32 s37, s73, 0
	s_add_i32 s27, s35, s81
	s_mov_b32 m0, s27
	s_nop 0
	global_load_lds_dwordx4 v148, s[36:37]
	s_add_i32 m0, s27, 0x2000
	s_nop 0
	global_load_lds_dwordx4 v146, s[36:37]
	s_waitcnt vmcnt(6)
	s_barrier
	v_mfma_f32_16x16x32_bf16 v[52:55], v[220:223], v[156:159], v[52:55]
	v_mfma_f32_16x16x32_bf16 v[48:51], v[232:235], v[156:159], v[48:51]
	v_mfma_f32_16x16x32_bf16 v[36:39], v[220:223], v[164:167], v[36:39]
	v_mfma_f32_16x16x32_bf16 v[32:35], v[232:235], v[164:167], v[32:35]
	v_mfma_f32_16x16x32_bf16 v[20:23], v[220:223], v[192:195], v[20:23]
	v_mfma_f32_16x16x32_bf16 v[16:19], v[232:235], v[192:195], v[16:19]
	v_mfma_f32_16x16x32_bf16 v[4:7], v[220:223], v[200:203], v[4:7]
	v_mfma_f32_16x16x32_bf16 v[0:3], v[232:235], v[200:203], v[0:3]
	v_mfma_f32_16x16x32_bf16 v[52:55], v[228:231], v[160:163], v[52:55]
	v_mfma_f32_16x16x32_bf16 v[48:51], v[236:239], v[160:163], v[48:51]
	v_mfma_f32_16x16x32_bf16 v[36:39], v[228:231], v[188:191], v[36:39]
	v_mfma_f32_16x16x32_bf16 v[32:35], v[236:239], v[188:191], v[32:35]
	v_mfma_f32_16x16x32_bf16 v[20:23], v[228:231], v[196:199], v[20:23]
	v_mfma_f32_16x16x32_bf16 v[16:19], v[236:239], v[196:199], v[16:19]
	v_mfma_f32_16x16x32_bf16 v[4:7], v[228:231], v[204:207], v[4:7]
	v_mfma_f32_16x16x32_bf16 v[0:3], v[236:239], v[204:207], v[0:3]
	s_barrier
	s_add_i32 s34, s34, 2
	s_add_u32 s52, s52, 0x100
	s_addc_u32 s53, s53, 0
	s_add_u32 s31, s31, 0x100
	s_addc_u32 s33, s33, 0
	s_cmp_gt_u32 s34, 13
	s_cbranch_scc0 .LBB0_326
	v_lshl_add_u32 v128, s0, 8, v151
	v_readlane_b32 s0, v252, 36
	v_ashrrev_i32_e32 v129, 31, v128
	v_readlane_b32 s1, v252, 37
	v_or_b32_e32 v132, 16, v128
	v_or_b32_e32 v136, 32, v128
	v_lshl_add_u64 v[130:131], v[128:129], 3, s[0:1]
	v_ashrrev_i32_e32 v133, 31, v132
	v_ashrrev_i32_e32 v137, 31, v136
	v_or_b32_e32 v140, 48, v128
	v_lshl_add_u64 v[134:135], v[132:133], 3, s[0:1]
	v_lshl_add_u64 v[138:139], v[136:137], 3, s[0:1]
	v_ashrrev_i32_e32 v141, 31, v140
	global_load_dwordx2 v[202:203], v[130:131], off
	global_load_dwordx2 v[200:201], v[134:135], off
	global_load_dwordx2 v[192:193], v[138:139], off
	global_load_dwordx2 v[166:167], v[130:131], off offset:1024
	v_add_u32_e32 v164, 0x90, v128
	v_add_u32_e32 v158, 0xa0, v128
	v_add_u32_e32 v156, 0xb0, v128
	v_lshl_add_u64 v[142:143], v[140:141], 3, s[0:1]
	v_ashrrev_i32_e32 v165, 31, v164
	v_ashrrev_i32_e32 v159, 31, v158
	v_ashrrev_i32_e32 v157, 31, v156
	v_lshl_add_u64 v[130:131], v[164:165], 3, s[0:1]
	v_lshl_add_u64 v[134:135], v[158:159], 3, s[0:1]
	v_lshl_add_u64 v[138:139], v[156:157], 3, s[0:1]
	global_load_dwordx2 v[196:197], v[142:143], off
	global_load_dwordx2 v[188:189], v[130:131], off
	global_load_dwordx2 v[162:163], v[134:135], off
	global_load_dwordx2 v[160:161], v[138:139], off
	v_add_u32_e32 v168, 0x80, v128
	s_mov_b64 s[0:1], -1
	s_cmp_gt_u32 s10, 1
	v_lshlrev_b32_e32 v144, 1, v150
	v_ashrrev_i32_e32 v169, 31, v168
	v_lshlrev_b64 v[204:205], 10, v[128:129]
	v_lshlrev_b64 v[198:199], 10, v[132:133]
	v_lshlrev_b64 v[194:195], 10, v[136:137]
	v_lshlrev_b64 v[190:191], 10, v[140:141]
	s_waitcnt vmcnt(0)
	v_ffbh_u32_e32 v222, v203
	v_ffbh_u32_e32 v221, v201
	v_ffbh_u32_e32 v220, v193
	v_ffbh_u32_e32 v219, v197
	s_cbranch_scc0 .LBB0_329
	s_cmp_lt_u32 s10, 4
	s_cselect_b64 vcc, -1, 0
	v_readlane_b32 s56, v254, 23
	s_and_b64 s[0:1], vcc, exec
	v_readlane_b32 s70, v254, 37
	v_readlane_b32 s36, v252, 15
	v_readlane_b32 s71, v254, 38
	v_readlane_b32 s37, v252, 16
	s_cselect_b32 s0, s70, s36
	s_mov_b32 s11, 0x4400000
	v_readlane_b32 s30, v254, 62
	s_cselect_b32 s1, s71, s37
	s_cselect_b32 s11, s11, 0x4800000
	v_readlane_b32 s31, v254, 63
	s_add_u32 s0, s0, s30
	s_addc_u32 s1, s1, s31
	global_load_dwordx4 v[136:139], v218, s[0:1] offset:16
	global_load_dwordx4 v[140:143], v218, s[0:1]
	global_load_dwordx4 v[128:131], v218, s[0:1] offset:144
	global_load_dwordx4 v[132:135], v218, s[0:1] offset:128
	v_and_b32_e32 v177, 64, v214
	v_xor_b32_e32 v176, 16, v214
	v_add_u32_e32 v177, 64, v177
	v_cndmask_b32_e32 v223, 1.0, v215, vcc
	v_cmp_lt_i32_e32 vcc, v176, v177
	v_readlane_b32 s9, v254, 52
	s_add_u32 s11, s9, s11
	v_cndmask_b32_e32 v176, v214, v176, vcc
	v_lshlrev_b32_e32 v225, 2, v176
	v_xor_b32_e32 v176, 32, v214
	v_cmp_lt_i32_e32 vcc, v176, v177
	v_readlane_b32 s9, v254, 61
	s_addc_u32 s25, s9, 0
	v_cndmask_b32_e32 v176, v214, v176, vcc
	v_lshlrev_b32_e32 v224, 2, v176
	v_min_u32_e32 v176, 32, v222
	v_lshlrev_b64 v[228:229], v176, v[202:203]
	v_min_u32_e32 v177, 1, v228
	v_or_b32_e32 v177, v229, v177
	v_cvt_f32_u32_e32 v177, v177
	v_sub_u32_e32 v176, 32, v176
	s_lshl_b32 s0, s10, 9
	s_and_b32 s0, s0, 0x200
	v_ldexp_f32 v176, v177, v176
	v_mul_f32_e32 v176, 0x35800000, v176
	v_fmamk_f32 v176, v176, 0x3a800000, v210
	s_add_u32 s0, s11, s0
	v_rsq_f32_e32 v176, v176
	s_addc_u32 s1, s25, 0
	v_lshl_add_u64 v[206:207], s[0:1], 0, v[144:145]
	v_readlane_b32 s48, v252, 27
	v_mov_b32_e32 v228, v176
	v_pk_mul_f32 v[230:231], v[124:125], v[228:229] op_sel_hi:[1,0]
	v_pk_mul_f32 v[232:233], v[126:127], v[228:229] op_sel_hi:[1,0]
	v_pk_mul_f32 v[236:237], v[230:231], v[230:231]
	v_pk_mul_f32 v[234:235], v[232:233], v[232:233]
	v_pk_mul_f32 v[250:251], v[114:115], v[228:229] op_sel_hi:[1,0]
	v_pk_mov_b32 v[238:239], v[236:237], v[234:235] op_sel:[1,0]
	v_mov_b32_e32 v237, v235
	v_pk_add_f32 v[234:235], v[238:239], v[236:237]
	v_pk_mul_f32 v[236:237], v[120:121], v[228:229] op_sel_hi:[1,0]
	v_pk_mul_f32 v[238:239], v[122:123], v[228:229] op_sel_hi:[1,0]
	v_pk_mul_f32 v[242:243], v[236:237], v[236:237]
	v_pk_mul_f32 v[240:241], v[238:239], v[238:239]
	v_pk_add_f32 v[234:235], v[234:235], v[234:235] op_sel_hi:[0,1]
	v_pk_mov_b32 v[244:245], v[242:243], v[240:241] op_sel:[1,0]
	v_mov_b32_e32 v243, v241
	v_pk_add_f32 v[240:241], v[244:245], v[242:243]
	v_pk_mul_f32 v[244:245], v[116:117], v[228:229] op_sel_hi:[1,0]
	v_pk_mul_f32 v[242:243], v[118:119], v[228:229] op_sel_hi:[1,0]
	v_mul_f32_e32 v234, v244, v244
	v_pk_fma_f32 v[246:247], v[244:245], v[244:245], v[234:235] op_sel_hi:[1,1,0]
	v_mul_f32_e32 v234, v242, v242
	v_pk_add_f32 v[240:241], v[240:241], v[240:241] op_sel_hi:[0,1]
	v_pk_fma_f32 v[248:249], v[242:243], v[242:243], v[234:235] op_sel_hi:[1,1,0]
	v_pk_mul_f32 v[176:177], v[112:113], v[228:229] op_sel_hi:[1,0]
	v_mul_f32_e32 v234, v250, v250
	v_mul_f32_e32 v246, v176, v176
	v_mul_f32_e32 v248, v177, v177
	v_mul_f32_e32 v240, v251, v251
	v_pk_add_f32 v[228:229], v[246:247], v[248:249]
	v_pk_add_f32 v[234:235], v[234:235], v[240:241]
	v_lshl_add_u64 v[240:241], v[206:207], 0, v[204:205]
	v_pk_add_f32 v[228:229], v[228:229], v[234:235]
	v_readlane_b32 s57, v254, 24
	v_add_f32_e32 v228, v228, v229
	ds_bpermute_b32 v229, v225, v228
	v_readlane_b32 s58, v254, 25
	v_readlane_b32 s59, v254, 26
	v_readlane_b32 s60, v254, 27
	v_readlane_b32 s61, v254, 28
	s_waitcnt lgkmcnt(0)
	v_add_f32_e32 v228, v228, v229
	ds_bpermute_b32 v229, v224, v228
	v_readlane_b32 s62, v254, 29
	v_readlane_b32 s63, v254, 30
	v_readlane_b32 s64, v254, 31
	v_readlane_b32 s65, v254, 32
	s_waitcnt lgkmcnt(0)
	v_add_f32_e32 v228, v228, v229
	v_fmamk_f32 v228, v228, 0x3c800000, v210
	v_readlane_b32 s66, v254, 33
	v_rsq_f32_e32 v228, v228
	v_readlane_b32 s67, v254, 34
	v_readlane_b32 s68, v254, 35
	v_readlane_b32 s69, v254, 36
	v_mul_f32_e32 v234, v223, v228
	v_pk_mul_f32 v[228:229], v[230:231], v[234:235] op_sel_hi:[1,0]
	v_pk_mul_f32 v[230:231], v[232:233], v[234:235] op_sel_hi:[1,0]
	s_waitcnt vmcnt(2)
	v_pk_mul_f32 v[228:229], v[140:141], v[228:229]
	v_pk_mul_f32 v[230:231], v[142:143], v[230:231]
	v_pk_mul_f32 v[232:233], v[236:237], v[234:235] op_sel_hi:[1,0]
	v_pk_mul_f32 v[236:237], v[238:239], v[234:235] op_sel_hi:[1,0]
	v_cvt_pk_bf16_f32 v228, v228, v229
	v_cvt_pk_bf16_f32 v229, v230, v231
	v_pk_mul_f32 v[232:233], v[136:137], v[232:233]
	v_pk_mul_f32 v[236:237], v[138:139], v[236:237]
	v_cvt_pk_bf16_f32 v230, v232, v233
	v_pk_mul_f32 v[176:177], v[176:177], v[234:235] op_sel_hi:[1,0]
	v_cvt_pk_bf16_f32 v231, v236, v237
	global_store_dwordx4 v[240:241], v[228:231], off
	v_pk_mul_f32 v[232:233], v[250:251], v[234:235] op_sel_hi:[1,0]
	s_waitcnt vmcnt(2)
	v_pk_mul_f32 v[176:177], v[128:129], v[176:177]
	v_pk_mul_f32 v[228:229], v[244:245], v[234:235] op_sel_hi:[1,0]
	v_pk_mul_f32 v[230:231], v[242:243], v[234:235] op_sel_hi:[1,0]
	s_waitcnt vmcnt(1)
	v_pk_mul_f32 v[228:229], v[132:133], v[228:229]
	v_pk_mul_f32 v[230:231], v[134:135], v[230:231]
	v_cvt_pk_bf16_f32 v228, v228, v229
	v_pk_mul_f32 v[232:233], v[130:131], v[232:233]
	v_cvt_pk_bf16_f32 v229, v230, v231
	v_cvt_pk_bf16_f32 v230, v176, v177
	s_nop 1
	v_readlane_b32 s38, v252, 17
	v_cvt_pk_bf16_f32 v231, v232, v233
	s_nop 1
	global_store_dwordx4 v[240:241], v[228:231], off offset:64
	v_readlane_b32 s39, v252, 18
	v_readlane_b32 s40, v252, 19
	v_min_u32_e32 v228, 32, v221
	v_lshlrev_b64 v[176:177], v228, v[200:201]
	v_min_u32_e32 v176, 1, v176
	v_or_b32_e32 v176, v177, v176
	v_cvt_f32_u32_e32 v176, v176
	v_sub_u32_e32 v177, 32, v228
	v_readlane_b32 s41, v252, 20
	v_readlane_b32 s42, v252, 21
	v_ldexp_f32 v176, v176, v177
	v_mul_f32_e32 v176, 0x35800000, v176
	v_fmamk_f32 v176, v176, 0x3a800000, v210
	v_readlane_b32 s43, v252, 22
	v_rsq_f32_e32 v176, v176
	v_readlane_b32 s44, v252, 23
	v_readlane_b32 s45, v252, 24
	v_readlane_b32 s46, v252, 25
	v_pk_mul_f32 v[228:229], v[108:109], v[176:177] op_sel_hi:[1,0]
	v_pk_mul_f32 v[230:231], v[110:111], v[176:177] op_sel_hi:[1,0]
	v_pk_mul_f32 v[234:235], v[228:229], v[228:229]
	v_pk_mul_f32 v[232:233], v[230:231], v[230:231]
	v_pk_mul_f32 v[248:249], v[98:99], v[176:177] op_sel_hi:[1,0]
	v_pk_mov_b32 v[236:237], v[234:235], v[232:233] op_sel:[1,0]
	v_mov_b32_e32 v235, v233
	v_pk_add_f32 v[232:233], v[236:237], v[234:235]
	v_pk_mul_f32 v[234:235], v[104:105], v[176:177] op_sel_hi:[1,0]
	v_pk_mul_f32 v[236:237], v[106:107], v[176:177] op_sel_hi:[1,0]
	v_pk_mul_f32 v[240:241], v[234:235], v[234:235]
	v_pk_mul_f32 v[238:239], v[236:237], v[236:237]
	v_pk_add_f32 v[232:233], v[232:233], v[232:233] op_sel_hi:[0,1]
	v_pk_mov_b32 v[242:243], v[240:241], v[238:239] op_sel:[1,0]
	v_mov_b32_e32 v241, v239
	v_pk_add_f32 v[238:239], v[242:243], v[240:241]
	v_pk_mul_f32 v[242:243], v[100:101], v[176:177] op_sel_hi:[1,0]
	v_pk_mul_f32 v[240:241], v[102:103], v[176:177] op_sel_hi:[1,0]
	v_mul_f32_e32 v232, v242, v242
	v_pk_fma_f32 v[244:245], v[242:243], v[242:243], v[232:233] op_sel_hi:[1,1,0]
	v_mul_f32_e32 v232, v240, v240
	v_pk_add_f32 v[238:239], v[238:239], v[238:239] op_sel_hi:[0,1]
	v_pk_fma_f32 v[246:247], v[240:241], v[240:241], v[232:233] op_sel_hi:[1,1,0]
	v_pk_mul_f32 v[176:177], v[96:97], v[176:177] op_sel_hi:[1,0]
	v_mul_f32_e32 v232, v248, v248
	v_mul_f32_e32 v244, v176, v176
	v_mul_f32_e32 v246, v177, v177
	v_mul_f32_e32 v238, v249, v249
	v_pk_add_f32 v[244:245], v[244:245], v[246:247]
	v_pk_add_f32 v[232:233], v[232:233], v[238:239]
	v_lshl_add_u64 v[238:239], v[206:207], 0, v[198:199]
	v_pk_add_f32 v[232:233], v[244:245], v[232:233]
	v_readlane_b32 s47, v252, 26
	v_add_f32_e32 v232, v232, v233
	ds_bpermute_b32 v233, v225, v232
	v_readlane_b32 s49, v252, 28
	v_readlane_b32 s50, v252, 29
	v_readlane_b32 s51, v252, 30
	v_readlane_b32 s48, v252, 40
	s_waitcnt lgkmcnt(0)
	v_add_f32_e32 v232, v232, v233
	ds_bpermute_b32 v233, v224, v232
	s_mov_b64 s[0:1], 0
	s_waitcnt lgkmcnt(0)
	v_add_f32_e32 v232, v232, v233
	v_fmamk_f32 v232, v232, 0x3c800000, v210
	s_nop 0
	v_rsq_f32_e32 v232, v232
	s_nop 0
	v_mul_f32_e32 v232, v223, v232
	v_pk_mul_f32 v[228:229], v[228:229], v[232:233] op_sel_hi:[1,0]
	v_pk_mul_f32 v[230:231], v[230:231], v[232:233] op_sel_hi:[1,0]
	v_pk_mul_f32 v[228:229], v[140:141], v[228:229]
	v_pk_mul_f32 v[230:231], v[142:143], v[230:231]
	v_pk_mul_f32 v[234:235], v[234:235], v[232:233] op_sel_hi:[1,0]
	v_pk_mul_f32 v[236:237], v[236:237], v[232:233] op_sel_hi:[1,0]
	v_cvt_pk_bf16_f32 v228, v228, v229
	v_cvt_pk_bf16_f32 v229, v230, v231
	v_pk_mul_f32 v[234:235], v[136:137], v[234:235]
	v_pk_mul_f32 v[236:237], v[138:139], v[236:237]
	v_cvt_pk_bf16_f32 v230, v234, v235
	v_pk_mul_f32 v[176:177], v[176:177], v[232:233] op_sel_hi:[1,0]
	v_cvt_pk_bf16_f32 v231, v236, v237
	global_store_dwordx4 v[238:239], v[228:231], off
	v_pk_mul_f32 v[176:177], v[128:129], v[176:177]
	s_nop 0
	v_pk_mul_f32 v[228:229], v[242:243], v[232:233] op_sel_hi:[1,0]
	v_pk_mul_f32 v[230:231], v[240:241], v[232:233] op_sel_hi:[1,0]
	v_pk_mul_f32 v[228:229], v[132:133], v[228:229]
	v_pk_mul_f32 v[230:231], v[134:135], v[230:231]
	v_pk_mul_f32 v[232:233], v[248:249], v[232:233] op_sel_hi:[1,0]
	v_cvt_pk_bf16_f32 v228, v228, v229
	v_cvt_pk_bf16_f32 v229, v230, v231
	v_cvt_pk_bf16_f32 v230, v176, v177
	s_nop 0
	v_pk_mul_f32 v[232:233], v[130:131], v[232:233]
	s_nop 0
	v_cvt_pk_bf16_f32 v231, v232, v233
	global_store_dwordx4 v[238:239], v[228:231], off offset:64
	s_nop 1
	v_min_u32_e32 v228, 32, v220
	v_lshlrev_b64 v[176:177], v228, v[192:193]
	v_min_u32_e32 v176, 1, v176
	v_or_b32_e32 v176, v177, v176
	v_cvt_f32_u32_e32 v176, v176
	v_sub_u32_e32 v177, 32, v228
	v_ldexp_f32 v176, v176, v177
	v_mul_f32_e32 v176, 0x35800000, v176
	v_fmamk_f32 v176, v176, 0x3a800000, v210
	s_nop 0
	v_rsq_f32_e32 v176, v176
	s_nop 0
	v_pk_mul_f32 v[228:229], v[92:93], v[176:177] op_sel_hi:[1,0]
	v_pk_mul_f32 v[230:231], v[94:95], v[176:177] op_sel_hi:[1,0]
	v_pk_mul_f32 v[234:235], v[228:229], v[228:229]
	v_pk_mul_f32 v[232:233], v[230:231], v[230:231]
	v_pk_mul_f32 v[248:249], v[82:83], v[176:177] op_sel_hi:[1,0]
	v_pk_mov_b32 v[236:237], v[234:235], v[232:233] op_sel:[1,0]
	v_mov_b32_e32 v235, v233
	v_pk_add_f32 v[232:233], v[236:237], v[234:235]
	v_pk_mul_f32 v[234:235], v[88:89], v[176:177] op_sel_hi:[1,0]
	v_pk_mul_f32 v[236:237], v[90:91], v[176:177] op_sel_hi:[1,0]
	v_pk_mul_f32 v[240:241], v[234:235], v[234:235]
	v_pk_mul_f32 v[238:239], v[236:237], v[236:237]
	v_pk_add_f32 v[232:233], v[232:233], v[232:233] op_sel_hi:[0,1]
	v_pk_mov_b32 v[242:243], v[240:241], v[238:239] op_sel:[1,0]
	v_mov_b32_e32 v241, v239
	v_pk_add_f32 v[238:239], v[242:243], v[240:241]
	v_pk_mul_f32 v[242:243], v[84:85], v[176:177] op_sel_hi:[1,0]
	v_pk_mul_f32 v[240:241], v[86:87], v[176:177] op_sel_hi:[1,0]
	v_mul_f32_e32 v232, v242, v242
	v_pk_fma_f32 v[244:245], v[242:243], v[242:243], v[232:233] op_sel_hi:[1,1,0]
	v_mul_f32_e32 v232, v240, v240
	v_pk_add_f32 v[238:239], v[238:239], v[238:239] op_sel_hi:[0,1]
	v_pk_fma_f32 v[246:247], v[240:241], v[240:241], v[232:233] op_sel_hi:[1,1,0]
	v_pk_mul_f32 v[176:177], v[80:81], v[176:177] op_sel_hi:[1,0]
	v_mul_f32_e32 v232, v248, v248
	v_mul_f32_e32 v244, v176, v176
	v_mul_f32_e32 v246, v177, v177
	v_mul_f32_e32 v238, v249, v249
	v_pk_add_f32 v[244:245], v[244:245], v[246:247]
	v_pk_add_f32 v[232:233], v[232:233], v[238:239]
	v_lshl_add_u64 v[238:239], v[206:207], 0, v[194:195]
	v_pk_add_f32 v[232:233], v[244:245], v[232:233]
	s_nop 0
	v_add_f32_e32 v232, v232, v233
	ds_bpermute_b32 v233, v225, v232
	s_waitcnt lgkmcnt(0)
	v_add_f32_e32 v232, v232, v233
	ds_bpermute_b32 v233, v224, v232
	s_waitcnt lgkmcnt(0)
	v_add_f32_e32 v232, v232, v233
	v_fmamk_f32 v232, v232, 0x3c800000, v210
	s_nop 0
	v_rsq_f32_e32 v232, v232
	s_nop 0
	v_mul_f32_e32 v232, v223, v232
	v_pk_mul_f32 v[228:229], v[228:229], v[232:233] op_sel_hi:[1,0]
	v_pk_mul_f32 v[230:231], v[230:231], v[232:233] op_sel_hi:[1,0]
	v_pk_mul_f32 v[228:229], v[140:141], v[228:229]
	v_pk_mul_f32 v[230:231], v[142:143], v[230:231]
	v_pk_mul_f32 v[234:235], v[234:235], v[232:233] op_sel_hi:[1,0]
	v_pk_mul_f32 v[236:237], v[236:237], v[232:233] op_sel_hi:[1,0]
	v_cvt_pk_bf16_f32 v228, v228, v229
	v_cvt_pk_bf16_f32 v229, v230, v231
	v_pk_mul_f32 v[234:235], v[136:137], v[234:235]
	v_pk_mul_f32 v[236:237], v[138:139], v[236:237]
	v_cvt_pk_bf16_f32 v230, v234, v235
	v_pk_mul_f32 v[176:177], v[176:177], v[232:233] op_sel_hi:[1,0]
	v_cvt_pk_bf16_f32 v231, v236, v237
	global_store_dwordx4 v[238:239], v[228:231], off
	v_pk_mul_f32 v[176:177], v[128:129], v[176:177]
	s_nop 0
	v_pk_mul_f32 v[228:229], v[242:243], v[232:233] op_sel_hi:[1,0]
	v_pk_mul_f32 v[230:231], v[240:241], v[232:233] op_sel_hi:[1,0]
	v_pk_mul_f32 v[228:229], v[132:133], v[228:229]
	v_pk_mul_f32 v[230:231], v[134:135], v[230:231]
	v_pk_mul_f32 v[232:233], v[248:249], v[232:233] op_sel_hi:[1,0]
	v_cvt_pk_bf16_f32 v228, v228, v229
	v_cvt_pk_bf16_f32 v229, v230, v231
	v_cvt_pk_bf16_f32 v230, v176, v177
	s_nop 0
	v_pk_mul_f32 v[232:233], v[130:131], v[232:233]
	s_nop 0
	v_cvt_pk_bf16_f32 v231, v232, v233
	global_store_dwordx4 v[238:239], v[228:231], off offset:64
	s_nop 1
	v_min_u32_e32 v228, 32, v219
	v_lshlrev_b64 v[176:177], v228, v[196:197]
	v_min_u32_e32 v176, 1, v176
	v_or_b32_e32 v176, v177, v176
	v_cvt_f32_u32_e32 v176, v176
	v_sub_u32_e32 v177, 32, v228
	v_ldexp_f32 v176, v176, v177
	v_mul_f32_e32 v176, 0x35800000, v176
	v_fmamk_f32 v176, v176, 0x3a800000, v210
	s_nop 0
	v_rsq_f32_e32 v176, v176
	s_nop 0
	v_pk_mul_f32 v[228:229], v[76:77], v[176:177] op_sel_hi:[1,0]
	v_pk_mul_f32 v[230:231], v[78:79], v[176:177] op_sel_hi:[1,0]
	v_pk_mul_f32 v[234:235], v[228:229], v[228:229]
	v_pk_mul_f32 v[232:233], v[230:231], v[230:231]
	v_pk_mul_f32 v[248:249], v[66:67], v[176:177] op_sel_hi:[1,0]
	v_pk_mov_b32 v[236:237], v[234:235], v[232:233] op_sel:[1,0]
	v_mov_b32_e32 v235, v233
	v_pk_add_f32 v[232:233], v[236:237], v[234:235]
	v_pk_mul_f32 v[234:235], v[72:73], v[176:177] op_sel_hi:[1,0]
	v_pk_mul_f32 v[236:237], v[74:75], v[176:177] op_sel_hi:[1,0]
	v_pk_mul_f32 v[240:241], v[234:235], v[234:235]
	v_pk_mul_f32 v[238:239], v[236:237], v[236:237]
	v_pk_add_f32 v[232:233], v[232:233], v[232:233] op_sel_hi:[0,1]
	v_pk_mov_b32 v[242:243], v[240:241], v[238:239] op_sel:[1,0]
	v_mov_b32_e32 v241, v239
	v_pk_add_f32 v[238:239], v[242:243], v[240:241]
	v_pk_mul_f32 v[242:243], v[68:69], v[176:177] op_sel_hi:[1,0]
	v_pk_mul_f32 v[240:241], v[70:71], v[176:177] op_sel_hi:[1,0]
	v_mul_f32_e32 v232, v242, v242
	v_pk_fma_f32 v[244:245], v[242:243], v[242:243], v[232:233] op_sel_hi:[1,1,0]
	v_mul_f32_e32 v232, v240, v240
	v_pk_add_f32 v[238:239], v[238:239], v[238:239] op_sel_hi:[0,1]
	v_pk_fma_f32 v[246:247], v[240:241], v[240:241], v[232:233] op_sel_hi:[1,1,0]
	v_pk_mul_f32 v[176:177], v[64:65], v[176:177] op_sel_hi:[1,0]
	v_mul_f32_e32 v232, v248, v248
	v_mul_f32_e32 v244, v176, v176
	v_mul_f32_e32 v246, v177, v177
	v_mul_f32_e32 v238, v249, v249
	v_pk_add_f32 v[244:245], v[244:245], v[246:247]
	v_pk_add_f32 v[232:233], v[232:233], v[238:239]
	v_lshl_add_u64 v[238:239], v[206:207], 0, v[190:191]
	v_pk_add_f32 v[232:233], v[244:245], v[232:233]
	s_nop 0
	v_add_f32_e32 v232, v232, v233
	ds_bpermute_b32 v233, v225, v232
	s_waitcnt lgkmcnt(0)
	v_add_f32_e32 v232, v232, v233
	ds_bpermute_b32 v233, v224, v232
	s_waitcnt lgkmcnt(0)
	v_add_f32_e32 v232, v232, v233
	v_fmamk_f32 v232, v232, 0x3c800000, v210
	s_nop 0
	v_rsq_f32_e32 v232, v232
	s_nop 0
	v_mul_f32_e32 v232, v223, v232
	v_pk_mul_f32 v[228:229], v[228:229], v[232:233] op_sel_hi:[1,0]
	v_pk_mul_f32 v[230:231], v[230:231], v[232:233] op_sel_hi:[1,0]
	v_pk_mul_f32 v[228:229], v[140:141], v[228:229]
	v_pk_mul_f32 v[230:231], v[142:143], v[230:231]
	v_pk_mul_f32 v[234:235], v[234:235], v[232:233] op_sel_hi:[1,0]
	v_pk_mul_f32 v[236:237], v[236:237], v[232:233] op_sel_hi:[1,0]
	v_pk_mul_f32 v[234:235], v[136:137], v[234:235]
	v_pk_mul_f32 v[236:237], v[138:139], v[236:237]
	v_cvt_pk_bf16_f32 v228, v228, v229
	v_cvt_pk_bf16_f32 v229, v230, v231
	v_cvt_pk_bf16_f32 v230, v234, v235
	v_pk_mul_f32 v[176:177], v[176:177], v[232:233] op_sel_hi:[1,0]
	v_cvt_pk_bf16_f32 v231, v236, v237
	global_store_dwordx4 v[238:239], v[228:231], off
	v_pk_mul_f32 v[176:177], v[128:129], v[176:177]
	s_nop 0
	v_pk_mul_f32 v[228:229], v[242:243], v[232:233] op_sel_hi:[1,0]
	v_pk_mul_f32 v[230:231], v[240:241], v[232:233] op_sel_hi:[1,0]
	v_pk_mul_f32 v[228:229], v[132:133], v[228:229]
	v_pk_mul_f32 v[230:231], v[134:135], v[230:231]
	v_pk_mul_f32 v[232:233], v[248:249], v[232:233] op_sel_hi:[1,0]
	v_cvt_pk_bf16_f32 v228, v228, v229
	v_cvt_pk_bf16_f32 v229, v230, v231
	v_cvt_pk_bf16_f32 v230, v176, v177
	v_ffbh_u32_e32 v176, v167
	v_pk_mul_f32 v[232:233], v[130:131], v[232:233]
	s_nop 0
	v_cvt_pk_bf16_f32 v231, v232, v233
	global_store_dwordx4 v[238:239], v[228:231], off offset:64
	s_nop 1
	v_min_u32_e32 v228, 32, v176
	v_lshlrev_b64 v[176:177], v228, v[166:167]
	v_min_u32_e32 v176, 1, v176
	v_or_b32_e32 v176, v177, v176
	v_cvt_f32_u32_e32 v176, v176
	v_sub_u32_e32 v177, 32, v228
	v_ldexp_f32 v176, v176, v177
	v_mul_f32_e32 v176, 0x35800000, v176
	v_fmamk_f32 v176, v176, 0x3a800000, v210
	s_nop 0
	v_rsq_f32_e32 v176, v176
	s_nop 0
	v_pk_mul_f32 v[228:229], v[60:61], v[176:177] op_sel_hi:[1,0]
	v_pk_mul_f32 v[230:231], v[62:63], v[176:177] op_sel_hi:[1,0]
	v_pk_mul_f32 v[234:235], v[228:229], v[228:229]
	v_pk_mul_f32 v[232:233], v[230:231], v[230:231]
	v_pk_mul_f32 v[248:249], v[50:51], v[176:177] op_sel_hi:[1,0]
	v_pk_mov_b32 v[236:237], v[234:235], v[232:233] op_sel:[1,0]
	v_mov_b32_e32 v235, v233
	v_pk_add_f32 v[232:233], v[236:237], v[234:235]
	v_pk_mul_f32 v[234:235], v[56:57], v[176:177] op_sel_hi:[1,0]
	v_pk_mul_f32 v[236:237], v[58:59], v[176:177] op_sel_hi:[1,0]
	v_pk_mul_f32 v[240:241], v[234:235], v[234:235]
	v_pk_mul_f32 v[238:239], v[236:237], v[236:237]
	v_pk_add_f32 v[232:233], v[232:233], v[232:233] op_sel_hi:[0,1]
	v_pk_mov_b32 v[242:243], v[240:241], v[238:239] op_sel:[1,0]
	v_mov_b32_e32 v241, v239
	v_pk_add_f32 v[238:239], v[242:243], v[240:241]
	v_pk_mul_f32 v[242:243], v[52:53], v[176:177] op_sel_hi:[1,0]
	v_pk_mul_f32 v[240:241], v[54:55], v[176:177] op_sel_hi:[1,0]
	v_mul_f32_e32 v232, v242, v242
	v_pk_fma_f32 v[244:245], v[242:243], v[242:243], v[232:233] op_sel_hi:[1,1,0]
	v_mul_f32_e32 v232, v240, v240
	v_pk_add_f32 v[238:239], v[238:239], v[238:239] op_sel_hi:[0,1]
	v_pk_fma_f32 v[246:247], v[240:241], v[240:241], v[232:233] op_sel_hi:[1,1,0]
	v_pk_mul_f32 v[176:177], v[48:49], v[176:177] op_sel_hi:[1,0]
	v_mul_f32_e32 v232, v248, v248
	v_mul_f32_e32 v244, v176, v176
	v_mul_f32_e32 v246, v177, v177
	v_mul_f32_e32 v238, v249, v249
	v_pk_add_f32 v[244:245], v[244:245], v[246:247]
	v_pk_add_f32 v[232:233], v[232:233], v[238:239]
	v_lshlrev_b64 v[238:239], 10, v[168:169]
	v_pk_add_f32 v[232:233], v[244:245], v[232:233]
	v_lshl_add_u64 v[238:239], v[206:207], 0, v[238:239]
	v_add_f32_e32 v232, v232, v233
	ds_bpermute_b32 v233, v225, v232
	s_waitcnt lgkmcnt(0)
	v_add_f32_e32 v232, v232, v233
	ds_bpermute_b32 v233, v224, v232
	s_waitcnt lgkmcnt(0)
	v_add_f32_e32 v232, v232, v233
	v_fmamk_f32 v232, v232, 0x3c800000, v210
	s_nop 0
	v_rsq_f32_e32 v232, v232
	s_nop 0
	v_mul_f32_e32 v232, v223, v232
	v_pk_mul_f32 v[228:229], v[228:229], v[232:233] op_sel_hi:[1,0]
	v_pk_mul_f32 v[230:231], v[230:231], v[232:233] op_sel_hi:[1,0]
	v_pk_mul_f32 v[228:229], v[140:141], v[228:229]
	v_pk_mul_f32 v[230:231], v[142:143], v[230:231]
	v_pk_mul_f32 v[234:235], v[234:235], v[232:233] op_sel_hi:[1,0]
	v_pk_mul_f32 v[236:237], v[236:237], v[232:233] op_sel_hi:[1,0]
	v_pk_mul_f32 v[234:235], v[136:137], v[234:235]
	v_pk_mul_f32 v[236:237], v[138:139], v[236:237]
	v_cvt_pk_bf16_f32 v228, v228, v229
	v_cvt_pk_bf16_f32 v229, v230, v231
	v_cvt_pk_bf16_f32 v230, v234, v235
	v_pk_mul_f32 v[176:177], v[176:177], v[232:233] op_sel_hi:[1,0]
	v_cvt_pk_bf16_f32 v231, v236, v237
	global_store_dwordx4 v[238:239], v[228:231], off
	v_pk_mul_f32 v[176:177], v[128:129], v[176:177]
	s_nop 0
	v_pk_mul_f32 v[228:229], v[242:243], v[232:233] op_sel_hi:[1,0]
	v_pk_mul_f32 v[230:231], v[240:241], v[232:233] op_sel_hi:[1,0]
	v_pk_mul_f32 v[228:229], v[132:133], v[228:229]
	v_pk_mul_f32 v[230:231], v[134:135], v[230:231]
	v_pk_mul_f32 v[232:233], v[248:249], v[232:233] op_sel_hi:[1,0]
	v_cvt_pk_bf16_f32 v228, v228, v229
	v_cvt_pk_bf16_f32 v229, v230, v231
	v_cvt_pk_bf16_f32 v230, v176, v177
	v_ffbh_u32_e32 v176, v189
	v_pk_mul_f32 v[232:233], v[130:131], v[232:233]
	s_nop 0
	v_cvt_pk_bf16_f32 v231, v232, v233
	global_store_dwordx4 v[238:239], v[228:231], off offset:64
	s_nop 1
	v_min_u32_e32 v228, 32, v176
	v_lshlrev_b64 v[176:177], v228, v[188:189]
	v_min_u32_e32 v176, 1, v176
	v_or_b32_e32 v176, v177, v176
	v_cvt_f32_u32_e32 v176, v176
	v_sub_u32_e32 v177, 32, v228
	v_ldexp_f32 v176, v176, v177
	v_mul_f32_e32 v176, 0x35800000, v176
	v_fmamk_f32 v176, v176, 0x3a800000, v210
	s_nop 0
	v_rsq_f32_e32 v176, v176
	s_nop 0
	v_pk_mul_f32 v[228:229], v[44:45], v[176:177] op_sel_hi:[1,0]
	v_pk_mul_f32 v[230:231], v[46:47], v[176:177] op_sel_hi:[1,0]
	v_pk_mul_f32 v[234:235], v[228:229], v[228:229]
	v_pk_mul_f32 v[232:233], v[230:231], v[230:231]
	v_pk_mul_f32 v[248:249], v[34:35], v[176:177] op_sel_hi:[1,0]
	v_pk_mov_b32 v[236:237], v[234:235], v[232:233] op_sel:[1,0]
	v_mov_b32_e32 v235, v233
	v_pk_add_f32 v[232:233], v[236:237], v[234:235]
	v_pk_mul_f32 v[234:235], v[40:41], v[176:177] op_sel_hi:[1,0]
	v_pk_mul_f32 v[236:237], v[42:43], v[176:177] op_sel_hi:[1,0]
	v_pk_mul_f32 v[240:241], v[234:235], v[234:235]
	v_pk_mul_f32 v[238:239], v[236:237], v[236:237]
	v_pk_add_f32 v[232:233], v[232:233], v[232:233] op_sel_hi:[0,1]
	v_pk_mov_b32 v[242:243], v[240:241], v[238:239] op_sel:[1,0]
	v_mov_b32_e32 v241, v239
	v_pk_add_f32 v[238:239], v[242:243], v[240:241]
	v_pk_mul_f32 v[242:243], v[36:37], v[176:177] op_sel_hi:[1,0]
	v_pk_mul_f32 v[240:241], v[38:39], v[176:177] op_sel_hi:[1,0]
	v_mul_f32_e32 v232, v242, v242
	v_pk_fma_f32 v[244:245], v[242:243], v[242:243], v[232:233] op_sel_hi:[1,1,0]
	v_mul_f32_e32 v232, v240, v240
	v_pk_add_f32 v[238:239], v[238:239], v[238:239] op_sel_hi:[0,1]
	v_pk_fma_f32 v[246:247], v[240:241], v[240:241], v[232:233] op_sel_hi:[1,1,0]
	v_pk_mul_f32 v[176:177], v[32:33], v[176:177] op_sel_hi:[1,0]
	v_mul_f32_e32 v232, v248, v248
	v_mul_f32_e32 v244, v176, v176
	v_mul_f32_e32 v246, v177, v177
	v_mul_f32_e32 v238, v249, v249
	v_pk_add_f32 v[244:245], v[244:245], v[246:247]
	v_pk_add_f32 v[232:233], v[232:233], v[238:239]
	v_lshlrev_b64 v[238:239], 10, v[164:165]
	v_pk_add_f32 v[232:233], v[244:245], v[232:233]
	v_lshl_add_u64 v[238:239], v[206:207], 0, v[238:239]
	v_add_f32_e32 v232, v232, v233
	ds_bpermute_b32 v233, v225, v232
	s_waitcnt lgkmcnt(0)
	v_add_f32_e32 v232, v232, v233
	ds_bpermute_b32 v233, v224, v232
	s_waitcnt lgkmcnt(0)
	v_add_f32_e32 v232, v232, v233
	v_fmamk_f32 v232, v232, 0x3c800000, v210
	s_nop 0
	v_rsq_f32_e32 v232, v232
	s_nop 0
	v_mul_f32_e32 v232, v223, v232
	v_pk_mul_f32 v[228:229], v[228:229], v[232:233] op_sel_hi:[1,0]
	v_pk_mul_f32 v[230:231], v[230:231], v[232:233] op_sel_hi:[1,0]
	v_pk_mul_f32 v[228:229], v[140:141], v[228:229]
	v_pk_mul_f32 v[230:231], v[142:143], v[230:231]
	v_pk_mul_f32 v[234:235], v[234:235], v[232:233] op_sel_hi:[1,0]
	v_pk_mul_f32 v[236:237], v[236:237], v[232:233] op_sel_hi:[1,0]
	v_pk_mul_f32 v[234:235], v[136:137], v[234:235]
	v_pk_mul_f32 v[236:237], v[138:139], v[236:237]
	v_cvt_pk_bf16_f32 v228, v228, v229
	v_cvt_pk_bf16_f32 v229, v230, v231
	v_cvt_pk_bf16_f32 v230, v234, v235
	v_pk_mul_f32 v[176:177], v[176:177], v[232:233] op_sel_hi:[1,0]
	v_cvt_pk_bf16_f32 v231, v236, v237
	global_store_dwordx4 v[238:239], v[228:231], off
	v_pk_mul_f32 v[176:177], v[128:129], v[176:177]
	s_nop 0
	v_pk_mul_f32 v[228:229], v[242:243], v[232:233] op_sel_hi:[1,0]
	v_pk_mul_f32 v[230:231], v[240:241], v[232:233] op_sel_hi:[1,0]
	v_pk_mul_f32 v[228:229], v[132:133], v[228:229]
	v_pk_mul_f32 v[230:231], v[134:135], v[230:231]
	v_pk_mul_f32 v[232:233], v[248:249], v[232:233] op_sel_hi:[1,0]
	v_cvt_pk_bf16_f32 v228, v228, v229
	v_cvt_pk_bf16_f32 v229, v230, v231
	v_cvt_pk_bf16_f32 v230, v176, v177
	v_ffbh_u32_e32 v176, v163
	v_pk_mul_f32 v[232:233], v[130:131], v[232:233]
	s_nop 0
	v_cvt_pk_bf16_f32 v231, v232, v233
	global_store_dwordx4 v[238:239], v[228:231], off offset:64
	s_nop 1
	v_min_u32_e32 v228, 32, v176
	v_lshlrev_b64 v[176:177], v228, v[162:163]
	v_min_u32_e32 v176, 1, v176
	v_or_b32_e32 v176, v177, v176
	v_cvt_f32_u32_e32 v176, v176
	v_sub_u32_e32 v177, 32, v228
	v_ldexp_f32 v176, v176, v177
	v_mul_f32_e32 v176, 0x35800000, v176
	v_fmamk_f32 v176, v176, 0x3a800000, v210
	s_nop 0
	v_rsq_f32_e32 v176, v176
	s_nop 0
	v_pk_mul_f32 v[228:229], v[28:29], v[176:177] op_sel_hi:[1,0]
	v_pk_mul_f32 v[230:231], v[30:31], v[176:177] op_sel_hi:[1,0]
	v_pk_mul_f32 v[234:235], v[228:229], v[228:229]
	v_pk_mul_f32 v[232:233], v[230:231], v[230:231]
	v_pk_mul_f32 v[248:249], v[18:19], v[176:177] op_sel_hi:[1,0]
	v_pk_mov_b32 v[236:237], v[234:235], v[232:233] op_sel:[1,0]
	v_mov_b32_e32 v235, v233
	v_pk_add_f32 v[232:233], v[236:237], v[234:235]
	v_pk_mul_f32 v[234:235], v[24:25], v[176:177] op_sel_hi:[1,0]
	v_pk_mul_f32 v[236:237], v[26:27], v[176:177] op_sel_hi:[1,0]
	v_pk_mul_f32 v[240:241], v[234:235], v[234:235]
	v_pk_mul_f32 v[238:239], v[236:237], v[236:237]
	v_pk_add_f32 v[232:233], v[232:233], v[232:233] op_sel_hi:[0,1]
	v_pk_mov_b32 v[242:243], v[240:241], v[238:239] op_sel:[1,0]
	v_mov_b32_e32 v241, v239
	v_pk_add_f32 v[238:239], v[242:243], v[240:241]
	v_pk_mul_f32 v[242:243], v[20:21], v[176:177] op_sel_hi:[1,0]
	v_pk_mul_f32 v[240:241], v[22:23], v[176:177] op_sel_hi:[1,0]
	v_mul_f32_e32 v232, v242, v242
	v_pk_fma_f32 v[244:245], v[242:243], v[242:243], v[232:233] op_sel_hi:[1,1,0]
	v_mul_f32_e32 v232, v240, v240
	v_pk_add_f32 v[238:239], v[238:239], v[238:239] op_sel_hi:[0,1]
	v_pk_fma_f32 v[246:247], v[240:241], v[240:241], v[232:233] op_sel_hi:[1,1,0]
	v_pk_mul_f32 v[176:177], v[16:17], v[176:177] op_sel_hi:[1,0]
	v_mul_f32_e32 v232, v248, v248
	v_mul_f32_e32 v244, v176, v176
	v_mul_f32_e32 v246, v177, v177
	v_mul_f32_e32 v238, v249, v249
	v_pk_add_f32 v[244:245], v[244:245], v[246:247]
	v_pk_add_f32 v[232:233], v[232:233], v[238:239]
	v_lshlrev_b64 v[238:239], 10, v[158:159]
	v_pk_add_f32 v[232:233], v[244:245], v[232:233]
	v_lshl_add_u64 v[238:239], v[206:207], 0, v[238:239]
	v_add_f32_e32 v232, v232, v233
	ds_bpermute_b32 v233, v225, v232
	s_waitcnt lgkmcnt(0)
	v_add_f32_e32 v232, v232, v233
	ds_bpermute_b32 v233, v224, v232
	s_waitcnt lgkmcnt(0)
	v_add_f32_e32 v232, v232, v233
	v_fmamk_f32 v232, v232, 0x3c800000, v210
	s_nop 0
	v_rsq_f32_e32 v232, v232
	s_nop 0
	v_mul_f32_e32 v232, v223, v232
	v_pk_mul_f32 v[228:229], v[228:229], v[232:233] op_sel_hi:[1,0]
	v_pk_mul_f32 v[230:231], v[230:231], v[232:233] op_sel_hi:[1,0]
	v_pk_mul_f32 v[228:229], v[140:141], v[228:229]
	v_pk_mul_f32 v[230:231], v[142:143], v[230:231]
	v_pk_mul_f32 v[234:235], v[234:235], v[232:233] op_sel_hi:[1,0]
	v_pk_mul_f32 v[236:237], v[236:237], v[232:233] op_sel_hi:[1,0]
	v_pk_mul_f32 v[234:235], v[136:137], v[234:235]
	v_pk_mul_f32 v[236:237], v[138:139], v[236:237]
	v_cvt_pk_bf16_f32 v228, v228, v229
	v_cvt_pk_bf16_f32 v229, v230, v231
	v_cvt_pk_bf16_f32 v230, v234, v235
	v_pk_mul_f32 v[176:177], v[176:177], v[232:233] op_sel_hi:[1,0]
	v_cvt_pk_bf16_f32 v231, v236, v237
	global_store_dwordx4 v[238:239], v[228:231], off
	v_pk_mul_f32 v[176:177], v[128:129], v[176:177]
	s_nop 0
	v_pk_mul_f32 v[228:229], v[242:243], v[232:233] op_sel_hi:[1,0]
	v_pk_mul_f32 v[230:231], v[240:241], v[232:233] op_sel_hi:[1,0]
	v_pk_mul_f32 v[228:229], v[132:133], v[228:229]
	v_pk_mul_f32 v[230:231], v[134:135], v[230:231]
	v_pk_mul_f32 v[232:233], v[248:249], v[232:233] op_sel_hi:[1,0]
	v_cvt_pk_bf16_f32 v228, v228, v229
	v_cvt_pk_bf16_f32 v229, v230, v231
	v_cvt_pk_bf16_f32 v230, v176, v177
	v_ffbh_u32_e32 v176, v161
	v_pk_mul_f32 v[232:233], v[130:131], v[232:233]
	s_nop 0
	v_cvt_pk_bf16_f32 v231, v232, v233
	global_store_dwordx4 v[238:239], v[228:231], off offset:64
	s_nop 1
	v_min_u32_e32 v228, 32, v176
	v_lshlrev_b64 v[176:177], v228, v[160:161]
	v_min_u32_e32 v176, 1, v176
	v_or_b32_e32 v176, v177, v176
	v_cvt_f32_u32_e32 v176, v176
	v_sub_u32_e32 v177, 32, v228
	v_ldexp_f32 v176, v176, v177
	v_mul_f32_e32 v176, 0x35800000, v176
	v_fmamk_f32 v176, v176, 0x3a800000, v210
	s_nop 0
	v_rsq_f32_e32 v176, v176
	s_nop 0
	v_pk_mul_f32 v[228:229], v[12:13], v[176:177] op_sel_hi:[1,0]
	v_pk_mul_f32 v[230:231], v[14:15], v[176:177] op_sel_hi:[1,0]
	v_pk_mul_f32 v[234:235], v[228:229], v[228:229]
	v_pk_mul_f32 v[232:233], v[230:231], v[230:231]
	v_pk_mul_f32 v[248:249], v[2:3], v[176:177] op_sel_hi:[1,0]
	v_pk_mov_b32 v[236:237], v[234:235], v[232:233] op_sel:[1,0]
	v_mov_b32_e32 v235, v233
	v_pk_add_f32 v[232:233], v[236:237], v[234:235]
	v_pk_mul_f32 v[234:235], v[8:9], v[176:177] op_sel_hi:[1,0]
	v_pk_mul_f32 v[236:237], v[10:11], v[176:177] op_sel_hi:[1,0]
	v_pk_mul_f32 v[240:241], v[234:235], v[234:235]
	v_pk_mul_f32 v[238:239], v[236:237], v[236:237]
	v_pk_add_f32 v[232:233], v[232:233], v[232:233] op_sel_hi:[0,1]
	v_pk_mov_b32 v[242:243], v[240:241], v[238:239] op_sel:[1,0]
	v_mov_b32_e32 v241, v239
	v_pk_add_f32 v[238:239], v[242:243], v[240:241]
	v_pk_mul_f32 v[242:243], v[4:5], v[176:177] op_sel_hi:[1,0]
	v_pk_mul_f32 v[240:241], v[6:7], v[176:177] op_sel_hi:[1,0]
	v_mul_f32_e32 v232, v242, v242
	v_pk_fma_f32 v[244:245], v[242:243], v[242:243], v[232:233] op_sel_hi:[1,1,0]
	v_mul_f32_e32 v232, v240, v240
	v_pk_add_f32 v[238:239], v[238:239], v[238:239] op_sel_hi:[0,1]
	v_pk_fma_f32 v[246:247], v[240:241], v[240:241], v[232:233] op_sel_hi:[1,1,0]
	v_pk_mul_f32 v[176:177], v[0:1], v[176:177] op_sel_hi:[1,0]
	v_mul_f32_e32 v232, v248, v248
	v_mul_f32_e32 v244, v176, v176
	v_mul_f32_e32 v246, v177, v177
	v_mul_f32_e32 v238, v249, v249
	v_pk_add_f32 v[244:245], v[244:245], v[246:247]
	v_pk_add_f32 v[232:233], v[232:233], v[238:239]
	s_nop 0
	v_pk_add_f32 v[232:233], v[244:245], v[232:233]
	s_nop 0
	v_add_f32_e32 v232, v232, v233
	ds_bpermute_b32 v225, v225, v232
	s_waitcnt lgkmcnt(0)
	v_add_f32_e32 v225, v232, v225
	ds_bpermute_b32 v224, v224, v225
	v_lshlrev_b64 v[232:233], 10, v[156:157]
	v_lshl_add_u64 v[206:207], v[206:207], 0, v[232:233]
	s_waitcnt lgkmcnt(0)
	v_add_f32_e32 v224, v225, v224
	v_fmamk_f32 v224, v224, 0x3c800000, v210
	s_nop 0
	v_rsq_f32_e32 v224, v224
	s_nop 0
	v_mul_f32_e32 v224, v223, v224
	v_pk_mul_f32 v[228:229], v[228:229], v[224:225] op_sel_hi:[1,0]
	v_pk_mul_f32 v[230:231], v[230:231], v[224:225] op_sel_hi:[1,0]
	v_pk_mul_f32 v[140:141], v[140:141], v[228:229]
	v_pk_mul_f32 v[142:143], v[142:143], v[230:231]
	v_pk_mul_f32 v[228:229], v[234:235], v[224:225] op_sel_hi:[1,0]
	v_pk_mul_f32 v[230:231], v[236:237], v[224:225] op_sel_hi:[1,0]
	s_nop 0
	v_pk_mul_f32 v[230:231], v[138:139], v[230:231]
	v_pk_mul_f32 v[138:139], v[136:137], v[228:229]
	v_cvt_pk_bf16_f32 v136, v140, v141
	v_cvt_pk_bf16_f32 v137, v142, v143
	s_nop 0
	v_cvt_pk_bf16_f32 v138, v138, v139
	v_cvt_pk_bf16_f32 v139, v230, v231
	global_store_dwordx4 v[206:207], v[136:139], off
	s_nop 1
	v_pk_mul_f32 v[136:137], v[242:243], v[224:225] op_sel_hi:[1,0]
	v_pk_mul_f32 v[138:139], v[240:241], v[224:225] op_sel_hi:[1,0]
	v_pk_mul_f32 v[132:133], v[132:133], v[136:137]
	v_pk_mul_f32 v[134:135], v[134:135], v[138:139]
	v_pk_mul_f32 v[136:137], v[176:177], v[224:225] op_sel_hi:[1,0]
	v_pk_mul_f32 v[138:139], v[248:249], v[224:225] op_sel_hi:[1,0]
	s_nop 0
	v_pk_mul_f32 v[138:139], v[130:131], v[138:139]
	v_pk_mul_f32 v[130:131], v[128:129], v[136:137]
	v_cvt_pk_bf16_f32 v128, v132, v133
	v_cvt_pk_bf16_f32 v129, v134, v135
	s_nop 0
	v_cvt_pk_bf16_f32 v130, v130, v131
	v_cvt_pk_bf16_f32 v131, v138, v139
	s_nop 1

.LBB0_341:
	s_lshl_b64 s[30:31], s[36:37], 13
	s_sub_u32 s30, 0, s30
	s_subb_u32 s31, 0, s31
	s_add_u32 s30, s22, s30
	v_readlane_b32 s22, v254, 54
	s_addc_u32 s31, s22, s31
	s_add_u32 s42, s30, 0x4c00000
	s_addc_u32 s43, s31, 0
	v_bfe_u32 v16, v8, 4, 2
	s_add_u32 s44, s30, 0x5000000
	v_and_b32_e32 v15, 15, v8
	v_lshlrev_b32_e32 v17, 4, v16
	v_lshlrev_b32_e32 v18, 2, v8
	s_addc_u32 s45, s31, 0
	v_lshl_or_b32 v190, s25, 6, v15
	v_lshl_or_b32 v17, v15, 6, v17
	s_lshl_b32 s25, s25, 13
	v_and_b32_e32 v18, 32, v18
	v_bitop3_b32 v19, v17, s25, v18 bitop3:0xde
	s_lshl_b32 s25, s27, 5
	s_and_b32 s79, s25, 0x60
	s_add_i32 m0, s77, 0x18000
	v_lshl_add_u64 v[6:7], v[6:7], 0, s[18:19]
	s_lshl_b32 s25, s79, 7
	s_waitcnt vmcnt(4)
	s_barrier
	global_load_lds_dwordx4 v[6:7], off
	v_lshl_add_u64 v[4:5], v[4:5], 0, s[18:19]
	s_add_i32 m0, s77, 0x1a000
	s_add_i32 s80, s77, 0x8000
	s_add_i32 s83, s77, 0xa000
	global_load_lds_dwordx4 v[4:5], off
	v_lshl_add_u64 v[2:3], v[2:3], 0, s[18:19]
	s_mov_b32 m0, s80
	s_add_u32 s30, s50, 0x40080
	global_load_lds_dwordx4 v[2:3], off
	v_lshl_add_u64 v[0:1], v[0:1], 0, s[18:19]
	s_mov_b32 m0, s83
	s_addc_u32 s31, s51, 0
	global_load_lds_dwordx4 v[0:1], off
	s_add_i32 m0, s77, 0x1c000
	v_lshl_add_u64 v[0:1], s[30:31], 0, v[148:149]
	global_load_lds_dwordx4 v[0:1], off
	v_lshl_add_u64 v[0:1], s[30:31], 0, v[152:153]
	s_add_i32 m0, s77, 0x1e000
	v_and_b32_e32 v3, 1, v9
	global_load_lds_dwordx4 v[0:1], off
	v_lshrrev_b32_e32 v1, 2, v8
	v_and_b32_e32 v2, 4, v1
	v_lshlrev_b32_e32 v1, 14, v9
	v_and_b32_e32 v1, 0xffff8000, v1
	v_lshl_add_u32 v1, v10, 11, v1
	v_lshl_or_b32 v1, v3, 6, v1
	v_lshl_add_u32 v156, v11, 1, v1
	v_lshlrev_b32_e32 v1, 14, v12
	v_and_b32_e32 v1, 0xffff8000, v1
	v_lshlrev_b32_e32 v191, 3, v16
	s_waitcnt vmcnt(6)
	v_readlane_b32 s30, v252, 36
	v_lshl_add_u32 v1, v13, 11, v1
	v_and_b32_e32 v3, 1, v12
	v_and_b32_e32 v0, 16, v191
	v_lshlrev_b32_e32 v144, 6, v16
	v_readlane_b32 s31, v252, 37
	v_lshl_or_b32 v1, v3, 6, v1
	s_sext_i32_i16 s11, s38
	v_bitop3_b32 v192, v17, s25, v18 bitop3:0xde
	v_add_u32_e32 v192, 0x10000, v192
	v_add_u32_e32 v193, 0xfffffe00, v190
	s_mov_b32 s84, 0
	v_cmp_eq_u32_e64 s[38:39], 0, v15
	v_lshl_add_u64 v[154:155], s[30:31], 0, v[144:145]
	v_mov_b32_e32 v157, v145
	v_lshl_add_u32 v158, v14, 1, v1
	v_mov_b32_e32 v159, v145
	v_add_u32_e32 v194, 0, v19
	v_lshlrev_b32_e32 v144, 1, v0
	v_lshlrev_b32_e32 v160, 1, v2
	s_barrier
	v_readfirstlane_b32 s101, v208
	s_nop 3
	s_lshr_b32 s101, s101, 8
	s_cmp_eq_u32 s101, 0
	s_cbranch_scc1 .Lprio_a2_done
	s_setprio 1

.LBB0_350:
	s_lshl_b32 s25, s84, 1
	s_add_i32 s25, s85, s25
	s_and_b32 s85, s25, 3
	s_lshl_b32 s25, s85, 19
	s_add_u32 s92, s74, s25
	v_cmp_lt_i64_e32 vcc, s[52:53], v[180:181]
	s_addc_u32 s93, s75, 0
	s_and_b64 s[30:31], vcc, exec
	s_cselect_b32 s25, s93, s1
	s_cselect_b32 s30, s92, s0
	s_ashr_i32 s47, s46, 31
	s_lshl_b64 s[34:35], s[46:47], 19
	s_add_u32 s94, s54, s34
	s_addc_u32 s95, s55, s35
	s_and_b64 s[34:35], vcc, exec
	s_cselect_b32 s31, s95, s51
	s_cselect_b32 s33, s94, s50
	s_add_u32 s0, s0, 0x40080
	s_addc_u32 s1, s1, 0
	s_add_u32 s34, s50, 0x100
	s_addc_u32 s35, s51, 0
	s_mov_b32 s36, -2
	s_add_u32 s27, s0, 0xfffc0080
	s_addc_u32 s37, s1, -1
	s_add_i32 s47, 0, 0x10000
	ds_read_b128 v[128:131], v192
	ds_read_b128 v[132:135], v192 offset:1024
	ds_read_b128 v[136:139], v192 offset:2048
	ds_read_b128 v[140:143], v192 offset:3072
	s_cmp_eq_u32 s36, 12
	s_cselect_b32 s53, s25, s37
	s_cselect_b32 s52, s30, s27
	s_cselect_b32 s51, s31, s35
	s_cselect_b32 s50, s33, s34
	s_add_i32 m0, s77, 0xc000
	ds_read_b128 v[162:165], v194
	ds_read_b128 v[166:169], v194 offset:1024
	ds_read_b128 v[196:199], v194 offset:2048
	ds_read_b128 v[200:203], v194 offset:3072
	ds_read_b128 v[204:207], v194 offset:4096
	ds_read_b128 v[216:219], v194 offset:5120
	ds_read_b128 v[220:223], v194 offset:6144
	ds_read_b128 v[228:231], v194 offset:7168
	global_load_lds_dwordx4 v156, s[0:1]
	s_add_i32 m0, s77, 0xe000
	s_nop 0
	global_load_lds_dwordx4 v158, s[0:1]
	s_waitcnt lgkmcnt(8)
	s_barrier
	s_waitcnt lgkmcnt(0)
	v_mfma_f32_16x16x32_bf16 v[124:127], v[128:131], v[162:165], 0
	v_mfma_f32_16x16x32_bf16 v[120:123], v[136:139], v[162:165], 0
	v_mfma_f32_16x16x32_bf16 v[116:119], v[128:131], v[196:199], 0
	v_mfma_f32_16x16x32_bf16 v[112:115], v[136:139], v[196:199], 0
	v_mfma_f32_16x16x32_bf16 v[108:111], v[128:131], v[204:207], 0
	v_mfma_f32_16x16x32_bf16 v[104:107], v[136:139], v[204:207], 0
	v_mfma_f32_16x16x32_bf16 v[100:103], v[128:131], v[220:223], 0
	v_mfma_f32_16x16x32_bf16 v[96:99], v[136:139], v[220:223], 0
	v_mfma_f32_16x16x32_bf16 v[124:127], v[132:135], v[166:169], v[124:127]
	v_mfma_f32_16x16x32_bf16 v[120:123], v[140:143], v[166:169], v[120:123]
	v_mfma_f32_16x16x32_bf16 v[116:119], v[132:135], v[200:203], v[116:119]
	v_mfma_f32_16x16x32_bf16 v[112:115], v[140:143], v[200:203], v[112:115]
	v_mfma_f32_16x16x32_bf16 v[108:111], v[132:135], v[216:219], v[108:111]
	v_mfma_f32_16x16x32_bf16 v[104:107], v[140:143], v[216:219], v[104:107]
	v_mfma_f32_16x16x32_bf16 v[100:103], v[132:135], v[228:231], v[100:103]
	v_mfma_f32_16x16x32_bf16 v[96:99], v[140:143], v[228:231], v[96:99]
	s_barrier
	s_add_i32 s27, 0, 0x14000
	s_add_i32 s37, s47, s76
	s_mov_b32 m0, s37
	ds_read_b128 v[232:235], v192 offset:16384
	ds_read_b128 v[236:239], v192 offset:17408
	ds_read_b128 v[240:243], v192 offset:18432
	ds_read_b128 v[244:247], v192 offset:19456
	global_load_lds_dwordx4 v148, s[50:51]
	s_add_i32 m0, s37, 0x2000
	s_nop 0
	global_load_lds_dwordx4 v152, s[50:51]
	s_barrier
	s_waitcnt lgkmcnt(0)
	v_mfma_f32_16x16x32_bf16 v[92:95], v[232:235], v[162:165], 0
	v_mfma_f32_16x16x32_bf16 v[88:91], v[240:243], v[162:165], 0
	v_mfma_f32_16x16x32_bf16 v[84:87], v[232:235], v[196:199], 0
	v_mfma_f32_16x16x32_bf16 v[80:83], v[240:243], v[196:199], 0
	v_mfma_f32_16x16x32_bf16 v[76:79], v[232:235], v[204:207], 0
	v_mfma_f32_16x16x32_bf16 v[72:75], v[240:243], v[204:207], 0
	v_mfma_f32_16x16x32_bf16 v[68:71], v[232:235], v[220:223], 0
	v_mfma_f32_16x16x32_bf16 v[64:67], v[240:243], v[220:223], 0
	v_mfma_f32_16x16x32_bf16 v[92:95], v[236:239], v[166:169], v[92:95]
	v_mfma_f32_16x16x32_bf16 v[88:91], v[244:247], v[166:169], v[88:91]
	v_mfma_f32_16x16x32_bf16 v[84:87], v[236:239], v[200:203], v[84:87]
	v_mfma_f32_16x16x32_bf16 v[80:83], v[244:247], v[200:203], v[80:83]
	v_mfma_f32_16x16x32_bf16 v[76:79], v[236:239], v[216:219], v[76:79]
	v_mfma_f32_16x16x32_bf16 v[72:75], v[244:247], v[216:219], v[72:75]
	v_mfma_f32_16x16x32_bf16 v[68:71], v[236:239], v[228:231], v[68:71]
	v_mfma_f32_16x16x32_bf16 v[64:67], v[244:247], v[228:231], v[64:67]
	s_barrier
	s_mov_b32 m0, s77
	v_lshl_add_u64 v[224:225], s[52:53], 0, v[146:147]
	ds_read_b128 v[162:165], v194 offset:16384
	ds_read_b128 v[166:169], v194 offset:17408
	ds_read_b128 v[196:199], v194 offset:18432
	ds_read_b128 v[200:203], v194 offset:19456
	ds_read_b128 v[204:207], v194 offset:20480
	ds_read_b128 v[216:219], v194 offset:21504
	ds_read_b128 v[220:223], v194 offset:22528
	ds_read_b128 v[228:231], v194 offset:23552
	global_load_lds_dwordx4 v[224:225], off
	v_lshl_add_u64 v[248:249], s[52:53], 0, v[150:151]
	s_mov_b32 m0, s78
	s_nop 0
	global_load_lds_dwordx4 v[248:249], off
	s_barrier
	s_waitcnt lgkmcnt(0)
	v_mfma_f32_16x16x32_bf16 v[60:63], v[128:131], v[162:165], 0
	v_mfma_f32_16x16x32_bf16 v[56:59], v[136:139], v[162:165], 0
	v_mfma_f32_16x16x32_bf16 v[52:55], v[128:131], v[196:199], 0
	v_mfma_f32_16x16x32_bf16 v[48:51], v[136:139], v[196:199], 0
	v_mfma_f32_16x16x32_bf16 v[44:47], v[128:131], v[204:207], 0
	v_mfma_f32_16x16x32_bf16 v[40:43], v[136:139], v[204:207], 0
	v_mfma_f32_16x16x32_bf16 v[36:39], v[128:131], v[220:223], 0
	v_mfma_f32_16x16x32_bf16 v[32:35], v[136:139], v[220:223], 0
	v_mfma_f32_16x16x32_bf16 v[60:63], v[132:135], v[166:169], v[60:63]
	v_mfma_f32_16x16x32_bf16 v[56:59], v[140:143], v[166:169], v[56:59]
	v_mfma_f32_16x16x32_bf16 v[52:55], v[132:135], v[200:203], v[52:55]
	v_mfma_f32_16x16x32_bf16 v[48:51], v[140:143], v[200:203], v[48:51]
	v_mfma_f32_16x16x32_bf16 v[44:47], v[132:135], v[216:219], v[44:47]
	v_mfma_f32_16x16x32_bf16 v[40:43], v[140:143], v[216:219], v[40:43]
	v_mfma_f32_16x16x32_bf16 v[36:39], v[132:135], v[228:231], v[36:39]
	v_mfma_f32_16x16x32_bf16 v[32:35], v[140:143], v[228:231], v[32:35]
	s_barrier
	s_add_u32 s56, s50, 0x40000
	s_addc_u32 s57, s51, 0
	s_add_i32 s27, s27, s76
	s_mov_b32 m0, s27
	s_nop 0
	global_load_lds_dwordx4 v148, s[56:57]
	s_add_i32 m0, s27, 0x2000
	s_nop 0
	global_load_lds_dwordx4 v152, s[56:57]
	s_waitcnt vmcnt(6)
	s_barrier
	v_mfma_f32_16x16x32_bf16 v[28:31], v[232:235], v[162:165], 0
	v_mfma_f32_16x16x32_bf16 v[24:27], v[240:243], v[162:165], 0
	v_mfma_f32_16x16x32_bf16 v[20:23], v[232:235], v[196:199], 0
	v_mfma_f32_16x16x32_bf16 v[16:19], v[240:243], v[196:199], 0
	v_mfma_f32_16x16x32_bf16 v[12:15], v[232:235], v[204:207], 0
	v_mfma_f32_16x16x32_bf16 v[8:11], v[240:243], v[204:207], 0
	v_mfma_f32_16x16x32_bf16 v[4:7], v[232:235], v[220:223], 0
	v_mfma_f32_16x16x32_bf16 v[0:3], v[240:243], v[220:223], 0
	v_mfma_f32_16x16x32_bf16 v[28:31], v[236:239], v[166:169], v[28:31]
	v_mfma_f32_16x16x32_bf16 v[24:27], v[244:247], v[166:169], v[24:27]
	v_mfma_f32_16x16x32_bf16 v[20:23], v[236:239], v[200:203], v[20:23]
	v_mfma_f32_16x16x32_bf16 v[16:19], v[244:247], v[200:203], v[16:19]
	v_mfma_f32_16x16x32_bf16 v[12:15], v[236:239], v[216:219], v[12:15]
	v_mfma_f32_16x16x32_bf16 v[8:11], v[244:247], v[216:219], v[8:11]
	v_mfma_f32_16x16x32_bf16 v[4:7], v[236:239], v[228:231], v[4:7]
	v_mfma_f32_16x16x32_bf16 v[0:3], v[244:247], v[228:231], v[0:3]
	s_barrier
	s_add_i32 s27, 0, 0x18000
	ds_read_b128 v[128:131], v192 offset:32768
	ds_read_b128 v[132:135], v192 offset:33792
	ds_read_b128 v[136:139], v192 offset:34816
	ds_read_b128 v[140:143], v192 offset:35840
	s_add_u32 s52, s52, 0x40000
	s_addc_u32 s53, s53, 0
	s_mov_b32 m0, s81
	ds_read_b128 v[162:165], v194 offset:32768
	ds_read_b128 v[166:169], v194 offset:33792
	ds_read_b128 v[196:199], v194 offset:34816
	ds_read_b128 v[200:203], v194 offset:35840
	ds_read_b128 v[204:207], v194 offset:36864
	ds_read_b128 v[216:219], v194 offset:37888
	ds_read_b128 v[220:223], v194 offset:38912
	ds_read_b128 v[228:231], v194 offset:39936
	global_load_lds_dwordx4 v146, s[52:53]
	s_mov_b32 m0, s82
	s_nop 0
	global_load_lds_dwordx4 v150, s[52:53]
	s_waitcnt lgkmcnt(8)
	s_barrier
	s_waitcnt lgkmcnt(0)
	v_mfma_f32_16x16x32_bf16 v[124:127], v[128:131], v[162:165], v[124:127]
	v_mfma_f32_16x16x32_bf16 v[120:123], v[136:139], v[162:165], v[120:123]
	v_mfma_f32_16x16x32_bf16 v[116:119], v[128:131], v[196:199], v[116:119]
	v_mfma_f32_16x16x32_bf16 v[112:115], v[136:139], v[196:199], v[112:115]
	v_mfma_f32_16x16x32_bf16 v[108:111], v[128:131], v[204:207], v[108:111]
	v_mfma_f32_16x16x32_bf16 v[104:107], v[136:139], v[204:207], v[104:107]
	v_mfma_f32_16x16x32_bf16 v[100:103], v[128:131], v[220:223], v[100:103]
	v_mfma_f32_16x16x32_bf16 v[96:99], v[136:139], v[220:223], v[96:99]
	v_mfma_f32_16x16x32_bf16 v[124:127], v[132:135], v[166:169], v[124:127]
	v_mfma_f32_16x16x32_bf16 v[120:123], v[140:143], v[166:169], v[120:123]
	v_mfma_f32_16x16x32_bf16 v[116:119], v[132:135], v[200:203], v[116:119]
	v_mfma_f32_16x16x32_bf16 v[112:115], v[140:143], v[200:203], v[112:115]
	v_mfma_f32_16x16x32_bf16 v[108:111], v[132:135], v[216:219], v[108:111]
	v_mfma_f32_16x16x32_bf16 v[104:107], v[140:143], v[216:219], v[104:107]
	v_mfma_f32_16x16x32_bf16 v[100:103], v[132:135], v[228:231], v[100:103]
	v_mfma_f32_16x16x32_bf16 v[96:99], v[140:143], v[228:231], v[96:99]
	s_barrier
	s_add_i32 s37, 0, 0x1c000
	s_add_i32 s27, s27, s76
	s_add_u32 s56, s50, s18
	s_addc_u32 s57, s51, s19
	s_mov_b32 m0, s27
	ds_read_b128 v[232:235], v192 offset:49152
	ds_read_b128 v[236:239], v192 offset:50176
	ds_read_b128 v[240:243], v192 offset:51200
	ds_read_b128 v[244:247], v192 offset:52224
	global_load_lds_dwordx4 v148, s[56:57]
	s_add_u32 s56, s50, s18
	s_addc_u32 s57, s51, s19
	s_add_i32 m0, s27, 0x2000
	s_nop 0
	global_load_lds_dwordx4 v152, s[56:57]
	s_barrier
	s_waitcnt lgkmcnt(0)
	v_mfma_f32_16x16x32_bf16 v[92:95], v[232:235], v[162:165], v[92:95]
	v_mfma_f32_16x16x32_bf16 v[88:91], v[240:243], v[162:165], v[88:91]
	v_mfma_f32_16x16x32_bf16 v[84:87], v[232:235], v[196:199], v[84:87]
	v_mfma_f32_16x16x32_bf16 v[80:83], v[240:243], v[196:199], v[80:83]
	v_mfma_f32_16x16x32_bf16 v[76:79], v[232:235], v[204:207], v[76:79]
	v_mfma_f32_16x16x32_bf16 v[72:75], v[240:243], v[204:207], v[72:75]
	v_mfma_f32_16x16x32_bf16 v[68:71], v[232:235], v[220:223], v[68:71]
	v_mfma_f32_16x16x32_bf16 v[64:67], v[240:243], v[220:223], v[64:67]
	v_mfma_f32_16x16x32_bf16 v[92:95], v[236:239], v[166:169], v[92:95]
	v_mfma_f32_16x16x32_bf16 v[88:91], v[244:247], v[166:169], v[88:91]
	v_mfma_f32_16x16x32_bf16 v[84:87], v[236:239], v[200:203], v[84:87]
	v_mfma_f32_16x16x32_bf16 v[80:83], v[244:247], v[200:203], v[80:83]
	v_mfma_f32_16x16x32_bf16 v[76:79], v[236:239], v[216:219], v[76:79]
	v_mfma_f32_16x16x32_bf16 v[72:75], v[244:247], v[216:219], v[72:75]
	v_mfma_f32_16x16x32_bf16 v[68:71], v[236:239], v[228:231], v[68:71]
	v_mfma_f32_16x16x32_bf16 v[64:67], v[244:247], v[228:231], v[64:67]
	s_barrier
	s_mov_b32 m0, s80
	v_lshl_add_u64 v[176:177], v[224:225], 0, s[18:19]
	ds_read_b128 v[162:165], v194 offset:49152
	ds_read_b128 v[166:169], v194 offset:50176
	ds_read_b128 v[196:199], v194 offset:51200
	ds_read_b128 v[200:203], v194 offset:52224
	ds_read_b128 v[204:207], v194 offset:53248
	ds_read_b128 v[216:219], v194 offset:54272
	ds_read_b128 v[220:223], v194 offset:55296
	ds_read_b128 v[228:231], v194 offset:56320
	global_load_lds_dwordx4 v[176:177], off
	v_lshl_add_u64 v[176:177], v[248:249], 0, s[18:19]
	s_mov_b32 m0, s83
	s_nop 0
	global_load_lds_dwordx4 v[176:177], off
	s_barrier
	s_waitcnt lgkmcnt(0)
	v_mfma_f32_16x16x32_bf16 v[60:63], v[128:131], v[162:165], v[60:63]
	v_mfma_f32_16x16x32_bf16 v[56:59], v[136:139], v[162:165], v[56:59]
	v_mfma_f32_16x16x32_bf16 v[52:55], v[128:131], v[196:199], v[52:55]
	v_mfma_f32_16x16x32_bf16 v[48:51], v[136:139], v[196:199], v[48:51]
	v_mfma_f32_16x16x32_bf16 v[44:47], v[128:131], v[204:207], v[44:47]
	v_mfma_f32_16x16x32_bf16 v[40:43], v[136:139], v[204:207], v[40:43]
	v_mfma_f32_16x16x32_bf16 v[36:39], v[128:131], v[220:223], v[36:39]
	v_mfma_f32_16x16x32_bf16 v[32:35], v[136:139], v[220:223], v[32:35]
	v_mfma_f32_16x16x32_bf16 v[60:63], v[132:135], v[166:169], v[60:63]
	v_mfma_f32_16x16x32_bf16 v[56:59], v[140:143], v[166:169], v[56:59]
	v_mfma_f32_16x16x32_bf16 v[52:55], v[132:135], v[200:203], v[52:55]
	v_mfma_f32_16x16x32_bf16 v[48:51], v[140:143], v[200:203], v[48:51]
	v_mfma_f32_16x16x32_bf16 v[44:47], v[132:135], v[216:219], v[44:47]
	v_mfma_f32_16x16x32_bf16 v[40:43], v[140:143], v[216:219], v[40:43]
	v_mfma_f32_16x16x32_bf16 v[36:39], v[132:135], v[228:231], v[36:39]
	v_mfma_f32_16x16x32_bf16 v[32:35], v[140:143], v[228:231], v[32:35]
	s_barrier
	s_add_u32 s50, s50, 0x40080
	s_addc_u32 s51, s51, 0
	s_add_i32 s27, s37, s76
	s_mov_b32 m0, s27
	s_nop 0
	global_load_lds_dwordx4 v148, s[50:51]
	s_add_i32 m0, s27, 0x2000
	s_nop 0
	global_load_lds_dwordx4 v152, s[50:51]
	s_waitcnt vmcnt(6)
	s_barrier
	v_mfma_f32_16x16x32_bf16 v[28:31], v[232:235], v[162:165], v[28:31]
	v_mfma_f32_16x16x32_bf16 v[24:27], v[240:243], v[162:165], v[24:27]
	v_mfma_f32_16x16x32_bf16 v[20:23], v[232:235], v[196:199], v[20:23]
	v_mfma_f32_16x16x32_bf16 v[16:19], v[240:243], v[196:199], v[16:19]
	v_mfma_f32_16x16x32_bf16 v[12:15], v[232:235], v[204:207], v[12:15]
	v_mfma_f32_16x16x32_bf16 v[8:11], v[240:243], v[204:207], v[8:11]
	v_mfma_f32_16x16x32_bf16 v[4:7], v[232:235], v[220:223], v[4:7]
	v_mfma_f32_16x16x32_bf16 v[0:3], v[240:243], v[220:223], v[0:3]
	v_mfma_f32_16x16x32_bf16 v[28:31], v[236:239], v[166:169], v[28:31]
	v_mfma_f32_16x16x32_bf16 v[24:27], v[244:247], v[166:169], v[24:27]
	v_mfma_f32_16x16x32_bf16 v[20:23], v[236:239], v[200:203], v[20:23]
	v_mfma_f32_16x16x32_bf16 v[16:19], v[244:247], v[200:203], v[16:19]
	v_mfma_f32_16x16x32_bf16 v[12:15], v[236:239], v[216:219], v[12:15]
	v_mfma_f32_16x16x32_bf16 v[8:11], v[244:247], v[216:219], v[8:11]
	v_mfma_f32_16x16x32_bf16 v[4:7], v[236:239], v[228:231], v[4:7]
	v_mfma_f32_16x16x32_bf16 v[0:3], v[244:247], v[228:231], v[0:3]
	s_barrier
	s_add_i32 s36, s36, 2
	s_add_u32 s0, s0, 0x100
	s_addc_u32 s1, s1, 0
	s_add_u32 s34, s34, 0x100
	s_addc_u32 s35, s35, 0
	s_cmp_gt_u32 s36, 13
.LBB0_351:
	s_add_u32 s27, s0, 0xfffc0080
	s_addc_u32 s37, s1, -1
	s_add_i32 s47, 0, 0x10000
	ds_read_b128 v[128:131], v192
	ds_read_b128 v[132:135], v192 offset:1024
	ds_read_b128 v[136:139], v192 offset:2048
	ds_read_b128 v[140:143], v192 offset:3072
	s_cmp_eq_u32 s36, 12
	s_cselect_b32 s53, s25, s37
	s_cselect_b32 s52, s30, s27
	s_cselect_b32 s51, s31, s35
	s_cselect_b32 s50, s33, s34
	s_add_i32 m0, s77, 0xc000
	ds_read_b128 v[162:165], v194
	ds_read_b128 v[166:169], v194 offset:1024
	ds_read_b128 v[196:199], v194 offset:2048
	ds_read_b128 v[200:203], v194 offset:3072
	ds_read_b128 v[204:207], v194 offset:4096
	ds_read_b128 v[216:219], v194 offset:5120
	ds_read_b128 v[220:223], v194 offset:6144
	ds_read_b128 v[228:231], v194 offset:7168
	global_load_lds_dwordx4 v156, s[0:1]
	s_add_i32 m0, s77, 0xe000
	s_nop 0
	global_load_lds_dwordx4 v158, s[0:1]
	s_waitcnt lgkmcnt(8)
	s_barrier
	s_waitcnt lgkmcnt(0)
	v_mfma_f32_16x16x32_bf16 v[124:127], v[128:131], v[162:165], v[124:127]
	v_mfma_f32_16x16x32_bf16 v[120:123], v[136:139], v[162:165], v[120:123]
	v_mfma_f32_16x16x32_bf16 v[116:119], v[128:131], v[196:199], v[116:119]
	v_mfma_f32_16x16x32_bf16 v[112:115], v[136:139], v[196:199], v[112:115]
	v_mfma_f32_16x16x32_bf16 v[108:111], v[128:131], v[204:207], v[108:111]
	v_mfma_f32_16x16x32_bf16 v[104:107], v[136:139], v[204:207], v[104:107]
	v_mfma_f32_16x16x32_bf16 v[100:103], v[128:131], v[220:223], v[100:103]
	v_mfma_f32_16x16x32_bf16 v[96:99], v[136:139], v[220:223], v[96:99]
	v_mfma_f32_16x16x32_bf16 v[124:127], v[132:135], v[166:169], v[124:127]
	v_mfma_f32_16x16x32_bf16 v[120:123], v[140:143], v[166:169], v[120:123]
	v_mfma_f32_16x16x32_bf16 v[116:119], v[132:135], v[200:203], v[116:119]
	v_mfma_f32_16x16x32_bf16 v[112:115], v[140:143], v[200:203], v[112:115]
	v_mfma_f32_16x16x32_bf16 v[108:111], v[132:135], v[216:219], v[108:111]
	v_mfma_f32_16x16x32_bf16 v[104:107], v[140:143], v[216:219], v[104:107]
	v_mfma_f32_16x16x32_bf16 v[100:103], v[132:135], v[228:231], v[100:103]
	v_mfma_f32_16x16x32_bf16 v[96:99], v[140:143], v[228:231], v[96:99]
	s_barrier
	s_add_i32 s27, 0, 0x14000
	s_add_i32 s37, s47, s76
	s_mov_b32 m0, s37
	ds_read_b128 v[232:235], v192 offset:16384
	ds_read_b128 v[236:239], v192 offset:17408
	ds_read_b128 v[240:243], v192 offset:18432
	ds_read_b128 v[244:247], v192 offset:19456
	global_load_lds_dwordx4 v148, s[50:51]
	s_add_i32 m0, s37, 0x2000
	s_nop 0
	global_load_lds_dwordx4 v152, s[50:51]
	s_barrier
	s_waitcnt lgkmcnt(0)
	v_mfma_f32_16x16x32_bf16 v[92:95], v[232:235], v[162:165], v[92:95]
	v_mfma_f32_16x16x32_bf16 v[88:91], v[240:243], v[162:165], v[88:91]
	v_mfma_f32_16x16x32_bf16 v[84:87], v[232:235], v[196:199], v[84:87]
	v_mfma_f32_16x16x32_bf16 v[80:83], v[240:243], v[196:199], v[80:83]
	v_mfma_f32_16x16x32_bf16 v[76:79], v[232:235], v[204:207], v[76:79]
	v_mfma_f32_16x16x32_bf16 v[72:75], v[240:243], v[204:207], v[72:75]
	v_mfma_f32_16x16x32_bf16 v[68:71], v[232:235], v[220:223], v[68:71]
	v_mfma_f32_16x16x32_bf16 v[64:67], v[240:243], v[220:223], v[64:67]
	v_mfma_f32_16x16x32_bf16 v[92:95], v[236:239], v[166:169], v[92:95]
	v_mfma_f32_16x16x32_bf16 v[88:91], v[244:247], v[166:169], v[88:91]
	v_mfma_f32_16x16x32_bf16 v[84:87], v[236:239], v[200:203], v[84:87]
	v_mfma_f32_16x16x32_bf16 v[80:83], v[244:247], v[200:203], v[80:83]
	v_mfma_f32_16x16x32_bf16 v[76:79], v[236:239], v[216:219], v[76:79]
	v_mfma_f32_16x16x32_bf16 v[72:75], v[244:247], v[216:219], v[72:75]
	v_mfma_f32_16x16x32_bf16 v[68:71], v[236:239], v[228:231], v[68:71]
	v_mfma_f32_16x16x32_bf16 v[64:67], v[244:247], v[228:231], v[64:67]
	s_barrier
	s_mov_b32 m0, s77
	v_lshl_add_u64 v[224:225], s[52:53], 0, v[146:147]
	ds_read_b128 v[162:165], v194 offset:16384
	ds_read_b128 v[166:169], v194 offset:17408
	ds_read_b128 v[196:199], v194 offset:18432
	ds_read_b128 v[200:203], v194 offset:19456
	ds_read_b128 v[204:207], v194 offset:20480
	ds_read_b128 v[216:219], v194 offset:21504
	ds_read_b128 v[220:223], v194 offset:22528
	ds_read_b128 v[228:231], v194 offset:23552
	global_load_lds_dwordx4 v[224:225], off
	v_lshl_add_u64 v[248:249], s[52:53], 0, v[150:151]
	s_mov_b32 m0, s78
	s_nop 0
	global_load_lds_dwordx4 v[248:249], off
	s_barrier
	s_waitcnt lgkmcnt(0)
	v_mfma_f32_16x16x32_bf16 v[60:63], v[128:131], v[162:165], v[60:63]
	v_mfma_f32_16x16x32_bf16 v[56:59], v[136:139], v[162:165], v[56:59]
	v_mfma_f32_16x16x32_bf16 v[52:55], v[128:131], v[196:199], v[52:55]
	v_mfma_f32_16x16x32_bf16 v[48:51], v[136:139], v[196:199], v[48:51]
	v_mfma_f32_16x16x32_bf16 v[44:47], v[128:131], v[204:207], v[44:47]
	v_mfma_f32_16x16x32_bf16 v[40:43], v[136:139], v[204:207], v[40:43]
	v_mfma_f32_16x16x32_bf16 v[36:39], v[128:131], v[220:223], v[36:39]
	v_mfma_f32_16x16x32_bf16 v[32:35], v[136:139], v[220:223], v[32:35]
	v_mfma_f32_16x16x32_bf16 v[60:63], v[132:135], v[166:169], v[60:63]
	v_mfma_f32_16x16x32_bf16 v[56:59], v[140:143], v[166:169], v[56:59]
	v_mfma_f32_16x16x32_bf16 v[52:55], v[132:135], v[200:203], v[52:55]
	v_mfma_f32_16x16x32_bf16 v[48:51], v[140:143], v[200:203], v[48:51]
	v_mfma_f32_16x16x32_bf16 v[44:47], v[132:135], v[216:219], v[44:47]
	v_mfma_f32_16x16x32_bf16 v[40:43], v[140:143], v[216:219], v[40:43]
	v_mfma_f32_16x16x32_bf16 v[36:39], v[132:135], v[228:231], v[36:39]
	v_mfma_f32_16x16x32_bf16 v[32:35], v[140:143], v[228:231], v[32:35]
	s_barrier
	s_add_u32 s56, s50, 0x40000
	s_addc_u32 s57, s51, 0
	s_add_i32 s27, s27, s76
	s_mov_b32 m0, s27
	s_nop 0
	global_load_lds_dwordx4 v148, s[56:57]
	s_add_i32 m0, s27, 0x2000
	s_nop 0
	global_load_lds_dwordx4 v152, s[56:57]
	s_waitcnt vmcnt(6)
	s_barrier
	v_mfma_f32_16x16x32_bf16 v[28:31], v[232:235], v[162:165], v[28:31]
	v_mfma_f32_16x16x32_bf16 v[24:27], v[240:243], v[162:165], v[24:27]
	v_mfma_f32_16x16x32_bf16 v[20:23], v[232:235], v[196:199], v[20:23]
	v_mfma_f32_16x16x32_bf16 v[16:19], v[240:243], v[196:199], v[16:19]
	v_mfma_f32_16x16x32_bf16 v[12:15], v[232:235], v[204:207], v[12:15]
	v_mfma_f32_16x16x32_bf16 v[8:11], v[240:243], v[204:207], v[8:11]
	v_mfma_f32_16x16x32_bf16 v[4:7], v[232:235], v[220:223], v[4:7]
	v_mfma_f32_16x16x32_bf16 v[0:3], v[240:243], v[220:223], v[0:3]
	v_mfma_f32_16x16x32_bf16 v[28:31], v[236:239], v[166:169], v[28:31]
	v_mfma_f32_16x16x32_bf16 v[24:27], v[244:247], v[166:169], v[24:27]
	v_mfma_f32_16x16x32_bf16 v[20:23], v[236:239], v[200:203], v[20:23]
	v_mfma_f32_16x16x32_bf16 v[16:19], v[244:247], v[200:203], v[16:19]
	v_mfma_f32_16x16x32_bf16 v[12:15], v[236:239], v[216:219], v[12:15]
	v_mfma_f32_16x16x32_bf16 v[8:11], v[244:247], v[216:219], v[8:11]
	v_mfma_f32_16x16x32_bf16 v[4:7], v[236:239], v[228:231], v[4:7]
	v_mfma_f32_16x16x32_bf16 v[0:3], v[244:247], v[228:231], v[0:3]
	s_barrier
	s_add_i32 s27, 0, 0x18000
	ds_read_b128 v[128:131], v192 offset:32768
	ds_read_b128 v[132:135], v192 offset:33792
	ds_read_b128 v[136:139], v192 offset:34816
	ds_read_b128 v[140:143], v192 offset:35840
	s_add_u32 s52, s52, 0x40000
	s_addc_u32 s53, s53, 0
	s_mov_b32 m0, s81
	ds_read_b128 v[162:165], v194 offset:32768
	ds_read_b128 v[166:169], v194 offset:33792
	ds_read_b128 v[196:199], v194 offset:34816
	ds_read_b128 v[200:203], v194 offset:35840
	ds_read_b128 v[204:207], v194 offset:36864
	ds_read_b128 v[216:219], v194 offset:37888
	ds_read_b128 v[220:223], v194 offset:38912
	ds_read_b128 v[228:231], v194 offset:39936
	global_load_lds_dwordx4 v146, s[52:53]
	s_mov_b32 m0, s82
	s_nop 0
	global_load_lds_dwordx4 v150, s[52:53]
	s_waitcnt lgkmcnt(8)
	s_barrier
	s_waitcnt lgkmcnt(0)
	v_mfma_f32_16x16x32_bf16 v[124:127], v[128:131], v[162:165], v[124:127]
	v_mfma_f32_16x16x32_bf16 v[120:123], v[136:139], v[162:165], v[120:123]
	v_mfma_f32_16x16x32_bf16 v[116:119], v[128:131], v[196:199], v[116:119]
	v_mfma_f32_16x16x32_bf16 v[112:115], v[136:139], v[196:199], v[112:115]
	v_mfma_f32_16x16x32_bf16 v[108:111], v[128:131], v[204:207], v[108:111]
	v_mfma_f32_16x16x32_bf16 v[104:107], v[136:139], v[204:207], v[104:107]
	v_mfma_f32_16x16x32_bf16 v[100:103], v[128:131], v[220:223], v[100:103]
	v_mfma_f32_16x16x32_bf16 v[96:99], v[136:139], v[220:223], v[96:99]
	v_mfma_f32_16x16x32_bf16 v[124:127], v[132:135], v[166:169], v[124:127]
	v_mfma_f32_16x16x32_bf16 v[120:123], v[140:143], v[166:169], v[120:123]
	v_mfma_f32_16x16x32_bf16 v[116:119], v[132:135], v[200:203], v[116:119]
	v_mfma_f32_16x16x32_bf16 v[112:115], v[140:143], v[200:203], v[112:115]
	v_mfma_f32_16x16x32_bf16 v[108:111], v[132:135], v[216:219], v[108:111]
	v_mfma_f32_16x16x32_bf16 v[104:107], v[140:143], v[216:219], v[104:107]
	v_mfma_f32_16x16x32_bf16 v[100:103], v[132:135], v[228:231], v[100:103]
	v_mfma_f32_16x16x32_bf16 v[96:99], v[140:143], v[228:231], v[96:99]
	s_barrier
	s_add_i32 s37, 0, 0x1c000
	s_add_i32 s27, s27, s76
	s_add_u32 s56, s50, s18
	s_addc_u32 s57, s51, s19
	s_mov_b32 m0, s27
	ds_read_b128 v[232:235], v192 offset:49152
	ds_read_b128 v[236:239], v192 offset:50176
	ds_read_b128 v[240:243], v192 offset:51200
	ds_read_b128 v[244:247], v192 offset:52224
	global_load_lds_dwordx4 v148, s[56:57]
	s_add_u32 s56, s50, s18
	s_addc_u32 s57, s51, s19
	s_add_i32 m0, s27, 0x2000
	s_nop 0
	global_load_lds_dwordx4 v152, s[56:57]
	s_barrier
	s_waitcnt lgkmcnt(0)
	v_mfma_f32_16x16x32_bf16 v[92:95], v[232:235], v[162:165], v[92:95]
	v_mfma_f32_16x16x32_bf16 v[88:91], v[240:243], v[162:165], v[88:91]
	v_mfma_f32_16x16x32_bf16 v[84:87], v[232:235], v[196:199], v[84:87]
	v_mfma_f32_16x16x32_bf16 v[80:83], v[240:243], v[196:199], v[80:83]
	v_mfma_f32_16x16x32_bf16 v[76:79], v[232:235], v[204:207], v[76:79]
	v_mfma_f32_16x16x32_bf16 v[72:75], v[240:243], v[204:207], v[72:75]
	v_mfma_f32_16x16x32_bf16 v[68:71], v[232:235], v[220:223], v[68:71]
	v_mfma_f32_16x16x32_bf16 v[64:67], v[240:243], v[220:223], v[64:67]
	v_mfma_f32_16x16x32_bf16 v[92:95], v[236:239], v[166:169], v[92:95]
	v_mfma_f32_16x16x32_bf16 v[88:91], v[244:247], v[166:169], v[88:91]
	v_mfma_f32_16x16x32_bf16 v[84:87], v[236:239], v[200:203], v[84:87]
	v_mfma_f32_16x16x32_bf16 v[80:83], v[244:247], v[200:203], v[80:83]
	v_mfma_f32_16x16x32_bf16 v[76:79], v[236:239], v[216:219], v[76:79]
	v_mfma_f32_16x16x32_bf16 v[72:75], v[244:247], v[216:219], v[72:75]
	v_mfma_f32_16x16x32_bf16 v[68:71], v[236:239], v[228:231], v[68:71]
	v_mfma_f32_16x16x32_bf16 v[64:67], v[244:247], v[228:231], v[64:67]
	s_barrier
	s_mov_b32 m0, s80
	v_lshl_add_u64 v[176:177], v[224:225], 0, s[18:19]
	ds_read_b128 v[162:165], v194 offset:49152
	ds_read_b128 v[166:169], v194 offset:50176
	ds_read_b128 v[196:199], v194 offset:51200
	ds_read_b128 v[200:203], v194 offset:52224
	ds_read_b128 v[204:207], v194 offset:53248
	ds_read_b128 v[216:219], v194 offset:54272
	ds_read_b128 v[220:223], v194 offset:55296
	ds_read_b128 v[228:231], v194 offset:56320
	global_load_lds_dwordx4 v[176:177], off
	v_lshl_add_u64 v[176:177], v[248:249], 0, s[18:19]
	s_mov_b32 m0, s83
	s_nop 0
	global_load_lds_dwordx4 v[176:177], off
	s_barrier
	s_waitcnt lgkmcnt(0)
	v_mfma_f32_16x16x32_bf16 v[60:63], v[128:131], v[162:165], v[60:63]
	v_mfma_f32_16x16x32_bf16 v[56:59], v[136:139], v[162:165], v[56:59]
	v_mfma_f32_16x16x32_bf16 v[52:55], v[128:131], v[196:199], v[52:55]
	v_mfma_f32_16x16x32_bf16 v[48:51], v[136:139], v[196:199], v[48:51]
	v_mfma_f32_16x16x32_bf16 v[44:47], v[128:131], v[204:207], v[44:47]
	v_mfma_f32_16x16x32_bf16 v[40:43], v[136:139], v[204:207], v[40:43]
	v_mfma_f32_16x16x32_bf16 v[36:39], v[128:131], v[220:223], v[36:39]
	v_mfma_f32_16x16x32_bf16 v[32:35], v[136:139], v[220:223], v[32:35]
	v_mfma_f32_16x16x32_bf16 v[60:63], v[132:135], v[166:169], v[60:63]
	v_mfma_f32_16x16x32_bf16 v[56:59], v[140:143], v[166:169], v[56:59]
	v_mfma_f32_16x16x32_bf16 v[52:55], v[132:135], v[200:203], v[52:55]
	v_mfma_f32_16x16x32_bf16 v[48:51], v[140:143], v[200:203], v[48:51]
	v_mfma_f32_16x16x32_bf16 v[44:47], v[132:135], v[216:219], v[44:47]
	v_mfma_f32_16x16x32_bf16 v[40:43], v[140:143], v[216:219], v[40:43]
	v_mfma_f32_16x16x32_bf16 v[36:39], v[132:135], v[228:231], v[36:39]
	v_mfma_f32_16x16x32_bf16 v[32:35], v[140:143], v[228:231], v[32:35]
	s_barrier
	s_add_u32 s50, s50, 0x40080
	s_addc_u32 s51, s51, 0
	s_add_i32 s27, s37, s76
	s_mov_b32 m0, s27
	s_nop 0
	global_load_lds_dwordx4 v148, s[50:51]
	s_add_i32 m0, s27, 0x2000
	s_nop 0
	global_load_lds_dwordx4 v152, s[50:51]
	s_waitcnt vmcnt(6)
	s_barrier
	v_mfma_f32_16x16x32_bf16 v[28:31], v[232:235], v[162:165], v[28:31]
	v_mfma_f32_16x16x32_bf16 v[24:27], v[240:243], v[162:165], v[24:27]
	v_mfma_f32_16x16x32_bf16 v[20:23], v[232:235], v[196:199], v[20:23]
	v_mfma_f32_16x16x32_bf16 v[16:19], v[240:243], v[196:199], v[16:19]
	v_mfma_f32_16x16x32_bf16 v[12:15], v[232:235], v[204:207], v[12:15]
	v_mfma_f32_16x16x32_bf16 v[8:11], v[240:243], v[204:207], v[8:11]
	v_mfma_f32_16x16x32_bf16 v[4:7], v[232:235], v[220:223], v[4:7]
	v_mfma_f32_16x16x32_bf16 v[0:3], v[240:243], v[220:223], v[0:3]
	v_mfma_f32_16x16x32_bf16 v[28:31], v[236:239], v[166:169], v[28:31]
	v_mfma_f32_16x16x32_bf16 v[24:27], v[244:247], v[166:169], v[24:27]
	v_mfma_f32_16x16x32_bf16 v[20:23], v[236:239], v[200:203], v[20:23]
	v_mfma_f32_16x16x32_bf16 v[16:19], v[244:247], v[200:203], v[16:19]
	v_mfma_f32_16x16x32_bf16 v[12:15], v[236:239], v[216:219], v[12:15]
	v_mfma_f32_16x16x32_bf16 v[8:11], v[244:247], v[216:219], v[8:11]
	v_mfma_f32_16x16x32_bf16 v[4:7], v[236:239], v[228:231], v[4:7]
	v_mfma_f32_16x16x32_bf16 v[0:3], v[244:247], v[228:231], v[0:3]
	s_barrier
	s_add_i32 s36, s36, 2
	s_add_u32 s0, s0, 0x100
	s_addc_u32 s1, s1, 0
	s_add_u32 s34, s34, 0x100
	s_addc_u32 s35, s35, 0
	s_cmp_gt_u32 s36, 13
	s_cbranch_scc0 .LBB0_351
	s_lshl_b32 s0, s11, 8
	s_or_b32 s50, s0, s79
	s_ashr_i32 s51, s50, 31
	v_lshl_add_u64 v[140:141], s[50:51], 3, v[154:155]
	global_load_dwordx4 v[128:131], v[140:141], off offset:48
	global_load_dwordx4 v[132:135], v[140:141], off offset:32
	global_load_dwordx4 v[136:139], v[140:141], off offset:16
	global_load_dwordx4 v[162:165], v[140:141], off
	s_mov_b32 s34, 0x35800000
	s_mov_b32 s0, 0x358637bd
	v_mov_b64_e32 v[168:169], s[0:1]
	s_mov_b32 s30, 0x45800000
	s_cmp_lt_u32 s10, 2
	s_waitcnt vmcnt(0)
	v_ffbh_u32_e32 v142, v165
	v_min_u32_e32 v161, 32, v142
	v_lshlrev_b64 v[142:143], v161, v[164:165]
	v_min_u32_e32 v142, 1, v142
	v_or_b32_e32 v142, v143, v142
	v_cvt_f32_u32_e32 v142, v142
	v_sub_u32_e32 v143, 32, v161
	v_ldexp_f32 v143, v142, v143
	v_ffbh_u32_e32 v142, v163
	v_min_u32_e32 v142, 32, v142
	v_lshlrev_b64 v[162:163], v142, v[162:163]
	v_min_u32_e32 v161, 1, v162
	v_or_b32_e32 v161, v163, v161
	v_cvt_f32_u32_e32 v161, v161
	v_sub_u32_e32 v142, 32, v142
	v_ldexp_f32 v142, v161, v142
	v_pk_mul_f32 v[142:143], v[142:143], s[34:35] op_sel_hi:[1,0]
	s_nop 0
	v_pk_fma_f32 v[142:143], v[142:143], s[2:3], v[168:169] op_sel_hi:[1,0,0]
	s_nop 0
	v_mul_f32_e32 v161, 0x4b800000, v142
	v_cmp_gt_f32_e64 s[0:1], s89, v142
	v_cmp_gt_f32_e32 vcc, s89, v143
	s_nop 0
	v_cndmask_b32_e64 v142, v142, v161, s[0:1]
	v_mul_f32_e32 v161, 0x4b800000, v143
	v_cndmask_b32_e32 v143, v143, v161, vcc
	v_rsq_f32_e32 v142, v142
	v_rsq_f32_e32 v143, v143
	s_nop 0
	v_pk_mul_f32 v[162:163], v[142:143], s[30:31] op_sel_hi:[1,0]
	s_nop 0
	v_cndmask_b32_e64 v166, v142, v162, s[0:1]
	v_ffbh_u32_e32 v142, v139
	v_min_u32_e32 v142, 32, v142
	v_lshlrev_b64 v[138:139], v142, v[138:139]
	v_min_u32_e32 v138, 1, v138
	v_or_b32_e32 v138, v139, v138
	v_cvt_f32_u32_e32 v138, v138
	v_sub_u32_e32 v139, 32, v142
	v_cndmask_b32_e32 v167, v143, v163, vcc
	v_pk_mul_f32 v[60:61], v[60:61], v[166:167]
	v_ldexp_f32 v139, v138, v139
	v_ffbh_u32_e32 v138, v137
	v_min_u32_e32 v138, 32, v138
	v_lshlrev_b64 v[136:137], v138, v[136:137]
	v_min_u32_e32 v136, 1, v136
	v_or_b32_e32 v136, v137, v136
	v_cvt_f32_u32_e32 v136, v136
	v_sub_u32_e32 v137, 32, v138
	v_pk_mul_f32 v[52:53], v[52:53], v[166:167]
	v_pk_mul_f32 v[44:45], v[44:45], v[166:167]
	v_ldexp_f32 v138, v136, v137
	v_pk_mul_f32 v[136:137], v[138:139], s[34:35] op_sel_hi:[1,0]
	v_pk_mul_f32 v[36:37], v[36:37], v[166:167]
	v_pk_fma_f32 v[136:137], v[136:137], s[2:3], v[168:169] op_sel_hi:[1,0,0]
	s_nop 0
	v_mul_f32_e32 v138, 0x4b800000, v136
	v_cmp_gt_f32_e64 s[0:1], s89, v136
	v_cmp_gt_f32_e32 vcc, s89, v137
	s_nop 0
	v_cndmask_b32_e64 v136, v136, v138, s[0:1]
	v_mul_f32_e32 v138, 0x4b800000, v137
	v_cndmask_b32_e32 v137, v137, v138, vcc
	v_rsq_f32_e32 v136, v136
	v_rsq_f32_e32 v137, v137
	s_nop 0
	v_pk_mul_f32 v[138:139], v[136:137], s[30:31] op_sel_hi:[1,0]
	s_nop 0
	v_cndmask_b32_e64 v162, v136, v138, s[0:1]
	v_ffbh_u32_e32 v136, v135
	v_min_u32_e32 v136, 32, v136
	v_lshlrev_b64 v[134:135], v136, v[134:135]
	v_min_u32_e32 v134, 1, v134
	v_or_b32_e32 v134, v135, v134
	v_cvt_f32_u32_e32 v134, v134
	v_sub_u32_e32 v135, 32, v136
	v_cndmask_b32_e32 v163, v137, v139, vcc
	v_ldexp_f32 v135, v134, v135
	v_ffbh_u32_e32 v134, v133
	v_min_u32_e32 v134, 32, v134
	v_lshlrev_b64 v[132:133], v134, v[132:133]
	v_min_u32_e32 v132, 1, v132
	v_or_b32_e32 v132, v133, v132
	v_cvt_f32_u32_e32 v132, v132
	v_sub_u32_e32 v133, 32, v134
	v_ldexp_f32 v134, v132, v133
	v_pk_mul_f32 v[132:133], v[134:135], s[34:35] op_sel_hi:[1,0]
	s_nop 0
	v_pk_fma_f32 v[132:133], v[132:133], s[2:3], v[168:169] op_sel_hi:[1,0,0]
	s_nop 0
	v_mul_f32_e32 v134, 0x4b800000, v132
	v_cmp_gt_f32_e64 s[0:1], s89, v132
	v_cmp_gt_f32_e32 vcc, s89, v133
	s_nop 0
	v_cndmask_b32_e64 v132, v132, v134, s[0:1]
	v_mul_f32_e32 v134, 0x4b800000, v133
	v_cndmask_b32_e32 v133, v133, v134, vcc
	v_rsq_f32_e32 v132, v132
	v_rsq_f32_e32 v133, v133
	s_nop 0
	v_pk_mul_f32 v[134:135], v[132:133], s[30:31] op_sel_hi:[1,0]
	s_nop 0
	v_cndmask_b32_e64 v188, v132, v134, s[0:1]
	v_ffbh_u32_e32 v132, v131
	v_min_u32_e32 v132, 32, v132
	v_lshlrev_b64 v[130:131], v132, v[130:131]
	v_min_u32_e32 v130, 1, v130
	v_or_b32_e32 v130, v131, v130
	v_cvt_f32_u32_e32 v130, v130
	v_sub_u32_e32 v131, 32, v132
	v_cndmask_b32_e32 v189, v133, v135, vcc
	v_pk_mul_f32 v[56:57], v[56:57], v[188:189]
	v_ldexp_f32 v131, v130, v131
	v_ffbh_u32_e32 v130, v129
	v_min_u32_e32 v130, 32, v130
	v_lshlrev_b64 v[128:129], v130, v[128:129]
	v_min_u32_e32 v128, 1, v128
	v_or_b32_e32 v128, v129, v128
	v_cvt_f32_u32_e32 v128, v128
	v_sub_u32_e32 v129, 32, v130
	v_pk_mul_f32 v[48:49], v[48:49], v[188:189]
	v_pk_mul_f32 v[40:41], v[40:41], v[188:189]
	v_ldexp_f32 v130, v128, v129
	v_pk_mul_f32 v[128:129], v[130:131], s[34:35] op_sel_hi:[1,0]
	v_pk_mul_f32 v[32:33], v[32:33], v[188:189]
	v_pk_fma_f32 v[128:129], v[128:129], s[2:3], v[168:169] op_sel_hi:[1,0,0]
	s_nop 0
	v_mul_f32_e32 v130, 0x4b800000, v128
	v_cmp_gt_f32_e64 s[0:1], s89, v128
	v_cmp_gt_f32_e32 vcc, s89, v129
	s_nop 0
	v_cndmask_b32_e64 v128, v128, v130, s[0:1]
	v_mul_f32_e32 v130, 0x4b800000, v129
	v_cndmask_b32_e32 v129, v129, v130, vcc
	v_rsq_f32_e32 v128, v128
	v_rsq_f32_e32 v129, v129
	s_nop 0
	v_pk_mul_f32 v[130:131], v[128:129], s[30:31] op_sel_hi:[1,0]
	s_nop 0
	v_cndmask_b32_e32 v165, v129, v131, vcc
	v_cndmask_b32_e64 v164, v128, v130, s[0:1]
	global_load_dwordx4 v[128:131], v[140:141], off offset:1072
	global_load_dwordx4 v[132:135], v[140:141], off offset:1056
	global_load_dwordx4 v[136:139], v[140:141], off offset:1040
	s_nop 0
	global_load_dwordx4 v[140:143], v[140:141], off offset:1024
	s_waitcnt vmcnt(0)
	v_ffbh_u32_e32 v161, v143
	v_min_u32_e32 v161, 32, v161
	v_lshlrev_b64 v[142:143], v161, v[142:143]
	v_min_u32_e32 v142, 1, v142
	v_or_b32_e32 v142, v143, v142
	v_cvt_f32_u32_e32 v142, v142
	v_sub_u32_e32 v143, 32, v161
	v_ldexp_f32 v143, v142, v143
	v_ffbh_u32_e32 v142, v141
	v_min_u32_e32 v142, 32, v142
	v_lshlrev_b64 v[140:141], v142, v[140:141]
	v_min_u32_e32 v140, 1, v140
	v_or_b32_e32 v140, v141, v140
	v_cvt_f32_u32_e32 v140, v140
	v_sub_u32_e32 v141, 32, v142
	v_ldexp_f32 v142, v140, v141
	v_pk_mul_f32 v[140:141], v[142:143], s[34:35] op_sel_hi:[1,0]
	s_nop 0
	v_pk_fma_f32 v[140:141], v[140:141], s[2:3], v[168:169] op_sel_hi:[1,0,0]
	s_nop 0
	v_mul_f32_e32 v142, 0x4b800000, v140
	v_cmp_gt_f32_e64 s[0:1], s89, v140
	v_cmp_gt_f32_e32 vcc, s89, v141
	s_nop 0
	v_cndmask_b32_e64 v140, v140, v142, s[0:1]
	v_mul_f32_e32 v142, 0x4b800000, v141
	v_cndmask_b32_e32 v141, v141, v142, vcc
	v_rsq_f32_e32 v140, v140
	v_rsq_f32_e32 v141, v141
	s_nop 0
	v_pk_mul_f32 v[142:143], v[140:141], s[30:31] op_sel_hi:[1,0]
	s_nop 0
	v_cndmask_b32_e64 v142, v140, v142, s[0:1]
	v_ffbh_u32_e32 v140, v139
	v_min_u32_e32 v140, 32, v140
	v_lshlrev_b64 v[138:139], v140, v[138:139]
	v_min_u32_e32 v138, 1, v138
	v_or_b32_e32 v138, v139, v138
	v_cvt_f32_u32_e32 v138, v138
	v_sub_u32_e32 v139, 32, v140
	v_cndmask_b32_e32 v143, v141, v143, vcc
	v_pk_mul_f32 v[140:141], v[124:125], v[166:167]
	v_ldexp_f32 v139, v138, v139
	v_ffbh_u32_e32 v138, v137
	v_min_u32_e32 v138, 32, v138
	v_lshlrev_b64 v[136:137], v138, v[136:137]
	v_min_u32_e32 v136, 1, v136
	v_or_b32_e32 v136, v137, v136
	v_cvt_f32_u32_e32 v136, v136
	v_sub_u32_e32 v137, 32, v138
	v_pk_mul_f32 v[28:29], v[28:29], v[142:143]
	v_pk_mul_f32 v[20:21], v[20:21], v[142:143]
	v_ldexp_f32 v138, v136, v137
	v_pk_mul_f32 v[136:137], v[138:139], s[34:35] op_sel_hi:[1,0]
	v_pk_mul_f32 v[12:13], v[12:13], v[142:143]
	v_pk_fma_f32 v[136:137], v[136:137], s[2:3], v[168:169] op_sel_hi:[1,0,0]
	v_pk_mul_f32 v[4:5], v[4:5], v[142:143]
	v_mul_f32_e32 v138, 0x4b800000, v136
	v_cmp_gt_f32_e64 s[0:1], s89, v136
	v_cmp_gt_f32_e32 vcc, s89, v137
	s_nop 0
	v_cndmask_b32_e64 v136, v136, v138, s[0:1]
	v_mul_f32_e32 v138, 0x4b800000, v137
	v_cndmask_b32_e32 v137, v137, v138, vcc
	v_rsq_f32_e32 v136, v136
	v_rsq_f32_e32 v137, v137
	s_nop 0
	v_pk_mul_f32 v[138:139], v[136:137], s[30:31] op_sel_hi:[1,0]
	s_nop 0
	v_cndmask_b32_e64 v136, v136, v138, s[0:1]
	v_ffbh_u32_e32 v138, v135
	v_min_u32_e32 v138, 32, v138
	v_lshlrev_b64 v[134:135], v138, v[134:135]
	v_min_u32_e32 v134, 1, v134
	v_or_b32_e32 v134, v135, v134
	v_cvt_f32_u32_e32 v134, v134
	v_sub_u32_e32 v135, 32, v138
	v_cndmask_b32_e32 v137, v137, v139, vcc
	v_pk_mul_f32 v[138:139], v[120:121], v[188:189]
	v_ldexp_f32 v135, v134, v135
	v_ffbh_u32_e32 v134, v133
	v_min_u32_e32 v134, 32, v134
	v_lshlrev_b64 v[132:133], v134, v[132:133]
	v_min_u32_e32 v132, 1, v132
	v_or_b32_e32 v132, v133, v132
	v_cvt_f32_u32_e32 v132, v132
	v_sub_u32_e32 v133, 32, v134
	v_pk_mul_f32 v[120:121], v[84:85], v[142:143]
	v_ldexp_f32 v134, v132, v133
	v_pk_mul_f32 v[132:133], v[134:135], s[34:35] op_sel_hi:[1,0]
	s_nop 0
	v_pk_fma_f32 v[132:133], v[132:133], s[2:3], v[168:169] op_sel_hi:[1,0,0]
	s_nop 0
	v_mul_f32_e32 v134, 0x4b800000, v132
	v_cmp_gt_f32_e64 s[0:1], s89, v132
	v_cmp_gt_f32_e32 vcc, s89, v133
	s_nop 0
	v_cndmask_b32_e64 v132, v132, v134, s[0:1]
	v_mul_f32_e32 v134, 0x4b800000, v133
	v_cndmask_b32_e32 v133, v133, v134, vcc
	v_rsq_f32_e32 v132, v132
	v_rsq_f32_e32 v133, v133
	s_nop 0
	v_pk_mul_f32 v[134:135], v[132:133], s[30:31] op_sel_hi:[1,0]
	s_nop 0
	v_cndmask_b32_e64 v176, v132, v134, s[0:1]
	v_ffbh_u32_e32 v132, v131
	v_min_u32_e32 v132, 32, v132
	v_lshlrev_b64 v[130:131], v132, v[130:131]
	v_min_u32_e32 v130, 1, v130
	v_or_b32_e32 v130, v131, v130
	v_cvt_f32_u32_e32 v130, v130
	v_sub_u32_e32 v131, 32, v132
	v_cndmask_b32_e32 v177, v133, v135, vcc
	v_pk_mul_f32 v[124:125], v[88:89], v[176:177]
	v_ldexp_f32 v131, v130, v131
	v_ffbh_u32_e32 v130, v129
	v_min_u32_e32 v130, 32, v130
	v_lshlrev_b64 v[128:129], v130, v[128:129]
	v_min_u32_e32 v128, 1, v128
	v_or_b32_e32 v128, v129, v128
	v_cvt_f32_u32_e32 v128, v128
	v_sub_u32_e32 v129, 32, v130
	v_pk_mul_f32 v[134:135], v[116:117], v[166:167]
	v_pk_mul_f32 v[132:133], v[112:113], v[188:189]
	v_ldexp_f32 v130, v128, v129
	v_pk_mul_f32 v[128:129], v[130:131], s[34:35] op_sel_hi:[1,0]
	v_pk_mul_f32 v[116:117], v[80:81], v[176:177]
	v_pk_fma_f32 v[128:129], v[128:129], s[2:3], v[168:169] op_sel_hi:[1,0,0]
	v_pk_mul_f32 v[88:89], v[104:105], v[188:189]
	v_mul_f32_e32 v130, 0x4b800000, v128
	v_cmp_gt_f32_e64 s[0:1], s89, v128
	v_cmp_gt_f32_e32 vcc, s89, v129
	v_pk_mul_f32 v[112:113], v[76:77], v[142:143]
	v_cndmask_b32_e64 v128, v128, v130, s[0:1]
	v_mul_f32_e32 v130, 0x4b800000, v129
	v_cndmask_b32_e32 v129, v129, v130, vcc
	v_rsq_f32_e32 v128, v128
	v_rsq_f32_e32 v129, v129
	v_pk_mul_f32 v[76:77], v[100:101], v[166:167]
	v_pk_mul_f32 v[104:105], v[68:69], v[142:143]
	v_pk_mul_f32 v[24:25], v[24:25], v[176:177]
	v_pk_mul_f32 v[130:131], v[128:129], s[30:31] op_sel_hi:[1,0]
	v_pk_mul_f32 v[16:17], v[16:17], v[176:177]
	v_cndmask_b32_e32 v129, v129, v131, vcc
	v_cndmask_b32_e64 v128, v128, v130, s[0:1]
	s_mov_b64 s[0:1], -1
	v_pk_mul_f32 v[130:131], v[92:93], v[142:143]
	v_pk_mul_f32 v[92:93], v[108:109], v[166:167]
	v_pk_mul_f32 v[108:109], v[72:73], v[176:177]
	v_pk_mul_f32 v[72:73], v[96:97], v[188:189]
	v_pk_mul_f32 v[96:97], v[64:65], v[176:177]
	v_pk_mul_f32 v[8:9], v[8:9], v[176:177]
	v_pk_mul_f32 v[0:1], v[0:1], v[176:177]
	s_cbranch_scc1 .LBB0_354
	v_lshl_add_u32 v68, s10, 8, v193
	v_ashrrev_i32_e32 v69, 31, v68
	v_pk_mul_f32 v[64:65], v[126:127], v[162:163]
	v_cvt_pk_bf16_f32 v80, v140, v141
	s_lshl_b64 s[0:1], s[50:51], 1
	v_cvt_pk_bf16_f32 v81, v64, v65
	v_lshlrev_b64 v[64:65], 13, v[68:69]
	v_lshl_add_u64 v[64:65], s[44:45], 0, v[64:65]
	v_lshl_add_u64 v[64:65], v[64:65], 0, s[0:1]
	v_lshl_add_u64 v[64:65], v[64:65], 0, v[144:145]
	v_mov_b32_e32 v161, v145
	v_lshl_add_u64 v[64:65], v[64:65], 0, v[160:161]
	global_store_dwordx2 v[64:65], v[80:81], off
	v_pk_mul_f32 v[80:81], v[122:123], v[164:165]
	v_cvt_pk_bf16_f32 v84, v138, v139
	s_nop 0
	v_cvt_pk_bf16_f32 v85, v80, v81
	v_pk_mul_f32 v[80:81], v[94:95], v[136:137]
	global_store_dwordx2 v[64:65], v[84:85], off offset:16
	v_cvt_pk_bf16_f32 v84, v130, v131
	v_cvt_pk_bf16_f32 v85, v80, v81
	v_pk_mul_f32 v[80:81], v[90:91], v[128:129]
	global_store_dwordx2 v[64:65], v[84:85], off offset:256
	v_cvt_pk_bf16_f32 v84, v124, v125
	v_cvt_pk_bf16_f32 v85, v80, v81
	v_or_b32_e32 v80, 16, v68
	v_ashrrev_i32_e32 v81, 31, v80
	v_lshlrev_b64 v[80:81], 13, v[80:81]
	v_lshl_add_u64 v[80:81], s[44:45], 0, v[80:81]
	v_lshl_add_u64 v[80:81], v[80:81], 0, s[0:1]
	v_lshl_add_u64 v[80:81], v[80:81], 0, v[144:145]
	global_store_dwordx2 v[64:65], v[84:85], off offset:272
	v_pk_mul_f32 v[84:85], v[118:119], v[162:163]
	v_cvt_pk_bf16_f32 v100, v134, v135
	v_lshl_add_u64 v[80:81], v[80:81], 0, v[160:161]
	v_cvt_pk_bf16_f32 v101, v84, v85
	global_store_dwordx2 v[80:81], v[100:101], off
	v_pk_mul_f32 v[84:85], v[114:115], v[164:165]
	v_cvt_pk_bf16_f32 v100, v132, v133
	s_nop 0
	v_cvt_pk_bf16_f32 v101, v84, v85
	global_store_dwordx2 v[80:81], v[100:101], off offset:16
	v_pk_mul_f32 v[84:85], v[86:87], v[136:137]
	v_cvt_pk_bf16_f32 v100, v120, v121
	s_nop 0
	v_cvt_pk_bf16_f32 v101, v84, v85
	global_store_dwordx2 v[80:81], v[100:101], off offset:256
	v_pk_mul_f32 v[84:85], v[82:83], v[128:129]
	v_cvt_pk_bf16_f32 v100, v116, v117
	s_nop 0
	v_cvt_pk_bf16_f32 v101, v84, v85
	global_store_dwordx2 v[80:81], v[100:101], off offset:272
	v_or_b32_e32 v80, 32, v68
	v_ashrrev_i32_e32 v81, 31, v80
	v_lshlrev_b64 v[80:81], 13, v[80:81]
	v_lshl_add_u64 v[80:81], s[44:45], 0, v[80:81]
	v_or_b32_e32 v68, 48, v68
	v_lshl_add_u64 v[80:81], v[80:81], 0, s[0:1]
	v_ashrrev_i32_e32 v69, 31, v68
	v_pk_mul_f32 v[84:85], v[110:111], v[162:163]
	v_lshl_add_u64 v[80:81], v[80:81], 0, v[144:145]
	v_lshlrev_b64 v[68:69], 13, v[68:69]
	v_cvt_pk_bf16_f32 v100, v92, v93
	v_cvt_pk_bf16_f32 v101, v84, v85
	v_lshl_add_u64 v[80:81], v[80:81], 0, v[160:161]
	v_pk_mul_f32 v[84:85], v[106:107], v[164:165]
	v_lshl_add_u64 v[68:69], s[44:45], 0, v[68:69]
	global_store_dwordx2 v[80:81], v[100:101], off
	v_cvt_pk_bf16_f32 v100, v88, v89
	v_cvt_pk_bf16_f32 v101, v84, v85
	v_pk_mul_f32 v[84:85], v[78:79], v[136:137]
	v_lshl_add_u64 v[68:69], v[68:69], 0, s[0:1]
	global_store_dwordx2 v[80:81], v[100:101], off offset:16
	v_cvt_pk_bf16_f32 v100, v112, v113
	v_cvt_pk_bf16_f32 v101, v84, v85
	v_pk_mul_f32 v[84:85], v[74:75], v[128:129]
	v_lshl_add_u64 v[68:69], v[68:69], 0, v[144:145]
	global_store_dwordx2 v[80:81], v[100:101], off offset:256
	v_cvt_pk_bf16_f32 v100, v108, v109
	v_cvt_pk_bf16_f32 v101, v84, v85
	global_store_dwordx2 v[80:81], v[100:101], off offset:272
	v_cvt_pk_bf16_f32 v84, v76, v77
	v_lshl_add_u64 v[68:69], v[68:69], 0, v[160:161]
	v_pk_mul_f32 v[80:81], v[102:103], v[162:163]
	s_mov_b64 s[0:1], 0x100000
	v_cvt_pk_bf16_f32 v85, v80, v81
	global_store_dwordx2 v[68:69], v[84:85], off
	v_cvt_pk_bf16_f32 v84, v72, v73
	v_pk_mul_f32 v[80:81], v[98:99], v[164:165]
	s_nop 0
	v_cvt_pk_bf16_f32 v85, v80, v81
	global_store_dwordx2 v[68:69], v[84:85], off offset:16
	v_cvt_pk_bf16_f32 v84, v104, v105
	v_pk_mul_f32 v[80:81], v[70:71], v[136:137]
	s_nop 0
	v_cvt_pk_bf16_f32 v85, v80, v81
	global_store_dwordx2 v[68:69], v[84:85], off offset:256
	v_cvt_pk_bf16_f32 v84, v96, v97
	v_pk_mul_f32 v[80:81], v[66:67], v[128:129]
	s_nop 0
	v_cvt_pk_bf16_f32 v85, v80, v81
	global_store_dwordx2 v[68:69], v[84:85], off offset:272
	v_add_co_u32_e32 v84, vcc, s29, v64
	v_pk_mul_f32 v[68:69], v[62:63], v[162:163]
	s_nop 0
	v_addc_co_u32_e32 v85, vcc, 0, v65, vcc
	v_cvt_pk_bf16_f32 v80, v60, v61
	v_cvt_pk_bf16_f32 v81, v68, v69
	v_lshl_add_u64 v[68:69], v[64:65], 0, s[0:1]
	global_store_dwordx2 v[84:85], v[80:81], off
	v_cvt_pk_bf16_f32 v84, v56, v57
	v_pk_mul_f32 v[80:81], v[58:59], v[164:165]
	s_mov_b64 s[0:1], 0x120000
	v_cvt_pk_bf16_f32 v85, v80, v81
	global_store_dwordx2 v[68:69], v[84:85], off offset:16
	v_cvt_pk_bf16_f32 v84, v28, v29
	v_pk_mul_f32 v[80:81], v[30:31], v[136:137]
	s_nop 0
	v_cvt_pk_bf16_f32 v85, v80, v81
	global_store_dwordx2 v[68:69], v[84:85], off offset:256
	v_cvt_pk_bf16_f32 v84, v24, v25
	v_pk_mul_f32 v[80:81], v[26:27], v[128:129]
	s_nop 0
	v_cvt_pk_bf16_f32 v85, v80, v81
	global_store_dwordx2 v[68:69], v[84:85], off offset:272
	v_add_co_u32_e32 v84, vcc, s49, v64
	v_pk_mul_f32 v[68:69], v[54:55], v[162:163]
	v_cvt_pk_bf16_f32 v80, v52, v53
	s_nop 0
	v_addc_co_u32_e32 v85, vcc, 0, v65, vcc
	v_cvt_pk_bf16_f32 v81, v68, v69
	v_lshl_add_u64 v[68:69], v[64:65], 0, s[0:1]
	global_store_dwordx2 v[84:85], v[80:81], off
	v_pk_mul_f32 v[80:81], v[50:51], v[164:165]
	v_cvt_pk_bf16_f32 v84, v48, v49
	s_mov_b64 s[0:1], 0x140000
	v_cvt_pk_bf16_f32 v85, v80, v81
	global_store_dwordx2 v[68:69], v[84:85], off offset:16
	v_pk_mul_f32 v[80:81], v[22:23], v[136:137]
	v_cvt_pk_bf16_f32 v84, v20, v21
	s_nop 0
	v_cvt_pk_bf16_f32 v85, v80, v81
	global_store_dwordx2 v[68:69], v[84:85], off offset:256
	v_pk_mul_f32 v[80:81], v[18:19], v[128:129]
	v_cvt_pk_bf16_f32 v84, v16, v17
	s_nop 0
	v_cvt_pk_bf16_f32 v85, v80, v81
	global_store_dwordx2 v[68:69], v[84:85], off offset:272
	v_pk_mul_f32 v[68:69], v[46:47], v[162:163]
	v_cvt_pk_bf16_f32 v80, v44, v45
	s_nop 0
	v_cvt_pk_bf16_f32 v81, v68, v69
	v_lshl_add_u64 v[68:69], v[64:65], 0, s[0:1]
	s_mov_b32 s0, 0x140000
	v_add_co_u32_e32 v84, vcc, s0, v64
	s_mov_b64 s[0:1], 0x160000
	s_nop 0
	v_addc_co_u32_e32 v85, vcc, 0, v65, vcc
	global_store_dwordx2 v[84:85], v[80:81], off
	v_pk_mul_f32 v[80:81], v[42:43], v[164:165]
	v_cvt_pk_bf16_f32 v84, v40, v41
	s_nop 0
	v_cvt_pk_bf16_f32 v85, v80, v81
	global_store_dwordx2 v[68:69], v[84:85], off offset:16
	v_pk_mul_f32 v[80:81], v[14:15], v[136:137]
	v_cvt_pk_bf16_f32 v84, v12, v13
	s_nop 0
	v_cvt_pk_bf16_f32 v85, v80, v81
	global_store_dwordx2 v[68:69], v[84:85], off offset:256
	v_pk_mul_f32 v[80:81], v[10:11], v[128:129]
	v_cvt_pk_bf16_f32 v84, v8, v9
	s_nop 0
	v_cvt_pk_bf16_f32 v85, v80, v81
	global_store_dwordx2 v[68:69], v[84:85], off offset:272
	v_pk_mul_f32 v[68:69], v[38:39], v[162:163]
	v_cvt_pk_bf16_f32 v80, v36, v37
	s_nop 0
	v_cvt_pk_bf16_f32 v81, v68, v69
	v_lshl_add_u64 v[68:69], v[64:65], 0, s[0:1]
	s_mov_b32 s0, 0x160000
	v_add_co_u32_e32 v64, vcc, s0, v64
	s_mov_b64 s[0:1], 0
	s_nop 0
	v_addc_co_u32_e32 v65, vcc, 0, v65, vcc
	global_store_dwordx2 v[64:65], v[80:81], off
	v_pk_mul_f32 v[64:65], v[34:35], v[164:165]
	v_cvt_pk_bf16_f32 v80, v32, v33
	s_nop 0
	v_cvt_pk_bf16_f32 v81, v64, v65
	global_store_dwordx2 v[68:69], v[80:81], off offset:16
	v_pk_mul_f32 v[64:65], v[6:7], v[136:137]
	v_cvt_pk_bf16_f32 v80, v4, v5
	s_nop 0
	v_cvt_pk_bf16_f32 v81, v64, v65
	global_store_dwordx2 v[68:69], v[80:81], off offset:256
	v_pk_mul_f32 v[64:65], v[2:3], v[128:129]
	v_cvt_pk_bf16_f32 v80, v0, v1
	s_nop 0
	v_cvt_pk_bf16_f32 v81, v64, v65
	s_nop 1
	global_store_dwordx2 v[68:69], v[80:81], off offset:272
